# first K-iteration peeled with C=0 (no per-unit accumulator zeroing); hand-written G1 scale and G3 SwiGLU epilogues: rstd cached per pm in LDS, packed f32 math
# speedup vs baseline: 1.0314x; 1.0207x over previous
; #define PG8_STAGE(bufoff, gbase, voff) do { _Pragma("unroll") for (int _i = 0; _i < 2; ++_i) \
;         __builtin_amdgcn_global_load_lds((const unsigned*)((const char*)(gbase) + (voff)[_i]), (PG8_LAS unsigned*)(lds + (bufoff) + ldsw + _i * 8192), 16, 0, 0); } while (0)
; #define PG8_WAIT_V(n) asm volatile("s_waitcnt vmcnt(" #n ")" ::: "memory")
; #define PG8_BAR __builtin_amdgcn_s_barrier()
; template <class Epi, class Sched, bool ALIGN_EPI = false, bool SP2 = false>
; __device__ __forceinline__ void gemm_phase(PG8_LAS unsigned char* lds, const Gemm g, const Sched& S, const Epi& E, int tid_in) {
;     ...
;     const int tid = tid_, wid = __builtin_amdgcn_readfirstlane(tid >> 6), lane = tid & 63, wr = wid >> 2, wc = wid & 3, fr = lane & 15, fq = lane >> 4;
;     int K_ = g.K; asm volatile("" : "+s"(K_));
;     const int K = K_, nt = K / BK;
;     unsigned voffA[2], voffB[2];
; #pragma unroll
;     for (int i = 0; i < 2; ++i) { int R, C; stage_rc(tid * 16 + i * 8192, R, C); const int Rb = Epi::PERM ? ((R & ~31) + perm32(R & 31)) : R;
;         voffA[i] = (unsigned)(R * K + C) * 2u; voffB[i] = (unsigned)(Rb * K + C) * 2u; }
;     const size_t kstep = (size_t)(BK * 2);
;     const size_t hstep = (size_t)HALF * K * 2;
;     const size_t tstep = 2 * hstep;
;     const unsigned ldsw = (unsigned)wid * 1024u;
;     const int aoff = lds_byte(wr * 64 + fr, fq * 8), boff = lds_byte(wc * 32 + fr, fq * 8);
;     ...
;         PG8_STAGE(PG8_SB(1, 0), cB + kstep, voffB); PG8_STAGE(PG8_SA(1, 0), cA + kstep, voffA); PG8_STAGE(PG8_SB(1, 1), cB + hstep + kstep, voffB);
;         PG8_WAIT_V(6); PG8_BAR;
.LBB0_140:
	s_add_u32 s14, s2, 0x14000000
	s_addc_u32 s15, s3, 0
	s_add_i32 m0, s43, 0x18000
	v_lshl_add_u64 v[8:9], v[8:9], 0, s[64:65]
	s_waitcnt vmcnt(2)
	s_mov_b32 s100, -1
	s_barrier
	global_load_lds_dwordx4 v[8:9], off
	v_lshl_add_u64 v[4:5], v[4:5], 0, s[64:65]
	s_add_i32 m0, s43, 0x1a000
	s_add_i32 s34, s43, 0x8000
	global_load_lds_dwordx4 v[4:5], off
	v_lshl_add_u64 v[4:5], v[6:7], 0, s[64:65]
	s_mov_b32 m0, s34
	s_add_i32 s35, s43, 0xa000
	global_load_lds_dwordx4 v[4:5], off
	v_lshl_add_u64 v[4:5], v[10:11], 0, s[64:65]
	s_mov_b32 m0, s35
	v_lshl_add_u64 v[2:3], v[2:3], 0, s[64:65]
	global_load_lds_dwordx4 v[4:5], off
	s_add_i32 m0, s43, 0x1c000
	v_lshl_add_u64 v[0:1], v[0:1], 0, s[64:65]
	global_load_lds_dwordx4 v[2:3], off
	s_add_i32 m0, s43, 0x1e000
	v_and_b32_e32 v147, 15, v12
	global_load_lds_dwordx4 v[0:1], off
	v_bfe_u32 v2, v12, 4, 2
	s_lshr_b32 s5, s5, 26
	s_add_i32 s5, s4, s5
	v_lshlrev_b32_e32 v0, 4, v2
	v_lshlrev_b32_e32 v149, 2, v147
	s_ashr_i32 s55, s5, 6
	v_lshl_or_b32 v0, v147, 6, v0
	s_lshl_b32 s5, s17, 13
	v_and_b32_e32 v1, 32, v149
	v_bitop3_b32 v3, v0, s5, v1 bitop3:0xde
	s_lshl_b32 s5, s16, 5
	s_and_b32 s5, s5, 0x60
	s_lshl_b32 s16, s5, 7
	v_bitop3_b32 v151, v0, s16, v1 bitop3:0xde
	v_and_b32_e32 v0, 63, v12
	v_lshlrev_b32_e32 v0, 2, v0
	v_mov_b32_e32 v1, v157
	v_lshl_add_u64 v[0:1], s[2:3], 0, v[0:1]
	s_mov_b64 s[2:3], 0x30000000
	s_waitcnt lgkmcnt(0)
	s_ashr_i32 s54, s53, 31
	s_lshl_b32 s56, s17, 6
	v_lshl_add_u64 v[134:135], v[0:1], 0, s[2:3]
	v_add_u32_e32 v0, v18, v16
	s_cmp_gt_i32 s4, 63
	v_add_lshl_u32 v0, v0, v17, 1
	v_mov_b32_e32 v1, v157
	s_waitcnt vmcnt(6)
	s_cselect_b64 s[16:17], -1, 0
	s_add_i32 s57, s55, -2
	v_lshl_add_u64 v[136:137], s[8:9], 0, v[0:1]
	v_add_u32_e32 v0, v15, v13
	s_cmpk_lt_u32 s24, 0x100
	v_add_lshl_u32 v0, v0, v14, 1
	s_cselect_b64 s[24:25], -1, 0
	v_or_b32_e32 v152, 64, v149
	v_or_b32_e32 v153, 0x80, v149
	v_or_b32_e32 v154, 0xc0, v149
	v_lshl_or_b32 v155, v2, 3, s5
	v_lshl_add_u64 v[138:139], s[8:9], 0, v[0:1]
	s_mov_b32 s60, 0
	v_add_u32_e32 v161, 0, v3
	v_readlane_b32 s66, v254, 29
	v_readlane_b32 s67, v254, 30
	s_barrier
	s_branch .LBB0_143

; #define PG8_STAGE(bufoff, gbase, voff) do { _Pragma("unroll") for (int _i = 0; _i < 2; ++_i) \
;         __builtin_amdgcn_global_load_lds((const unsigned*)((const char*)(gbase) + (voff)[_i]), (PG8_LAS unsigned*)(lds + (bufoff) + ldsw + _i * 8192), 16, 0, 0); } while (0)
; #define PG8_LDA(dst, b, h) do { _Pragma("unroll") for (int m = 0; m < 4; ++m) _Pragma("unroll") for (int k = 0; k < 2; ++k) dst[m][k] = *(const PG8_LAS bf16x8*)(lds + PG8_SA(b, h) + aoff + m * 2048 + k * 1024); } while (0)
; #define PG8_LDB(dst, b, h) do { _Pragma("unroll") for (int n = 0; n < 2; ++n) _Pragma("unroll") for (int k = 0; k < 2; ++k) dst[n][k] = *(const PG8_LAS bf16x8*)(lds + PG8_SB(b, h) + boff + n * 2048 + k * 1024); } while (0)
; #define PG8_MMA(ai, bj, At, Bt) do { __builtin_amdgcn_s_setprio(1); _Pragma("unroll") for (int m = 0; m < 4; ++m) _Pragma("unroll") for (int n = 0; n < 2; ++n) _Pragma("unroll") for (int k = 0; k < 2; ++k) \
;         acc[ai][bj][m][n] = __builtin_amdgcn_mfma_f32_16x16x32_bf16(Bt[n][k], At[m][k], acc[ai][bj][m][n], 0, 0, 0); __builtin_amdgcn_s_setprio(0); } while (0)
; #define PG8_WAIT_V(n) asm volatile("s_waitcnt vmcnt(" #n ")" ::: "memory")
; #define PG8_WAIT_L(n) asm volatile("s_waitcnt lgkmcnt(" #n ")" ::: "memory")
; template <class Epi, class Sched, bool ALIGN_EPI = false, bool SP2 = false>
; __device__ __forceinline__ void gemm_phase(PG8_LAS unsigned char* lds, const Gemm g, const Sched& S, const Epi& E, int tid_in) {
;     ...
;             const bool last = (t == nt - 2);
;             const char* a1 = cA + (size_t)(t + 1) * kstep;
;             const char* a2 = last ? nA : cA + (size_t)(t + 2) * kstep; const char* b2 = last ? nB : cB + (size_t)(t + 2) * kstep;
;             const char* a3 = a2 + kstep; const char* b3 = b2 + kstep;
;             if (last && has_next) S.a_ready(nxt);
;             if constexpr (SP2) {
;             PG8_LDB(B0, 0, 0); PG8_LDB(B1, 0, 1); PG8_SCHED; PG8_LDA(At, 0, 0); PG8_STAGE(PG8_SA(1, 1), a1 + hstep, voffA);
;             PG8_WAIT_V(8); PG8_WAIT_L(0); PG8_BAR; PG8_MMA(0, 0, At, B0); PG8_MMA(0, 1, At, B1); PG8_BAR; PG8_SCHED;
;     ...
;         for (int a = 0; a < 2; ++a)
; #pragma unroll
;             for (int b = 0; b < 2; ++b)
; #pragma unroll
;                 for (int m = 0; m < 4; ++m)
; #pragma unroll
;                     for (int n = 0; n < 2; ++n) acc[a][b][m][n] = (f32x4){0.f, 0.f, 0.f, 0.f};
.LBB0_149:
	s_andn2_b64 vcc, exec, s[16:17]
	s_cbranch_vccz .Lpeel_enter_g1
	v_mov_b32_e32 v127, 0
	v_mov_b32_e32 v126, v127
	v_mov_b32_e32 v125, v127
	v_mov_b32_e32 v124, v127
	v_mov_b32_e32 v123, v127
	v_mov_b32_e32 v122, v127
	v_mov_b32_e32 v121, v127
	v_mov_b32_e32 v120, v127
	v_mov_b32_e32 v111, v127
	v_mov_b32_e32 v110, v127
	v_mov_b32_e32 v109, v127
	v_mov_b32_e32 v108, v127
	v_mov_b32_e32 v107, v127
	v_mov_b32_e32 v106, v127
	v_mov_b32_e32 v105, v127
	v_mov_b32_e32 v104, v127
	v_mov_b32_e32 v95, v127
	v_mov_b32_e32 v94, v127
	v_mov_b32_e32 v93, v127
	v_mov_b32_e32 v92, v127
	v_mov_b32_e32 v91, v127
	v_mov_b32_e32 v90, v127
	v_mov_b32_e32 v89, v127
	v_mov_b32_e32 v88, v127
	v_mov_b32_e32 v79, v127
	v_mov_b32_e32 v78, v127
	v_mov_b32_e32 v77, v127
	v_mov_b32_e32 v76, v127
	v_mov_b32_e32 v75, v127
	v_mov_b32_e32 v74, v127
	v_mov_b32_e32 v73, v127
	v_mov_b32_e32 v72, v127
	v_mov_b32_e32 v119, v127
	v_mov_b32_e32 v118, v127
	v_mov_b32_e32 v117, v127
	v_mov_b32_e32 v116, v127
	v_mov_b32_e32 v115, v127
	v_mov_b32_e32 v114, v127
	v_mov_b32_e32 v113, v127
	v_mov_b32_e32 v112, v127
	v_mov_b32_e32 v103, v127
	v_mov_b32_e32 v102, v127
	v_mov_b32_e32 v101, v127
	v_mov_b32_e32 v100, v127
	v_mov_b32_e32 v99, v127
	v_mov_b32_e32 v98, v127
	v_mov_b32_e32 v97, v127
	v_mov_b32_e32 v96, v127
	v_mov_b32_e32 v87, v127
	v_mov_b32_e32 v86, v127
	v_mov_b32_e32 v85, v127
	v_mov_b32_e32 v84, v127
	v_mov_b32_e32 v83, v127
	v_mov_b32_e32 v82, v127
	v_mov_b32_e32 v81, v127
	v_mov_b32_e32 v80, v127
	v_mov_b32_e32 v71, v127
	v_mov_b32_e32 v70, v127
	v_mov_b32_e32 v69, v127
	v_mov_b32_e32 v68, v127
	v_mov_b32_e32 v67, v127
	v_mov_b32_e32 v66, v127
	v_mov_b32_e32 v65, v127
	v_mov_b32_e32 v64, v127
	v_mov_b32_e32 v63, v127
	v_mov_b32_e32 v62, v127
	v_mov_b32_e32 v61, v127
	v_mov_b32_e32 v60, v127
	v_mov_b32_e32 v59, v127
	v_mov_b32_e32 v58, v127
	v_mov_b32_e32 v57, v127
	v_mov_b32_e32 v56, v127
	v_mov_b32_e32 v47, v127
	v_mov_b32_e32 v46, v127
	v_mov_b32_e32 v45, v127
	v_mov_b32_e32 v44, v127
	v_mov_b32_e32 v43, v127
	v_mov_b32_e32 v42, v127
	v_mov_b32_e32 v41, v127
	v_mov_b32_e32 v40, v127
	v_mov_b32_e32 v31, v127
	v_mov_b32_e32 v30, v127
	v_mov_b32_e32 v29, v127
	v_mov_b32_e32 v28, v127
	v_mov_b32_e32 v27, v127
	v_mov_b32_e32 v26, v127
	v_mov_b32_e32 v25, v127
	v_mov_b32_e32 v24, v127
	v_mov_b32_e32 v15, v127
	v_mov_b32_e32 v14, v127
	v_mov_b32_e32 v13, v127
	v_mov_b32_e32 v12, v127
	v_mov_b32_e32 v11, v127
	v_mov_b32_e32 v10, v127
	v_mov_b32_e32 v9, v127
	v_mov_b32_e32 v8, v127
	v_mov_b32_e32 v55, v127
	v_mov_b32_e32 v54, v127
	v_mov_b32_e32 v53, v127
	v_mov_b32_e32 v52, v127
	v_mov_b32_e32 v51, v127
	v_mov_b32_e32 v50, v127
	v_mov_b32_e32 v49, v127
	v_mov_b32_e32 v48, v127
	v_mov_b32_e32 v39, v127
	v_mov_b32_e32 v38, v127
	v_mov_b32_e32 v37, v127
	v_mov_b32_e32 v36, v127
	v_mov_b32_e32 v35, v127
	v_mov_b32_e32 v34, v127
	v_mov_b32_e32 v33, v127
	v_mov_b32_e32 v32, v127
	v_mov_b32_e32 v23, v127
	v_mov_b32_e32 v22, v127
	v_mov_b32_e32 v21, v127
	v_mov_b32_e32 v20, v127
	v_mov_b32_e32 v19, v127
	v_mov_b32_e32 v18, v127
	v_mov_b32_e32 v17, v127
	v_mov_b32_e32 v16, v127
	v_mov_b32_e32 v7, v127
	v_mov_b32_e32 v6, v127
	v_mov_b32_e32 v5, v127
	v_mov_b32_e32 v4, v127
	v_mov_b32_e32 v3, v127
	v_mov_b32_e32 v2, v127
	v_mov_b32_e32 v1, v127
	v_mov_b32_e32 v0, v127
	s_branch .LBB0_153
.Lpeel_enter_g1:
	s_add_u32 s0, s0, 0x80
	s_addc_u32 s1, s1, 0
	s_add_u32 s22, s22, 0x100
	s_addc_u32 s23, s23, 0
	s_mov_b32 s4, 0
	s_add_i32 s36, s4, 2
	s_add_u32 s37, s0, 0x80
	s_addc_u32 s5, s1, 0
	s_add_i32 s90, 0, 0x10000
	s_cmp_eq_u32 s57, s4
	s_cselect_b32 s5, s39, s5
	s_cselect_b32 s4, s38, s37
	v_add_u32_e32 v144, s90, v151
	s_cselect_b32 s89, s45, s23
	s_cselect_b32 s88, s44, s22
	s_add_i32 s37, 0, 0x14000
	ds_read_b128 v[140:143], v144
	ds_read_b128 v[166:169], v144 offset:1024
	ds_read_b128 v[170:173], v144 offset:2048
	ds_read_b128 v[174:177], v144 offset:3072
	v_add_u32_e32 v144, s37, v151
	ds_read_b128 v[178:181], v144
	ds_read_b128 v[182:185], v144 offset:1024
	ds_read_b128 v[186:189], v144 offset:2048
	ds_read_b128 v[190:193], v144 offset:3072
	v_lshl_add_u64 v[144:145], s[0:1], 0, v[136:137]
	s_add_i32 m0, s43, 0xc000
	ds_read_b128 v[194:197], v161
	ds_read_b128 v[198:201], v161 offset:1024
	ds_read_b128 v[202:205], v161 offset:2048
	ds_read_b128 v[206:209], v161 offset:3072
	ds_read_b128 v[210:213], v161 offset:4096
	ds_read_b128 v[214:217], v161 offset:5120
	ds_read_b128 v[218:221], v161 offset:6144
	ds_read_b128 v[222:225], v161 offset:7168
	global_load_lds_dwordx4 v[144:145], off
	v_lshl_add_u64 v[144:145], s[0:1], 0, v[138:139]
	s_add_i32 m0, s43, 0xe000
	s_nop 0
	global_load_lds_dwordx4 v[144:145], off
	s_waitcnt vmcnt(8)
	s_waitcnt lgkmcnt(0)
	s_barrier
; #define PG8_STAGE(bufoff, gbase, voff) do { _Pragma("unroll") for (int _i = 0; _i < 2; ++_i) \
;         __builtin_amdgcn_global_load_lds((const unsigned*)((const char*)(gbase) + (voff)[_i]), (PG8_LAS unsigned*)(lds + (bufoff) + ldsw + _i * 8192), 16, 0, 0); } while (0)
; #define PG8_LDA(dst, b, h) do { _Pragma("unroll") for (int m = 0; m < 4; ++m) _Pragma("unroll") for (int k = 0; k < 2; ++k) dst[m][k] = *(const PG8_LAS bf16x8*)(lds + PG8_SA(b, h) + aoff + m * 2048 + k * 1024); } while (0)
; #define PG8_MMA(ai, bj, At, Bt) do { __builtin_amdgcn_s_setprio(1); _Pragma("unroll") for (int m = 0; m < 4; ++m) _Pragma("unroll") for (int n = 0; n < 2; ++n) _Pragma("unroll") for (int k = 0; k < 2; ++k) \
;         acc[ai][bj][m][n] = __builtin_amdgcn_mfma_f32_16x16x32_bf16(Bt[n][k], At[m][k], acc[ai][bj][m][n], 0, 0, 0); __builtin_amdgcn_s_setprio(0); } while (0)
; #define PG8_WAIT_V(n) asm volatile("s_waitcnt vmcnt(" #n ")" ::: "memory")
; #define PG8_WAIT_L(n) asm volatile("s_waitcnt lgkmcnt(" #n ")" ::: "memory")
; #define PG8_BAR __builtin_amdgcn_s_barrier()
; #define PG8_SCHED __builtin_amdgcn_sched_barrier(0)
; template <class Epi, class Sched, bool ALIGN_EPI = false, bool SP2 = false>
; __device__ __forceinline__ void gemm_phase(PG8_LAS unsigned char* lds, const Gemm g, const Sched& S, const Epi& E, int tid_in) {
;     ...
;             PG8_WAIT_V(8); PG8_WAIT_L(0); PG8_BAR; PG8_MMA(0, 0, At, B0); PG8_MMA(0, 1, At, B1); PG8_BAR; PG8_SCHED;
;             PG8_LDA(At, 0, 1); PG8_STAGE(PG8_SB(0, 0), b2, voffB); PG8_STAGE(PG8_SB(0, 1), b2 + hstep, voffB); PG8_STAGE(PG8_SA(0, 0), a2, voffA);
;             PG8_WAIT_V(8); PG8_WAIT_L(0); PG8_BAR; PG8_MMA(1, 0, At, B0); PG8_MMA(1, 1, At, B1); PG8_BAR; PG8_SCHED;
	s_waitcnt lgkmcnt(0)
	v_mfma_f32_16x16x32_bf16 v[124:127], v[140:143], v[194:197], 0
	v_mfma_f32_16x16x32_bf16 v[120:123], v[170:173], v[194:197], 0
	v_mfma_f32_16x16x32_bf16 v[108:111], v[140:143], v[202:205], 0
	v_mfma_f32_16x16x32_bf16 v[104:107], v[170:173], v[202:205], 0
	v_mfma_f32_16x16x32_bf16 v[92:95], v[140:143], v[210:213], 0
	v_mfma_f32_16x16x32_bf16 v[88:91], v[170:173], v[210:213], 0
	v_mfma_f32_16x16x32_bf16 v[76:79], v[140:143], v[218:221], 0
	v_mfma_f32_16x16x32_bf16 v[72:75], v[170:173], v[218:221], 0
	v_mfma_f32_16x16x32_bf16 v[124:127], v[166:169], v[198:201], v[124:127]
	v_mfma_f32_16x16x32_bf16 v[120:123], v[174:177], v[198:201], v[120:123]
	v_mfma_f32_16x16x32_bf16 v[108:111], v[166:169], v[206:209], v[108:111]
	v_mfma_f32_16x16x32_bf16 v[104:107], v[174:177], v[206:209], v[104:107]
	v_mfma_f32_16x16x32_bf16 v[92:95], v[166:169], v[214:217], v[92:95]
	v_mfma_f32_16x16x32_bf16 v[88:91], v[174:177], v[214:217], v[88:91]
	v_mfma_f32_16x16x32_bf16 v[76:79], v[166:169], v[222:225], v[76:79]
	v_mfma_f32_16x16x32_bf16 v[72:75], v[174:177], v[222:225], v[72:75]
	v_mfma_f32_16x16x32_bf16 v[116:119], v[178:181], v[194:197], 0
	v_mfma_f32_16x16x32_bf16 v[112:115], v[186:189], v[194:197], 0
	v_mfma_f32_16x16x32_bf16 v[100:103], v[178:181], v[202:205], 0
	v_mfma_f32_16x16x32_bf16 v[96:99], v[186:189], v[202:205], 0
	v_mfma_f32_16x16x32_bf16 v[84:87], v[178:181], v[210:213], 0
	v_mfma_f32_16x16x32_bf16 v[80:83], v[186:189], v[210:213], 0
	v_mfma_f32_16x16x32_bf16 v[68:71], v[178:181], v[218:221], 0
	v_mfma_f32_16x16x32_bf16 v[64:67], v[186:189], v[218:221], 0
	v_mfma_f32_16x16x32_bf16 v[116:119], v[182:185], v[198:201], v[116:119]
	v_mfma_f32_16x16x32_bf16 v[112:115], v[190:193], v[198:201], v[112:115]
	v_mfma_f32_16x16x32_bf16 v[100:103], v[182:185], v[206:209], v[100:103]
	v_mfma_f32_16x16x32_bf16 v[96:99], v[190:193], v[206:209], v[96:99]
	v_mfma_f32_16x16x32_bf16 v[84:87], v[182:185], v[214:217], v[84:87]
	v_mfma_f32_16x16x32_bf16 v[80:83], v[190:193], v[214:217], v[80:83]
	v_mfma_f32_16x16x32_bf16 v[68:71], v[182:185], v[222:225], v[68:71]
	v_mfma_f32_16x16x32_bf16 v[64:67], v[190:193], v[222:225], v[64:67]
	s_barrier
	s_add_i32 s90, s90, s42
	v_lshl_add_u64 v[144:145], s[88:89], 0, v[156:157]
	s_mov_b32 m0, s90
	ds_read_b128 v[194:197], v161 offset:16384
	ds_read_b128 v[198:201], v161 offset:17408
	ds_read_b128 v[202:205], v161 offset:18432
	ds_read_b128 v[206:209], v161 offset:19456
	ds_read_b128 v[210:213], v161 offset:20480
	ds_read_b128 v[214:217], v161 offset:21504
	ds_read_b128 v[218:221], v161 offset:22528
	ds_read_b128 v[222:225], v161 offset:23552
	global_load_lds_dwordx4 v[144:145], off
	s_add_i32 m0, s90, 0x2000
	v_lshl_add_u64 v[226:227], s[88:89], 0, v[128:129]
	s_add_u32 s88, s88, s8
	s_addc_u32 s89, s89, s9
	s_add_i32 s37, s37, s42
	global_load_lds_dwordx4 v[226:227], off
	v_lshl_add_u64 v[228:229], s[88:89], 0, v[156:157]
	s_mov_b32 m0, s37
	v_lshl_add_u64 v[238:239], s[88:89], 0, v[128:129]
	global_load_lds_dwordx4 v[228:229], off
	s_add_i32 m0, s37, 0x2000
	v_lshl_add_u64 v[240:241], s[4:5], 0, v[132:133]
	global_load_lds_dwordx4 v[238:239], off
	s_mov_b32 m0, s43
	v_lshl_add_u64 v[242:243], s[4:5], 0, v[130:131]
	global_load_lds_dwordx4 v[240:241], off
	s_mov_b32 m0, s46
	s_nop 0
	global_load_lds_dwordx4 v[242:243], off
	s_waitcnt vmcnt(8)
	s_waitcnt lgkmcnt(0)
	s_barrier
	s_waitcnt lgkmcnt(0)
	v_mfma_f32_16x16x32_bf16 v[60:63], v[140:143], v[194:197], 0
	v_mfma_f32_16x16x32_bf16 v[56:59], v[170:173], v[194:197], 0
	v_mfma_f32_16x16x32_bf16 v[44:47], v[140:143], v[202:205], 0
	v_mfma_f32_16x16x32_bf16 v[40:43], v[170:173], v[202:205], 0
	v_mfma_f32_16x16x32_bf16 v[28:31], v[140:143], v[210:213], 0
	v_mfma_f32_16x16x32_bf16 v[24:27], v[170:173], v[210:213], 0
	v_mfma_f32_16x16x32_bf16 v[12:15], v[140:143], v[218:221], 0
	v_mfma_f32_16x16x32_bf16 v[8:11], v[170:173], v[218:221], 0
	v_mfma_f32_16x16x32_bf16 v[60:63], v[166:169], v[198:201], v[60:63]
	v_mfma_f32_16x16x32_bf16 v[56:59], v[174:177], v[198:201], v[56:59]
	v_mfma_f32_16x16x32_bf16 v[44:47], v[166:169], v[206:209], v[44:47]
	v_mfma_f32_16x16x32_bf16 v[40:43], v[174:177], v[206:209], v[40:43]
	v_mfma_f32_16x16x32_bf16 v[28:31], v[166:169], v[214:217], v[28:31]
	v_mfma_f32_16x16x32_bf16 v[24:27], v[174:177], v[214:217], v[24:27]
	v_mfma_f32_16x16x32_bf16 v[12:15], v[166:169], v[222:225], v[12:15]
	v_mfma_f32_16x16x32_bf16 v[8:11], v[174:177], v[222:225], v[8:11]
	v_mfma_f32_16x16x32_bf16 v[52:55], v[178:181], v[194:197], 0
	v_mfma_f32_16x16x32_bf16 v[48:51], v[186:189], v[194:197], 0
	v_mfma_f32_16x16x32_bf16 v[36:39], v[178:181], v[202:205], 0
	v_mfma_f32_16x16x32_bf16 v[32:35], v[186:189], v[202:205], 0
	v_mfma_f32_16x16x32_bf16 v[20:23], v[178:181], v[210:213], 0
	v_mfma_f32_16x16x32_bf16 v[16:19], v[186:189], v[210:213], 0
	v_mfma_f32_16x16x32_bf16 v[4:7], v[178:181], v[218:221], 0
	v_mfma_f32_16x16x32_bf16 v[0:3], v[186:189], v[218:221], 0
	v_mfma_f32_16x16x32_bf16 v[52:55], v[182:185], v[198:201], v[52:55]
	v_mfma_f32_16x16x32_bf16 v[48:51], v[190:193], v[198:201], v[48:51]
	v_mfma_f32_16x16x32_bf16 v[36:39], v[182:185], v[206:209], v[36:39]
	v_mfma_f32_16x16x32_bf16 v[32:35], v[190:193], v[206:209], v[32:35]
	v_mfma_f32_16x16x32_bf16 v[20:23], v[182:185], v[214:217], v[20:23]
	v_mfma_f32_16x16x32_bf16 v[16:19], v[190:193], v[214:217], v[16:19]
	v_mfma_f32_16x16x32_bf16 v[4:7], v[182:185], v[222:225], v[4:7]
	v_mfma_f32_16x16x32_bf16 v[0:3], v[190:193], v[222:225], v[0:3]
	s_barrier
; #define PG8_STAGE(bufoff, gbase, voff) do { _Pragma("unroll") for (int _i = 0; _i < 2; ++_i) \
;         __builtin_amdgcn_global_load_lds((const unsigned*)((const char*)(gbase) + (voff)[_i]), (PG8_LAS unsigned*)(lds + (bufoff) + ldsw + _i * 8192), 16, 0, 0); } while (0)
; #define PG8_LDA(dst, b, h) do { _Pragma("unroll") for (int m = 0; m < 4; ++m) _Pragma("unroll") for (int k = 0; k < 2; ++k) dst[m][k] = *(const PG8_LAS bf16x8*)(lds + PG8_SA(b, h) + aoff + m * 2048 + k * 1024); } while (0)
; #define PG8_LDB(dst, b, h) do { _Pragma("unroll") for (int n = 0; n < 2; ++n) _Pragma("unroll") for (int k = 0; k < 2; ++k) dst[n][k] = *(const PG8_LAS bf16x8*)(lds + PG8_SB(b, h) + boff + n * 2048 + k * 1024); } while (0)
; #define PG8_MMA(ai, bj, At, Bt) do { __builtin_amdgcn_s_setprio(1); _Pragma("unroll") for (int m = 0; m < 4; ++m) _Pragma("unroll") for (int n = 0; n < 2; ++n) _Pragma("unroll") for (int k = 0; k < 2; ++k) \
;         acc[ai][bj][m][n] = __builtin_amdgcn_mfma_f32_16x16x32_bf16(Bt[n][k], At[m][k], acc[ai][bj][m][n], 0, 0, 0); __builtin_amdgcn_s_setprio(0); } while (0)
; #define PG8_WAIT_V(n) asm volatile("s_waitcnt vmcnt(" #n ")" ::: "memory")
; #define PG8_WAIT_L(n) asm volatile("s_waitcnt lgkmcnt(" #n ")" ::: "memory")
; #define PG8_BAR __builtin_amdgcn_s_barrier()
; #define PG8_SCHED __builtin_amdgcn_sched_barrier(0)
; template <class Epi, class Sched, bool ALIGN_EPI = false, bool SP2 = false>
; __device__ __forceinline__ void gemm_phase(PG8_LAS unsigned char* lds, const Gemm g, const Sched& S, const Epi& E, int tid_in) {
;     ...
;             PG8_LDB(B0, 1, 0); PG8_LDB(B1, 1, 1); PG8_SCHED; PG8_LDA(At, 1, 0); PG8_STAGE(PG8_SA(0, 1), a2 + hstep, voffA);
;             PG8_WAIT_V(8); PG8_WAIT_L(0); PG8_BAR; PG8_MMA(0, 0, At, B0); PG8_MMA(0, 1, At, B1); PG8_BAR; PG8_SCHED;
;             PG8_LDA(At, 1, 1); PG8_STAGE(PG8_SB(1, 0), b3, voffB); PG8_STAGE(PG8_SB(1, 1), b3 + hstep, voffB); PG8_STAGE(PG8_SA(1, 0), a3, voffA);
;             PG8_WAIT_V(8); PG8_WAIT_L(0); PG8_BAR; PG8_MMA(1, 0, At, B0); PG8_MMA(1, 1, At, B1); PG8_BAR; PG8_SCHED;
	s_add_i32 s37, 0, 0x18000
	v_add_u32_e32 v146, s37, v151
	s_add_i32 s88, 0, 0x1c000
	ds_read_b128 v[140:143], v146
	ds_read_b128 v[166:169], v146 offset:1024
	ds_read_b128 v[170:173], v146 offset:2048
	ds_read_b128 v[174:177], v146 offset:3072
	v_add_u32_e32 v146, s88, v151
	ds_read_b128 v[178:181], v146
	ds_read_b128 v[182:185], v146 offset:1024
	ds_read_b128 v[186:189], v146 offset:2048
	ds_read_b128 v[190:193], v146 offset:3072
	s_add_u32 s4, s4, s8
	s_addc_u32 s5, s5, s9
	s_mov_b32 m0, s47
	v_lshl_add_u64 v[244:245], s[4:5], 0, v[132:133]
	ds_read_b128 v[194:197], v161 offset:32768
	ds_read_b128 v[198:201], v161 offset:33792
	ds_read_b128 v[202:205], v161 offset:34816
	ds_read_b128 v[206:209], v161 offset:35840
	ds_read_b128 v[210:213], v161 offset:36864
	ds_read_b128 v[214:217], v161 offset:37888
	ds_read_b128 v[218:221], v161 offset:38912
	ds_read_b128 v[222:225], v161 offset:39936
	global_load_lds_dwordx4 v[244:245], off
	v_lshl_add_u64 v[244:245], s[4:5], 0, v[130:131]
	s_mov_b32 m0, s52
	s_nop 0
	global_load_lds_dwordx4 v[244:245], off
	s_waitcnt vmcnt(8)
	s_waitcnt lgkmcnt(0)
	s_barrier
	s_waitcnt lgkmcnt(0)
	v_mfma_f32_16x16x32_bf16 v[124:127], v[140:143], v[194:197], v[124:127]
	v_mfma_f32_16x16x32_bf16 v[120:123], v[170:173], v[194:197], v[120:123]
	v_mfma_f32_16x16x32_bf16 v[108:111], v[140:143], v[202:205], v[108:111]
	v_mfma_f32_16x16x32_bf16 v[104:107], v[170:173], v[202:205], v[104:107]
	v_mfma_f32_16x16x32_bf16 v[92:95], v[140:143], v[210:213], v[92:95]
	v_mfma_f32_16x16x32_bf16 v[88:91], v[170:173], v[210:213], v[88:91]
	v_mfma_f32_16x16x32_bf16 v[76:79], v[140:143], v[218:221], v[76:79]
	v_mfma_f32_16x16x32_bf16 v[72:75], v[170:173], v[218:221], v[72:75]
	v_mfma_f32_16x16x32_bf16 v[124:127], v[166:169], v[198:201], v[124:127]
	v_mfma_f32_16x16x32_bf16 v[120:123], v[174:177], v[198:201], v[120:123]
	v_mfma_f32_16x16x32_bf16 v[108:111], v[166:169], v[206:209], v[108:111]
	v_mfma_f32_16x16x32_bf16 v[104:107], v[174:177], v[206:209], v[104:107]
	v_mfma_f32_16x16x32_bf16 v[92:95], v[166:169], v[214:217], v[92:95]
	v_mfma_f32_16x16x32_bf16 v[88:91], v[174:177], v[214:217], v[88:91]
	v_mfma_f32_16x16x32_bf16 v[76:79], v[166:169], v[222:225], v[76:79]
	v_mfma_f32_16x16x32_bf16 v[72:75], v[174:177], v[222:225], v[72:75]
	v_mfma_f32_16x16x32_bf16 v[116:119], v[178:181], v[194:197], v[116:119]
	v_mfma_f32_16x16x32_bf16 v[112:115], v[186:189], v[194:197], v[112:115]
	v_mfma_f32_16x16x32_bf16 v[100:103], v[178:181], v[202:205], v[100:103]
	v_mfma_f32_16x16x32_bf16 v[96:99], v[186:189], v[202:205], v[96:99]
	v_mfma_f32_16x16x32_bf16 v[84:87], v[178:181], v[210:213], v[84:87]
	v_mfma_f32_16x16x32_bf16 v[80:83], v[186:189], v[210:213], v[80:83]
	v_mfma_f32_16x16x32_bf16 v[68:71], v[178:181], v[218:221], v[68:71]
	v_mfma_f32_16x16x32_bf16 v[64:67], v[186:189], v[218:221], v[64:67]
	v_mfma_f32_16x16x32_bf16 v[116:119], v[182:185], v[198:201], v[116:119]
	v_mfma_f32_16x16x32_bf16 v[112:115], v[190:193], v[198:201], v[112:115]
	v_mfma_f32_16x16x32_bf16 v[100:103], v[182:185], v[206:209], v[100:103]
	v_mfma_f32_16x16x32_bf16 v[96:99], v[190:193], v[206:209], v[96:99]
	v_mfma_f32_16x16x32_bf16 v[84:87], v[182:185], v[214:217], v[84:87]
	v_mfma_f32_16x16x32_bf16 v[80:83], v[190:193], v[214:217], v[80:83]
	v_mfma_f32_16x16x32_bf16 v[68:71], v[182:185], v[222:225], v[68:71]
	v_mfma_f32_16x16x32_bf16 v[64:67], v[190:193], v[222:225], v[64:67]
	s_barrier
	s_add_i32 s4, s37, s42
	v_lshl_add_u64 v[144:145], v[144:145], 0, s[64:65]
	s_mov_b32 m0, s4
	ds_read_b128 v[194:197], v161 offset:49152
	ds_read_b128 v[198:201], v161 offset:50176
	ds_read_b128 v[202:205], v161 offset:51200
	ds_read_b128 v[206:209], v161 offset:52224
	ds_read_b128 v[210:213], v161 offset:53248
	ds_read_b128 v[214:217], v161 offset:54272
	ds_read_b128 v[218:221], v161 offset:55296
	ds_read_b128 v[222:225], v161 offset:56320
	global_load_lds_dwordx4 v[144:145], off
	v_lshl_add_u64 v[144:145], v[226:227], 0, s[64:65]
	s_add_i32 m0, s4, 0x2000
	s_add_i32 s4, s88, s42
	global_load_lds_dwordx4 v[144:145], off
	v_lshl_add_u64 v[144:145], v[228:229], 0, s[64:65]
	s_mov_b32 m0, s4
	s_nop 0
	global_load_lds_dwordx4 v[144:145], off
	v_lshl_add_u64 v[144:145], v[238:239], 0, s[64:65]
	s_add_i32 m0, s4, 0x2000
	s_nop 0
	global_load_lds_dwordx4 v[144:145], off
	v_lshl_add_u64 v[144:145], v[240:241], 0, s[64:65]
	s_mov_b32 m0, s34
	s_nop 0
	global_load_lds_dwordx4 v[144:145], off
	v_lshl_add_u64 v[144:145], v[242:243], 0, s[64:65]
	s_mov_b32 m0, s35
	s_nop 0
	global_load_lds_dwordx4 v[144:145], off
	s_waitcnt vmcnt(8)
	s_waitcnt lgkmcnt(0)
	s_barrier
	s_waitcnt lgkmcnt(0)
	v_mfma_f32_16x16x32_bf16 v[60:63], v[140:143], v[194:197], v[60:63]
	v_mfma_f32_16x16x32_bf16 v[56:59], v[170:173], v[194:197], v[56:59]
	v_mfma_f32_16x16x32_bf16 v[44:47], v[140:143], v[202:205], v[44:47]
	v_mfma_f32_16x16x32_bf16 v[40:43], v[170:173], v[202:205], v[40:43]
	v_mfma_f32_16x16x32_bf16 v[28:31], v[140:143], v[210:213], v[28:31]
	v_mfma_f32_16x16x32_bf16 v[24:27], v[170:173], v[210:213], v[24:27]
	v_mfma_f32_16x16x32_bf16 v[12:15], v[140:143], v[218:221], v[12:15]
	v_mfma_f32_16x16x32_bf16 v[8:11], v[170:173], v[218:221], v[8:11]
	v_mfma_f32_16x16x32_bf16 v[60:63], v[166:169], v[198:201], v[60:63]
	v_mfma_f32_16x16x32_bf16 v[56:59], v[174:177], v[198:201], v[56:59]
	v_mfma_f32_16x16x32_bf16 v[44:47], v[166:169], v[206:209], v[44:47]
	v_mfma_f32_16x16x32_bf16 v[40:43], v[174:177], v[206:209], v[40:43]
	v_mfma_f32_16x16x32_bf16 v[28:31], v[166:169], v[214:217], v[28:31]
	v_mfma_f32_16x16x32_bf16 v[24:27], v[174:177], v[214:217], v[24:27]
	v_mfma_f32_16x16x32_bf16 v[12:15], v[166:169], v[222:225], v[12:15]
	v_mfma_f32_16x16x32_bf16 v[8:11], v[174:177], v[222:225], v[8:11]
	v_mfma_f32_16x16x32_bf16 v[52:55], v[178:181], v[194:197], v[52:55]
	v_mfma_f32_16x16x32_bf16 v[48:51], v[186:189], v[194:197], v[48:51]
	v_mfma_f32_16x16x32_bf16 v[36:39], v[178:181], v[202:205], v[36:39]
	v_mfma_f32_16x16x32_bf16 v[32:35], v[186:189], v[202:205], v[32:35]
	v_mfma_f32_16x16x32_bf16 v[20:23], v[178:181], v[210:213], v[20:23]
	v_mfma_f32_16x16x32_bf16 v[16:19], v[186:189], v[210:213], v[16:19]
	v_mfma_f32_16x16x32_bf16 v[4:7], v[178:181], v[218:221], v[4:7]
	v_mfma_f32_16x16x32_bf16 v[0:3], v[186:189], v[218:221], v[0:3]
	v_mfma_f32_16x16x32_bf16 v[52:55], v[182:185], v[198:201], v[52:55]
	v_mfma_f32_16x16x32_bf16 v[48:51], v[190:193], v[198:201], v[48:51]
	v_mfma_f32_16x16x32_bf16 v[36:39], v[182:185], v[206:209], v[36:39]
	v_mfma_f32_16x16x32_bf16 v[32:35], v[190:193], v[206:209], v[32:35]
	v_mfma_f32_16x16x32_bf16 v[20:23], v[182:185], v[214:217], v[20:23]
	v_mfma_f32_16x16x32_bf16 v[16:19], v[190:193], v[214:217], v[16:19]
	v_mfma_f32_16x16x32_bf16 v[4:7], v[182:185], v[222:225], v[4:7]
	v_mfma_f32_16x16x32_bf16 v[0:3], v[190:193], v[222:225], v[0:3]
	s_barrier
	s_add_u32 s0, s0, 0x100
	s_addc_u32 s1, s1, 0
	s_add_u32 s22, s22, 0x100
	s_addc_u32 s23, s23, 0
	s_cmp_ge_i32 s36, s55
	s_mov_b32 s4, s36
	s_cbranch_scc0 .LBB0_151
	s_branch .Lpeel_exit_g1

; #define PG8_BAR __builtin_amdgcn_s_barrier()
; template <class Epi, class Sched, bool ALIGN_EPI = false, bool SP2 = false>
; __device__ __forceinline__ void gemm_phase(PG8_LAS unsigned char* lds, const Gemm g, const Sched& S, const Epi& E, int tid_in) {
;     ...
;         if constexpr (ALIGN_EPI) { if (wr == 0) PG8_BAR; }
;         if constexpr (!Epi::AFTER_DRAIN) { E(acc, cur, wr, wc, fr, fq); S.done(cur); }
.Lpeel_exit_g1:
	s_mov_b32 s88, 0x3a000000

; __device__ __forceinline__ void rows_rstd(const float* part, int M, int row0, int fr, int fq, float (&rs)[8]) {
;     const int L = fr | (fq << 4); const float* p = part + (row0 - fr) + L; float sa = 0.f, sb = 0.f;
; #pragma unroll
;     for (int i = 0; i < 32; ++i) { sa += p[(size_t)i * M]; sb += p[(size_t)i * M + HALF]; }
;     const int ra = __builtin_bit_cast(int, rsqrtf(sa * (1.0f / 2048.0f) + RMS_EPS)), rb = __builtin_bit_cast(int, rsqrtf(sb * (1.0f / 2048.0f) + RMS_EPS));
;     __device__ __forceinline__ void operator()(const f32x4 (&acc)[2][2][4][2], const Unit& u, int wr, int wc, int fr, int fq) const {
;         const int row0 = u.pm * BM + wr * 64 + fr; const int col0 = u.pn * BM + wc * 32 + 8 * fq;
;         float rs8[8]; rows_rstd(part, M, row0, fr, fq, rs8);
.LBB0_155:
	s_lshl_b32 s0, s67, 8
	s_add_i32 s0, s0, s56
	v_or_b32_e32 v150, s0, v147
	v_mul_lo_u32 v150, v150, s97
	v_lshl_or_b32 v143, s66, 8, v155
	v_lshl_add_u32 v150, v143, 1, v150
	v_and_b32_e32 v148, 0x60, v155
	v_lshlrev_b32_e32 v148, 4, v148
	s_lshl_b32 s1, s56, 5
	s_add_i32 s1, s1, 0x21000
	v_add_u32_e32 v146, s1, v148
	v_lshl_add_u32 v148, v147, 2, v146
	s_cmp_eq_u32 s100, s67
	s_cbranch_scc1 .Lepi_g1_cached
	v_readfirstlane_b32 s98, v134
	v_readfirstlane_b32 s99, v135
	v_lshlrev_b32_e32 v142, 2, v147
	v_and_b32_e32 v143, 0x18, v155
	v_lshl_add_u32 v142, v143, 3, v142
	v_add_u32_e32 v146, v146, v142
	s_lshl_b32 s0, s0, 2
	v_add_u32_e32 v142, s0, v142
	s_nop 1
	global_load_dword v168, v142, s[98:99]
	global_load_dword v169, v142, s[98:99] offset:512
	s_add_u32 s98, s98, 0x20000
	s_addc_u32 s99, s99, 0
	global_load_dword v170, v142, s[98:99]
	global_load_dword v171, v142, s[98:99] offset:512
	s_add_u32 s98, s98, 0x20000
	s_addc_u32 s99, s99, 0
	global_load_dword v172, v142, s[98:99]
	global_load_dword v173, v142, s[98:99] offset:512
	s_add_u32 s98, s98, 0x20000
	s_addc_u32 s99, s99, 0
	global_load_dword v174, v142, s[98:99]
	global_load_dword v175, v142, s[98:99] offset:512
	s_add_u32 s98, s98, 0x20000
	s_addc_u32 s99, s99, 0
	global_load_dword v176, v142, s[98:99]
	global_load_dword v177, v142, s[98:99] offset:512
	s_add_u32 s98, s98, 0x20000
	s_addc_u32 s99, s99, 0
	global_load_dword v178, v142, s[98:99]
	global_load_dword v179, v142, s[98:99] offset:512
	s_add_u32 s98, s98, 0x20000
	s_addc_u32 s99, s99, 0
	global_load_dword v180, v142, s[98:99]
	global_load_dword v181, v142, s[98:99] offset:512
	s_add_u32 s98, s98, 0x20000
	s_addc_u32 s99, s99, 0
	global_load_dword v182, v142, s[98:99]
	global_load_dword v183, v142, s[98:99] offset:512
	s_add_u32 s98, s98, 0x20000
	s_addc_u32 s99, s99, 0
	global_load_dword v184, v142, s[98:99]
	global_load_dword v185, v142, s[98:99] offset:512
	s_add_u32 s98, s98, 0x20000
	s_addc_u32 s99, s99, 0
	global_load_dword v186, v142, s[98:99]
	global_load_dword v187, v142, s[98:99] offset:512
	s_add_u32 s98, s98, 0x20000
	s_addc_u32 s99, s99, 0
	global_load_dword v188, v142, s[98:99]
	global_load_dword v189, v142, s[98:99] offset:512
	s_add_u32 s98, s98, 0x20000
	s_addc_u32 s99, s99, 0
	global_load_dword v190, v142, s[98:99]
	global_load_dword v191, v142, s[98:99] offset:512
	s_add_u32 s98, s98, 0x20000
	s_addc_u32 s99, s99, 0
	global_load_dword v192, v142, s[98:99]
	global_load_dword v193, v142, s[98:99] offset:512
	s_add_u32 s98, s98, 0x20000
	s_addc_u32 s99, s99, 0
	global_load_dword v194, v142, s[98:99]
	global_load_dword v195, v142, s[98:99] offset:512
	s_add_u32 s98, s98, 0x20000
	s_addc_u32 s99, s99, 0
	global_load_dword v196, v142, s[98:99]
	global_load_dword v197, v142, s[98:99] offset:512
	s_add_u32 s98, s98, 0x20000
	s_addc_u32 s99, s99, 0
	global_load_dword v198, v142, s[98:99]
	global_load_dword v199, v142, s[98:99] offset:512
	s_add_u32 s98, s98, 0x20000
	s_addc_u32 s99, s99, 0
	global_load_dword v200, v142, s[98:99]
	global_load_dword v201, v142, s[98:99] offset:512
	s_add_u32 s98, s98, 0x20000
	s_addc_u32 s99, s99, 0
	global_load_dword v202, v142, s[98:99]
	global_load_dword v203, v142, s[98:99] offset:512
	s_add_u32 s98, s98, 0x20000
	s_addc_u32 s99, s99, 0
	global_load_dword v204, v142, s[98:99]
	global_load_dword v205, v142, s[98:99] offset:512
	s_add_u32 s98, s98, 0x20000
	s_addc_u32 s99, s99, 0
	global_load_dword v206, v142, s[98:99]
	global_load_dword v207, v142, s[98:99] offset:512
	s_add_u32 s98, s98, 0x20000
	s_addc_u32 s99, s99, 0
	global_load_dword v208, v142, s[98:99]
	global_load_dword v209, v142, s[98:99] offset:512
	s_add_u32 s98, s98, 0x20000
	s_addc_u32 s99, s99, 0
	global_load_dword v210, v142, s[98:99]
	global_load_dword v211, v142, s[98:99] offset:512
	s_add_u32 s98, s98, 0x20000
	s_addc_u32 s99, s99, 0
	global_load_dword v212, v142, s[98:99]
	global_load_dword v213, v142, s[98:99] offset:512
	s_add_u32 s98, s98, 0x20000
	s_addc_u32 s99, s99, 0
	global_load_dword v214, v142, s[98:99]
	global_load_dword v215, v142, s[98:99] offset:512
	s_add_u32 s98, s98, 0x20000
	s_addc_u32 s99, s99, 0
	global_load_dword v216, v142, s[98:99]
	global_load_dword v217, v142, s[98:99] offset:512
	s_add_u32 s98, s98, 0x20000
	s_addc_u32 s99, s99, 0
	global_load_dword v218, v142, s[98:99]
	global_load_dword v219, v142, s[98:99] offset:512
	s_add_u32 s98, s98, 0x20000
	s_addc_u32 s99, s99, 0
	global_load_dword v220, v142, s[98:99]
	global_load_dword v221, v142, s[98:99] offset:512
	s_add_u32 s98, s98, 0x20000
	s_addc_u32 s99, s99, 0
	global_load_dword v222, v142, s[98:99]
	global_load_dword v223, v142, s[98:99] offset:512
	s_add_u32 s98, s98, 0x20000
	s_addc_u32 s99, s99, 0
	global_load_dword v224, v142, s[98:99]
	global_load_dword v225, v142, s[98:99] offset:512
	s_add_u32 s98, s98, 0x20000
	s_addc_u32 s99, s99, 0
	global_load_dword v226, v142, s[98:99]
	global_load_dword v227, v142, s[98:99] offset:512
	s_add_u32 s98, s98, 0x20000
	s_addc_u32 s99, s99, 0
	global_load_dword v228, v142, s[98:99]
	global_load_dword v229, v142, s[98:99] offset:512
	s_add_u32 s98, s98, 0x20000
	s_addc_u32 s99, s99, 0
	global_load_dword v140, v142, s[98:99]
	global_load_dword v141, v142, s[98:99] offset:512
	s_waitcnt vmcnt(62)
	v_add_f32_e32 v143, 0, v168
	v_add_f32_e32 v144, 0, v169
	s_waitcnt vmcnt(60)
	v_add_f32_e32 v143, v143, v170
	v_add_f32_e32 v144, v144, v171
	s_waitcnt vmcnt(58)
	v_add_f32_e32 v143, v143, v172
	v_add_f32_e32 v144, v144, v173
	s_waitcnt vmcnt(56)
	v_add_f32_e32 v143, v143, v174
	v_add_f32_e32 v144, v144, v175
	s_waitcnt vmcnt(54)
	v_add_f32_e32 v143, v143, v176
	v_add_f32_e32 v144, v144, v177
	s_waitcnt vmcnt(52)
; __device__ __forceinline__ unsigned cvt_pk_bf16(float lo, float hi) { unsigned r; asm volatile("s_nop 0\n\tv_cvt_pk_bf16_f32 %0, %1, %2" : "=v"(r) : "v"(lo), "v"(hi)); return r; }
; __device__ __forceinline__ void rows_rstd(const float* part, int M, int row0, int fr, int fq, float (&rs)[8]) {
;     ...
;     for (int i = 0; i < 32; ++i) { sa += p[(size_t)i * M]; sb += p[(size_t)i * M + HALF]; }
;     const int ra = __builtin_bit_cast(int, rsqrtf(sa * (1.0f / 2048.0f) + RMS_EPS)), rb = __builtin_bit_cast(int, rsqrtf(sb * (1.0f / 2048.0f) + RMS_EPS));
; #pragma unroll
;     for (int r = 0; r < 8; ++r) rs[r] = __builtin_bit_cast(float, __builtin_amdgcn_ds_bpermute(((r & 3) * 16 + fr) << 2, (r >> 2) ? rb : ra));
; }
;     __device__ __forceinline__ void operator()(const f32x4 (&acc)[2][2][4][2], const Unit& u, int wr, int wc, int fr, int fq) const {
;     ...
;             for (int m = 0; m < 4; ++m) { const int row = row0 + ai * HALF + m * 16; const float rs = rs8[ai * 4 + m];
;                 bf16_t* rowp = O + (size_t)row * ldc + col0;
; #pragma unroll
;                 for (int bj = 0; bj < 2; ++bj) { const f32x4 v0 = acc[ai][bj][m][0] * rs, v1 = acc[ai][bj][m][1] * rs;
;                     u32x4 w; w.x = cvt_pk_bf16(v0[0], v0[1]); w.y = cvt_pk_bf16(v0[2], v0[3]); w.z = cvt_pk_bf16(v1[0], v1[1]); w.w = cvt_pk_bf16(v1[2], v1[3]);
;                     *(u32x4*)(rowp + bj * HALF) = w; } }
	v_add_f32_e32 v143, v143, v178
	v_add_f32_e32 v144, v144, v179
	s_waitcnt vmcnt(50)
	v_add_f32_e32 v143, v143, v180
	v_add_f32_e32 v144, v144, v181
	s_waitcnt vmcnt(48)
	v_add_f32_e32 v143, v143, v182
	v_add_f32_e32 v144, v144, v183
	s_waitcnt vmcnt(46)
	v_add_f32_e32 v143, v143, v184
	v_add_f32_e32 v144, v144, v185
	s_waitcnt vmcnt(44)
	v_add_f32_e32 v143, v143, v186
	v_add_f32_e32 v144, v144, v187
	s_waitcnt vmcnt(42)
	v_add_f32_e32 v143, v143, v188
	v_add_f32_e32 v144, v144, v189
	s_waitcnt vmcnt(40)
	v_add_f32_e32 v143, v143, v190
	v_add_f32_e32 v144, v144, v191
	s_waitcnt vmcnt(38)
	v_add_f32_e32 v143, v143, v192
	v_add_f32_e32 v144, v144, v193
	s_waitcnt vmcnt(36)
	v_add_f32_e32 v143, v143, v194
	v_add_f32_e32 v144, v144, v195
	s_waitcnt vmcnt(34)
	v_add_f32_e32 v143, v143, v196
	v_add_f32_e32 v144, v144, v197
	s_waitcnt vmcnt(32)
	v_add_f32_e32 v143, v143, v198
	v_add_f32_e32 v144, v144, v199
	s_waitcnt vmcnt(30)
	v_add_f32_e32 v143, v143, v200
	v_add_f32_e32 v144, v144, v201
	s_waitcnt vmcnt(28)
	v_add_f32_e32 v143, v143, v202
	v_add_f32_e32 v144, v144, v203
	s_waitcnt vmcnt(26)
	v_add_f32_e32 v143, v143, v204
	v_add_f32_e32 v144, v144, v205
	s_waitcnt vmcnt(24)
	v_add_f32_e32 v143, v143, v206
	v_add_f32_e32 v144, v144, v207
	s_waitcnt vmcnt(22)
	v_add_f32_e32 v143, v143, v208
	v_add_f32_e32 v144, v144, v209
	s_waitcnt vmcnt(20)
	v_add_f32_e32 v143, v143, v210
	v_add_f32_e32 v144, v144, v211
	s_waitcnt vmcnt(18)
	v_add_f32_e32 v143, v143, v212
	v_add_f32_e32 v144, v144, v213
	s_waitcnt vmcnt(16)
	v_add_f32_e32 v143, v143, v214
	v_add_f32_e32 v144, v144, v215
	s_waitcnt vmcnt(14)
	v_add_f32_e32 v143, v143, v216
	v_add_f32_e32 v144, v144, v217
	s_waitcnt vmcnt(12)
	v_add_f32_e32 v143, v143, v218
	v_add_f32_e32 v144, v144, v219
	s_waitcnt vmcnt(10)
	v_add_f32_e32 v143, v143, v220
	v_add_f32_e32 v144, v144, v221
	s_waitcnt vmcnt(8)
	v_add_f32_e32 v143, v143, v222
	v_add_f32_e32 v144, v144, v223
	s_waitcnt vmcnt(6)
	v_add_f32_e32 v143, v143, v224
	v_add_f32_e32 v144, v144, v225
	s_waitcnt vmcnt(4)
	v_add_f32_e32 v143, v143, v226
	v_add_f32_e32 v144, v144, v227
	s_waitcnt vmcnt(2)
	v_add_f32_e32 v143, v143, v228
	v_add_f32_e32 v144, v144, v229
	s_waitcnt vmcnt(0)
	v_add_f32_e32 v143, v143, v140
	v_add_f32_e32 v144, v144, v141
	s_mov_b32 s1, 0x3a000000
	v_fma_f32 v143, v143, s1, v158
	v_fma_f32 v144, v144, s1, v158
	v_rsq_f32_e32 v143, v143
	v_rsq_f32_e32 v144, v144
	s_mov_b32 s100, s67
	s_nop 0
	ds_write_b32 v146, v143
	ds_write_b32 v146, v144 offset:256
.Lepi_g1_cached:
	ds_read_b32 v168, v148 offset:0
	ds_read_b32 v170, v148 offset:64
	ds_read_b32 v172, v148 offset:128
	ds_read_b32 v174, v148 offset:192
	ds_read_b32 v176, v148 offset:256
	ds_read_b32 v178, v148 offset:320
	ds_read_b32 v180, v148 offset:384
	ds_read_b32 v182, v148 offset:448
	s_lshl_b32 s0, s97, 4
	s_mul_i32 s1, s97, 0x50
	s_waitcnt lgkmcnt(7)
	v_pk_mul_f32 v[124:125], v[124:125], v[168:169] op_sel_hi:[1,0]
	v_pk_mul_f32 v[126:127], v[126:127], v[168:169] op_sel_hi:[1,0]
	v_pk_mul_f32 v[120:121], v[120:121], v[168:169] op_sel_hi:[1,0]
	v_pk_mul_f32 v[122:123], v[122:123], v[168:169] op_sel_hi:[1,0]
	v_cvt_pk_bf16_f32 v184, v124, v125
	v_cvt_pk_bf16_f32 v185, v126, v127
	v_cvt_pk_bf16_f32 v186, v120, v121
	v_cvt_pk_bf16_f32 v187, v122, v123
	global_store_dwordx4 v150, v[184:187], s[14:15]
	v_pk_mul_f32 v[116:117], v[116:117], v[168:169] op_sel_hi:[1,0]
	v_pk_mul_f32 v[118:119], v[118:119], v[168:169] op_sel_hi:[1,0]
	v_pk_mul_f32 v[112:113], v[112:113], v[168:169] op_sel_hi:[1,0]
	v_pk_mul_f32 v[114:115], v[114:115], v[168:169] op_sel_hi:[1,0]
	v_cvt_pk_bf16_f32 v188, v116, v117
	v_cvt_pk_bf16_f32 v189, v118, v119
	v_cvt_pk_bf16_f32 v190, v112, v113
	v_cvt_pk_bf16_f32 v191, v114, v115
	global_store_dwordx4 v150, v[188:191], s[14:15] offset:256
	v_add_u32_e32 v150, s0, v150
	s_waitcnt lgkmcnt(6)
	v_pk_mul_f32 v[108:109], v[108:109], v[170:171] op_sel_hi:[1,0]
	v_pk_mul_f32 v[110:111], v[110:111], v[170:171] op_sel_hi:[1,0]
	v_pk_mul_f32 v[104:105], v[104:105], v[170:171] op_sel_hi:[1,0]
	v_pk_mul_f32 v[106:107], v[106:107], v[170:171] op_sel_hi:[1,0]
	v_cvt_pk_bf16_f32 v184, v108, v109
	v_cvt_pk_bf16_f32 v185, v110, v111
	v_cvt_pk_bf16_f32 v186, v104, v105
	v_cvt_pk_bf16_f32 v187, v106, v107
	global_store_dwordx4 v150, v[184:187], s[14:15]
	v_pk_mul_f32 v[100:101], v[100:101], v[170:171] op_sel_hi:[1,0]
	v_pk_mul_f32 v[102:103], v[102:103], v[170:171] op_sel_hi:[1,0]
	v_pk_mul_f32 v[96:97], v[96:97], v[170:171] op_sel_hi:[1,0]
	v_pk_mul_f32 v[98:99], v[98:99], v[170:171] op_sel_hi:[1,0]
	v_cvt_pk_bf16_f32 v188, v100, v101
	v_cvt_pk_bf16_f32 v189, v102, v103
	v_cvt_pk_bf16_f32 v190, v96, v97
	v_cvt_pk_bf16_f32 v191, v98, v99
	global_store_dwordx4 v150, v[188:191], s[14:15] offset:256
	v_add_u32_e32 v150, s0, v150
	s_waitcnt lgkmcnt(5)
; __device__ __forceinline__ unsigned cvt_pk_bf16(float lo, float hi) { unsigned r; asm volatile("s_nop 0\n\tv_cvt_pk_bf16_f32 %0, %1, %2" : "=v"(r) : "v"(lo), "v"(hi)); return r; }
;     __device__ __forceinline__ void operator()(const f32x4 (&acc)[2][2][4][2], const Unit& u, int wr, int wc, int fr, int fq) const {
;     ...
;             for (int m = 0; m < 4; ++m) { const int row = row0 + ai * HALF + m * 16; const float rs = rs8[ai * 4 + m];
;                 bf16_t* rowp = O + (size_t)row * ldc + col0;
; #pragma unroll
;                 for (int bj = 0; bj < 2; ++bj) { const f32x4 v0 = acc[ai][bj][m][0] * rs, v1 = acc[ai][bj][m][1] * rs;
;                     u32x4 w; w.x = cvt_pk_bf16(v0[0], v0[1]); w.y = cvt_pk_bf16(v0[2], v0[3]); w.z = cvt_pk_bf16(v1[0], v1[1]); w.w = cvt_pk_bf16(v1[2], v1[3]);
;                     *(u32x4*)(rowp + bj * HALF) = w; } }
	v_pk_mul_f32 v[92:93], v[92:93], v[172:173] op_sel_hi:[1,0]
	v_pk_mul_f32 v[94:95], v[94:95], v[172:173] op_sel_hi:[1,0]
	v_pk_mul_f32 v[88:89], v[88:89], v[172:173] op_sel_hi:[1,0]
	v_pk_mul_f32 v[90:91], v[90:91], v[172:173] op_sel_hi:[1,0]
	v_cvt_pk_bf16_f32 v184, v92, v93
	v_cvt_pk_bf16_f32 v185, v94, v95
	v_cvt_pk_bf16_f32 v186, v88, v89
	v_cvt_pk_bf16_f32 v187, v90, v91
	global_store_dwordx4 v150, v[184:187], s[14:15]
	v_pk_mul_f32 v[84:85], v[84:85], v[172:173] op_sel_hi:[1,0]
	v_pk_mul_f32 v[86:87], v[86:87], v[172:173] op_sel_hi:[1,0]
	v_pk_mul_f32 v[80:81], v[80:81], v[172:173] op_sel_hi:[1,0]
	v_pk_mul_f32 v[82:83], v[82:83], v[172:173] op_sel_hi:[1,0]
	v_cvt_pk_bf16_f32 v188, v84, v85
	v_cvt_pk_bf16_f32 v189, v86, v87
	v_cvt_pk_bf16_f32 v190, v80, v81
	v_cvt_pk_bf16_f32 v191, v82, v83
	global_store_dwordx4 v150, v[188:191], s[14:15] offset:256
	v_add_u32_e32 v150, s0, v150
	s_waitcnt lgkmcnt(4)
	v_pk_mul_f32 v[76:77], v[76:77], v[174:175] op_sel_hi:[1,0]
	v_pk_mul_f32 v[78:79], v[78:79], v[174:175] op_sel_hi:[1,0]
	v_pk_mul_f32 v[72:73], v[72:73], v[174:175] op_sel_hi:[1,0]
	v_pk_mul_f32 v[74:75], v[74:75], v[174:175] op_sel_hi:[1,0]
	v_cvt_pk_bf16_f32 v184, v76, v77
	v_cvt_pk_bf16_f32 v185, v78, v79
	v_cvt_pk_bf16_f32 v186, v72, v73
	v_cvt_pk_bf16_f32 v187, v74, v75
	global_store_dwordx4 v150, v[184:187], s[14:15]
	v_pk_mul_f32 v[68:69], v[68:69], v[174:175] op_sel_hi:[1,0]
	v_pk_mul_f32 v[70:71], v[70:71], v[174:175] op_sel_hi:[1,0]
	v_pk_mul_f32 v[64:65], v[64:65], v[174:175] op_sel_hi:[1,0]
	v_pk_mul_f32 v[66:67], v[66:67], v[174:175] op_sel_hi:[1,0]
	v_cvt_pk_bf16_f32 v188, v68, v69
	v_cvt_pk_bf16_f32 v189, v70, v71
	v_cvt_pk_bf16_f32 v190, v64, v65
	v_cvt_pk_bf16_f32 v191, v66, v67
	global_store_dwordx4 v150, v[188:191], s[14:15] offset:256
	v_add_u32_e32 v150, s1, v150
	s_waitcnt lgkmcnt(3)
	v_pk_mul_f32 v[60:61], v[60:61], v[176:177] op_sel_hi:[1,0]
	v_pk_mul_f32 v[62:63], v[62:63], v[176:177] op_sel_hi:[1,0]
	v_pk_mul_f32 v[56:57], v[56:57], v[176:177] op_sel_hi:[1,0]
	v_pk_mul_f32 v[58:59], v[58:59], v[176:177] op_sel_hi:[1,0]
	v_cvt_pk_bf16_f32 v184, v60, v61
	v_cvt_pk_bf16_f32 v185, v62, v63
	v_cvt_pk_bf16_f32 v186, v56, v57
	v_cvt_pk_bf16_f32 v187, v58, v59
	global_store_dwordx4 v150, v[184:187], s[14:15]
	v_pk_mul_f32 v[52:53], v[52:53], v[176:177] op_sel_hi:[1,0]
	v_pk_mul_f32 v[54:55], v[54:55], v[176:177] op_sel_hi:[1,0]
	v_pk_mul_f32 v[48:49], v[48:49], v[176:177] op_sel_hi:[1,0]
	v_pk_mul_f32 v[50:51], v[50:51], v[176:177] op_sel_hi:[1,0]
	v_cvt_pk_bf16_f32 v188, v52, v53
	v_cvt_pk_bf16_f32 v189, v54, v55
	v_cvt_pk_bf16_f32 v190, v48, v49
	v_cvt_pk_bf16_f32 v191, v50, v51
	global_store_dwordx4 v150, v[188:191], s[14:15] offset:256
	v_add_u32_e32 v150, s0, v150
	s_waitcnt lgkmcnt(2)
	v_pk_mul_f32 v[44:45], v[44:45], v[178:179] op_sel_hi:[1,0]
	v_pk_mul_f32 v[46:47], v[46:47], v[178:179] op_sel_hi:[1,0]
	v_pk_mul_f32 v[40:41], v[40:41], v[178:179] op_sel_hi:[1,0]
	v_pk_mul_f32 v[42:43], v[42:43], v[178:179] op_sel_hi:[1,0]
	v_cvt_pk_bf16_f32 v184, v44, v45
	v_cvt_pk_bf16_f32 v185, v46, v47
	v_cvt_pk_bf16_f32 v186, v40, v41
	v_cvt_pk_bf16_f32 v187, v42, v43
	global_store_dwordx4 v150, v[184:187], s[14:15]
	v_pk_mul_f32 v[36:37], v[36:37], v[178:179] op_sel_hi:[1,0]
	v_pk_mul_f32 v[38:39], v[38:39], v[178:179] op_sel_hi:[1,0]
	v_pk_mul_f32 v[32:33], v[32:33], v[178:179] op_sel_hi:[1,0]
	v_pk_mul_f32 v[34:35], v[34:35], v[178:179] op_sel_hi:[1,0]
	v_cvt_pk_bf16_f32 v188, v36, v37
	v_cvt_pk_bf16_f32 v189, v38, v39
	v_cvt_pk_bf16_f32 v190, v32, v33
	v_cvt_pk_bf16_f32 v191, v34, v35
	global_store_dwordx4 v150, v[188:191], s[14:15] offset:256
	v_add_u32_e32 v150, s0, v150
	s_waitcnt lgkmcnt(1)
	v_pk_mul_f32 v[28:29], v[28:29], v[180:181] op_sel_hi:[1,0]
	v_pk_mul_f32 v[30:31], v[30:31], v[180:181] op_sel_hi:[1,0]
	v_pk_mul_f32 v[24:25], v[24:25], v[180:181] op_sel_hi:[1,0]
	v_pk_mul_f32 v[26:27], v[26:27], v[180:181] op_sel_hi:[1,0]
	v_cvt_pk_bf16_f32 v184, v28, v29
	v_cvt_pk_bf16_f32 v185, v30, v31
	v_cvt_pk_bf16_f32 v186, v24, v25
	v_cvt_pk_bf16_f32 v187, v26, v27
	global_store_dwordx4 v150, v[184:187], s[14:15]
	v_pk_mul_f32 v[20:21], v[20:21], v[180:181] op_sel_hi:[1,0]
	v_pk_mul_f32 v[22:23], v[22:23], v[180:181] op_sel_hi:[1,0]
	v_pk_mul_f32 v[16:17], v[16:17], v[180:181] op_sel_hi:[1,0]
	v_pk_mul_f32 v[18:19], v[18:19], v[180:181] op_sel_hi:[1,0]
	v_cvt_pk_bf16_f32 v188, v20, v21
	v_cvt_pk_bf16_f32 v189, v22, v23
	v_cvt_pk_bf16_f32 v190, v16, v17
	v_cvt_pk_bf16_f32 v191, v18, v19
	global_store_dwordx4 v150, v[188:191], s[14:15] offset:256
	v_add_u32_e32 v150, s0, v150
	s_waitcnt lgkmcnt(0)
	v_pk_mul_f32 v[12:13], v[12:13], v[182:183] op_sel_hi:[1,0]
	v_pk_mul_f32 v[14:15], v[14:15], v[182:183] op_sel_hi:[1,0]
	v_pk_mul_f32 v[8:9], v[8:9], v[182:183] op_sel_hi:[1,0]
	v_pk_mul_f32 v[10:11], v[10:11], v[182:183] op_sel_hi:[1,0]
	v_cvt_pk_bf16_f32 v184, v12, v13
	v_cvt_pk_bf16_f32 v185, v14, v15
	v_cvt_pk_bf16_f32 v186, v8, v9
	v_cvt_pk_bf16_f32 v187, v10, v11
	global_store_dwordx4 v150, v[184:187], s[14:15]
	v_pk_mul_f32 v[4:5], v[4:5], v[182:183] op_sel_hi:[1,0]
	v_pk_mul_f32 v[6:7], v[6:7], v[182:183] op_sel_hi:[1,0]
	v_pk_mul_f32 v[0:1], v[0:1], v[182:183] op_sel_hi:[1,0]
	v_pk_mul_f32 v[2:3], v[2:3], v[182:183] op_sel_hi:[1,0]
	v_cvt_pk_bf16_f32 v188, v4, v5
	v_cvt_pk_bf16_f32 v189, v6, v7
	v_cvt_pk_bf16_f32 v190, v0, v1
	v_cvt_pk_bf16_f32 v191, v2, v3
	global_store_dwordx4 v150, v[188:191], s[14:15] offset:256
	s_and_b64 vcc, exec, s[2:3]
	s_mov_b64 s[0:1], -1
	s_cbranch_vccnz .LBB0_142
	s_andn2_b64 vcc, exec, s[12:13]
	s_cbranch_vccnz .LBB0_141
	s_barrier
	s_branch .LBB0_141

; #define PG8_STAGE(bufoff, gbase, voff) do { _Pragma("unroll") for (int _i = 0; _i < 2; ++_i) \
;         __builtin_amdgcn_global_load_lds((const unsigned*)((const char*)(gbase) + (voff)[_i]), (PG8_LAS unsigned*)(lds + (bufoff) + ldsw + _i * 8192), 16, 0, 0); } while (0)
; #define PG8_LDA(dst, b, h) do { _Pragma("unroll") for (int m = 0; m < 4; ++m) _Pragma("unroll") for (int k = 0; k < 2; ++k) dst[m][k] = *(const PG8_LAS bf16x8*)(lds + PG8_SA(b, h) + aoff + m * 2048 + k * 1024); } while (0)
; #define PG8_LDB(dst, b, h) do { _Pragma("unroll") for (int n = 0; n < 2; ++n) _Pragma("unroll") for (int k = 0; k < 2; ++k) dst[n][k] = *(const PG8_LAS bf16x8*)(lds + PG8_SB(b, h) + boff + n * 2048 + k * 1024); } while (0)
; #define PG8_MMA(ai, bj, At, Bt) do { __builtin_amdgcn_s_setprio(1); _Pragma("unroll") for (int m = 0; m < 4; ++m) _Pragma("unroll") for (int n = 0; n < 2; ++n) _Pragma("unroll") for (int k = 0; k < 2; ++k) \
;         acc[ai][bj][m][n] = __builtin_amdgcn_mfma_f32_16x16x32_bf16(Bt[n][k], At[m][k], acc[ai][bj][m][n], 0, 0, 0); __builtin_amdgcn_s_setprio(0); } while (0)
; #define PG8_WAIT_V(n) asm volatile("s_waitcnt vmcnt(" #n ")" ::: "memory")
; #define PG8_WAIT_L(n) asm volatile("s_waitcnt lgkmcnt(" #n ")" ::: "memory")
; template <class Epi, class Sched, bool ALIGN_EPI = false, bool SP2 = false>
; __device__ __forceinline__ void gemm_phase(PG8_LAS unsigned char* lds, const Gemm g, const Sched& S, const Epi& E, int tid_in) {
;     ...
;             const bool last = (t == nt - 2);
;             const char* a1 = cA + (size_t)(t + 1) * kstep;
;             const char* a2 = last ? nA : cA + (size_t)(t + 2) * kstep; const char* b2 = last ? nB : cB + (size_t)(t + 2) * kstep;
;             const char* a3 = a2 + kstep; const char* b3 = b2 + kstep;
;             if (last && has_next) S.a_ready(nxt);
;             if constexpr (SP2) {
;             PG8_LDB(B0, 0, 0); PG8_LDB(B1, 0, 1); PG8_SCHED; PG8_LDA(At, 0, 0); PG8_STAGE(PG8_SA(1, 1), a1 + hstep, voffA);
;             PG8_WAIT_V(8); PG8_WAIT_L(0); PG8_BAR; PG8_MMA(0, 0, At, B0); PG8_MMA(0, 1, At, B1); PG8_BAR; PG8_SCHED;
;     ...
;         for (int a = 0; a < 2; ++a)
; #pragma unroll
;             for (int b = 0; b < 2; ++b)
; #pragma unroll
;                 for (int m = 0; m < 4; ++m)
; #pragma unroll
;                     for (int n = 0; n < 2; ++n) acc[a][b][m][n] = (f32x4){0.f, 0.f, 0.f, 0.f};
.LBB0_818:
	s_andn2_b64 vcc, exec, s[38:39]
	s_waitcnt lgkmcnt(0)
	s_cbranch_vccz .Lpeel_enter_g2
	v_mov_b32_e32 v127, 0
	v_mov_b32_e32 v126, v127
	v_mov_b32_e32 v125, v127
	v_mov_b32_e32 v124, v127
	v_mov_b32_e32 v123, v127
	v_mov_b32_e32 v122, v127
	v_mov_b32_e32 v121, v127
	v_mov_b32_e32 v120, v127
	v_mov_b32_e32 v111, v127
	v_mov_b32_e32 v110, v127
	v_mov_b32_e32 v109, v127
	v_mov_b32_e32 v108, v127
	v_mov_b32_e32 v107, v127
	v_mov_b32_e32 v106, v127
	v_mov_b32_e32 v105, v127
	v_mov_b32_e32 v104, v127
	v_mov_b32_e32 v95, v127
	v_mov_b32_e32 v94, v127
	v_mov_b32_e32 v93, v127
	v_mov_b32_e32 v92, v127
	v_mov_b32_e32 v91, v127
	v_mov_b32_e32 v90, v127
	v_mov_b32_e32 v89, v127
	v_mov_b32_e32 v88, v127
	v_mov_b32_e32 v79, v127
	v_mov_b32_e32 v78, v127
	v_mov_b32_e32 v77, v127
	v_mov_b32_e32 v76, v127
	v_mov_b32_e32 v75, v127
	v_mov_b32_e32 v74, v127
	v_mov_b32_e32 v73, v127
	v_mov_b32_e32 v72, v127
	v_mov_b32_e32 v119, v127
	v_mov_b32_e32 v118, v127
	v_mov_b32_e32 v117, v127
	v_mov_b32_e32 v116, v127
	v_mov_b32_e32 v115, v127
	v_mov_b32_e32 v114, v127
	v_mov_b32_e32 v113, v127
	v_mov_b32_e32 v112, v127
	v_mov_b32_e32 v103, v127
	v_mov_b32_e32 v102, v127
	v_mov_b32_e32 v101, v127
	v_mov_b32_e32 v100, v127
	v_mov_b32_e32 v99, v127
	v_mov_b32_e32 v98, v127
	v_mov_b32_e32 v97, v127
	v_mov_b32_e32 v96, v127
	v_mov_b32_e32 v87, v127
	v_mov_b32_e32 v86, v127
	v_mov_b32_e32 v85, v127
	v_mov_b32_e32 v84, v127
	v_mov_b32_e32 v83, v127
	v_mov_b32_e32 v82, v127
	v_mov_b32_e32 v81, v127
	v_mov_b32_e32 v80, v127
	v_mov_b32_e32 v71, v127
	v_mov_b32_e32 v70, v127
	v_mov_b32_e32 v69, v127
	v_mov_b32_e32 v68, v127
	v_mov_b32_e32 v67, v127
	v_mov_b32_e32 v66, v127
	v_mov_b32_e32 v65, v127
	v_mov_b32_e32 v64, v127
	v_mov_b32_e32 v63, v127
	v_mov_b32_e32 v62, v127
	v_mov_b32_e32 v61, v127
	v_mov_b32_e32 v60, v127
	v_mov_b32_e32 v59, v127
	v_mov_b32_e32 v58, v127
	v_mov_b32_e32 v57, v127
	v_mov_b32_e32 v56, v127
	v_mov_b32_e32 v47, v127
	v_mov_b32_e32 v46, v127
	v_mov_b32_e32 v45, v127
	v_mov_b32_e32 v44, v127
	v_mov_b32_e32 v43, v127
	v_mov_b32_e32 v42, v127
	v_mov_b32_e32 v41, v127
	v_mov_b32_e32 v40, v127
	v_mov_b32_e32 v31, v127
	v_mov_b32_e32 v30, v127
	v_mov_b32_e32 v29, v127
	v_mov_b32_e32 v28, v127
	v_mov_b32_e32 v27, v127
	v_mov_b32_e32 v26, v127
	v_mov_b32_e32 v25, v127
	v_mov_b32_e32 v24, v127
	v_mov_b32_e32 v15, v127
	v_mov_b32_e32 v14, v127
	v_mov_b32_e32 v13, v127
	v_mov_b32_e32 v12, v127
	v_mov_b32_e32 v11, v127
	v_mov_b32_e32 v10, v127
	v_mov_b32_e32 v9, v127
	v_mov_b32_e32 v8, v127
	v_mov_b32_e32 v55, v127
	v_mov_b32_e32 v54, v127
	v_mov_b32_e32 v53, v127
	v_mov_b32_e32 v52, v127
	v_mov_b32_e32 v51, v127
	v_mov_b32_e32 v50, v127
	v_mov_b32_e32 v49, v127
	v_mov_b32_e32 v48, v127
	v_mov_b32_e32 v39, v127
	v_mov_b32_e32 v38, v127
	v_mov_b32_e32 v37, v127
	v_mov_b32_e32 v36, v127
	v_mov_b32_e32 v35, v127
	v_mov_b32_e32 v34, v127
	v_mov_b32_e32 v33, v127
	v_mov_b32_e32 v32, v127
	v_mov_b32_e32 v23, v127
	v_mov_b32_e32 v22, v127
	v_mov_b32_e32 v21, v127
	v_mov_b32_e32 v20, v127
	v_mov_b32_e32 v19, v127
	v_mov_b32_e32 v18, v127
	v_mov_b32_e32 v17, v127
	v_mov_b32_e32 v16, v127
	v_mov_b32_e32 v7, v127
	v_mov_b32_e32 v6, v127
	v_mov_b32_e32 v5, v127
	v_mov_b32_e32 v4, v127
	v_mov_b32_e32 v3, v127
	v_mov_b32_e32 v2, v127
	v_mov_b32_e32 v1, v127
	v_mov_b32_e32 v0, v127
	s_branch .LBB0_821
.Lpeel_enter_g2:
	s_add_u32 s0, s0, 0x80
	s_addc_u32 s1, s1, 0
	s_add_u32 s63, s22, 0x100
	s_addc_u32 vcc_lo, s23, 0
	s_mov_b32 s22, 0
	s_add_i32 s36, s22, 2
	s_add_u32 s2, s0, 0x80
	s_addc_u32 s3, s1, 0
	s_add_i32 s37, 0, 0x10000
	s_cmp_eq_u32 s90, s22
	s_cselect_b32 s23, s9, s3
	s_cselect_b32 s22, s8, s2
	s_cselect_b32 s3, s55, vcc_lo
	s_cselect_b32 s2, s54, s63
	s_add_i32 vcc_hi, 0, 0x14000
	v_add_u32_e32 v146, s37, v237
	v_add_u32_e32 v154, vcc_hi, v237
	ds_read_b128 v[134:137], v146
	ds_read_b128 v[138:141], v146 offset:1024
	ds_read_b128 v[142:145], v146 offset:2048
	ds_read_b128 v[146:149], v146 offset:3072
	ds_read_b128 v[150:153], v154
	ds_read_b128 v[166:169], v154 offset:1024
	ds_read_b128 v[170:173], v154 offset:2048
	ds_read_b128 v[174:177], v154 offset:3072
	v_lshl_add_u64 v[154:155], s[0:1], 0, v[130:131]
	s_add_i32 m0, s47, 0xc000
	ds_read_b128 v[178:181], v241
	ds_read_b128 v[182:185], v241 offset:1024
	ds_read_b128 v[186:189], v241 offset:2048
	ds_read_b128 v[190:193], v241 offset:3072
	ds_read_b128 v[194:197], v241 offset:4096
	ds_read_b128 v[198:201], v241 offset:5120
	ds_read_b128 v[202:205], v241 offset:6144
	ds_read_b128 v[206:209], v241 offset:7168
	global_load_lds_dwordx4 v[154:155], off
	v_lshl_add_u64 v[154:155], s[0:1], 0, v[132:133]
	s_add_i32 m0, s47, 0xe000
	s_nop 0
	global_load_lds_dwordx4 v[154:155], off
	s_waitcnt vmcnt(8)
	s_waitcnt lgkmcnt(0)
	s_barrier
; #define PG8_STAGE(bufoff, gbase, voff) do { _Pragma("unroll") for (int _i = 0; _i < 2; ++_i) \
;         __builtin_amdgcn_global_load_lds((const unsigned*)((const char*)(gbase) + (voff)[_i]), (PG8_LAS unsigned*)(lds + (bufoff) + ldsw + _i * 8192), 16, 0, 0); } while (0)
; #define PG8_LDA(dst, b, h) do { _Pragma("unroll") for (int m = 0; m < 4; ++m) _Pragma("unroll") for (int k = 0; k < 2; ++k) dst[m][k] = *(const PG8_LAS bf16x8*)(lds + PG8_SA(b, h) + aoff + m * 2048 + k * 1024); } while (0)
; #define PG8_MMA(ai, bj, At, Bt) do { __builtin_amdgcn_s_setprio(1); _Pragma("unroll") for (int m = 0; m < 4; ++m) _Pragma("unroll") for (int n = 0; n < 2; ++n) _Pragma("unroll") for (int k = 0; k < 2; ++k) \
;         acc[ai][bj][m][n] = __builtin_amdgcn_mfma_f32_16x16x32_bf16(Bt[n][k], At[m][k], acc[ai][bj][m][n], 0, 0, 0); __builtin_amdgcn_s_setprio(0); } while (0)
; #define PG8_WAIT_V(n) asm volatile("s_waitcnt vmcnt(" #n ")" ::: "memory")
; #define PG8_WAIT_L(n) asm volatile("s_waitcnt lgkmcnt(" #n ")" ::: "memory")
; #define PG8_BAR __builtin_amdgcn_s_barrier()
; #define PG8_SCHED __builtin_amdgcn_sched_barrier(0)
; template <class Epi, class Sched, bool ALIGN_EPI = false, bool SP2 = false>
; __device__ __forceinline__ void gemm_phase(PG8_LAS unsigned char* lds, const Gemm g, const Sched& S, const Epi& E, int tid_in) {
;     ...
;             PG8_WAIT_V(8); PG8_WAIT_L(0); PG8_BAR; PG8_MMA(0, 0, At, B0); PG8_MMA(0, 1, At, B1); PG8_BAR; PG8_SCHED;
;             PG8_LDA(At, 0, 1); PG8_STAGE(PG8_SB(0, 0), b2, voffB); PG8_STAGE(PG8_SB(0, 1), b2 + hstep, voffB); PG8_STAGE(PG8_SA(0, 0), a2, voffA);
;             PG8_WAIT_V(8); PG8_WAIT_L(0); PG8_BAR; PG8_MMA(1, 0, At, B0); PG8_MMA(1, 1, At, B1); PG8_BAR; PG8_SCHED;
	s_waitcnt lgkmcnt(0)
	v_mfma_f32_16x16x32_bf16 v[124:127], v[134:137], v[178:181], 0
	v_mfma_f32_16x16x32_bf16 v[120:123], v[142:145], v[178:181], 0
	v_mfma_f32_16x16x32_bf16 v[108:111], v[134:137], v[186:189], 0
	v_mfma_f32_16x16x32_bf16 v[104:107], v[142:145], v[186:189], 0
	v_mfma_f32_16x16x32_bf16 v[92:95], v[134:137], v[194:197], 0
	v_mfma_f32_16x16x32_bf16 v[88:91], v[142:145], v[194:197], 0
	v_mfma_f32_16x16x32_bf16 v[76:79], v[134:137], v[202:205], 0
	v_mfma_f32_16x16x32_bf16 v[72:75], v[142:145], v[202:205], 0
	v_mfma_f32_16x16x32_bf16 v[124:127], v[138:141], v[182:185], v[124:127]
	v_mfma_f32_16x16x32_bf16 v[120:123], v[146:149], v[182:185], v[120:123]
	v_mfma_f32_16x16x32_bf16 v[108:111], v[138:141], v[190:193], v[108:111]
	v_mfma_f32_16x16x32_bf16 v[104:107], v[146:149], v[190:193], v[104:107]
	v_mfma_f32_16x16x32_bf16 v[92:95], v[138:141], v[198:201], v[92:95]
	v_mfma_f32_16x16x32_bf16 v[88:91], v[146:149], v[198:201], v[88:91]
	v_mfma_f32_16x16x32_bf16 v[76:79], v[138:141], v[206:209], v[76:79]
	v_mfma_f32_16x16x32_bf16 v[72:75], v[146:149], v[206:209], v[72:75]
	v_mfma_f32_16x16x32_bf16 v[116:119], v[150:153], v[178:181], 0
	v_mfma_f32_16x16x32_bf16 v[112:115], v[170:173], v[178:181], 0
	v_mfma_f32_16x16x32_bf16 v[100:103], v[150:153], v[186:189], 0
	v_mfma_f32_16x16x32_bf16 v[96:99], v[170:173], v[186:189], 0
	v_mfma_f32_16x16x32_bf16 v[84:87], v[150:153], v[194:197], 0
	v_mfma_f32_16x16x32_bf16 v[80:83], v[170:173], v[194:197], 0
	v_mfma_f32_16x16x32_bf16 v[68:71], v[150:153], v[202:205], 0
	v_mfma_f32_16x16x32_bf16 v[64:67], v[170:173], v[202:205], 0
	v_mfma_f32_16x16x32_bf16 v[116:119], v[166:169], v[182:185], v[116:119]
	v_mfma_f32_16x16x32_bf16 v[112:115], v[174:177], v[182:185], v[112:115]
	v_mfma_f32_16x16x32_bf16 v[100:103], v[166:169], v[190:193], v[100:103]
	v_mfma_f32_16x16x32_bf16 v[96:99], v[174:177], v[190:193], v[96:99]
	v_mfma_f32_16x16x32_bf16 v[84:87], v[166:169], v[198:201], v[84:87]
	v_mfma_f32_16x16x32_bf16 v[80:83], v[174:177], v[198:201], v[80:83]
	v_mfma_f32_16x16x32_bf16 v[68:71], v[166:169], v[206:209], v[68:71]
	v_mfma_f32_16x16x32_bf16 v[64:67], v[174:177], v[206:209], v[64:67]
	s_barrier
	s_add_i32 s37, s37, s46
	v_lshl_add_u64 v[154:155], s[2:3], 0, v[156:157]
	s_mov_b32 m0, s37
	ds_read_b128 v[178:181], v241 offset:16384
	ds_read_b128 v[182:185], v241 offset:17408
	ds_read_b128 v[186:189], v241 offset:18432
	ds_read_b128 v[190:193], v241 offset:19456
	ds_read_b128 v[194:197], v241 offset:20480
	ds_read_b128 v[198:201], v241 offset:21504
	ds_read_b128 v[202:205], v241 offset:22528
	ds_read_b128 v[206:209], v241 offset:23552
	global_load_lds_dwordx4 v[154:155], off
	s_add_i32 m0, s37, 0x2000
	v_lshl_add_u64 v[162:163], s[2:3], 0, v[128:129]
	s_add_u32 s2, s2, s12
	s_addc_u32 s3, s3, s13
	s_add_i32 s37, vcc_hi, s46
	global_load_lds_dwordx4 v[162:163], off
	v_lshl_add_u64 v[210:211], s[2:3], 0, v[156:157]
	s_mov_b32 m0, s37
	v_lshl_add_u64 v[212:213], s[2:3], 0, v[128:129]
	global_load_lds_dwordx4 v[210:211], off
	s_add_i32 m0, s37, 0x2000
	v_lshl_add_u64 v[214:215], s[22:23], 0, v[156:157]
	global_load_lds_dwordx4 v[212:213], off
	s_mov_b32 m0, s47
	v_lshl_add_u64 v[216:217], s[22:23], 0, v[128:129]
	global_load_lds_dwordx4 v[214:215], off
	s_mov_b32 m0, s52
	s_nop 0
	global_load_lds_dwordx4 v[216:217], off
	s_waitcnt vmcnt(8)
	s_waitcnt lgkmcnt(0)
	s_barrier
	s_waitcnt lgkmcnt(0)
	v_mfma_f32_16x16x32_bf16 v[60:63], v[134:137], v[178:181], 0
	v_mfma_f32_16x16x32_bf16 v[56:59], v[142:145], v[178:181], 0
	v_mfma_f32_16x16x32_bf16 v[44:47], v[134:137], v[186:189], 0
	v_mfma_f32_16x16x32_bf16 v[40:43], v[142:145], v[186:189], 0
	v_mfma_f32_16x16x32_bf16 v[28:31], v[134:137], v[194:197], 0
	v_mfma_f32_16x16x32_bf16 v[24:27], v[142:145], v[194:197], 0
	v_mfma_f32_16x16x32_bf16 v[12:15], v[134:137], v[202:205], 0
	v_mfma_f32_16x16x32_bf16 v[8:11], v[142:145], v[202:205], 0
	v_mfma_f32_16x16x32_bf16 v[60:63], v[138:141], v[182:185], v[60:63]
	v_mfma_f32_16x16x32_bf16 v[56:59], v[146:149], v[182:185], v[56:59]
	v_mfma_f32_16x16x32_bf16 v[44:47], v[138:141], v[190:193], v[44:47]
	v_mfma_f32_16x16x32_bf16 v[40:43], v[146:149], v[190:193], v[40:43]
	v_mfma_f32_16x16x32_bf16 v[28:31], v[138:141], v[198:201], v[28:31]
	v_mfma_f32_16x16x32_bf16 v[24:27], v[146:149], v[198:201], v[24:27]
	v_mfma_f32_16x16x32_bf16 v[12:15], v[138:141], v[206:209], v[12:15]
	v_mfma_f32_16x16x32_bf16 v[8:11], v[146:149], v[206:209], v[8:11]
	v_mfma_f32_16x16x32_bf16 v[52:55], v[150:153], v[178:181], 0
	v_mfma_f32_16x16x32_bf16 v[48:51], v[170:173], v[178:181], 0
	v_mfma_f32_16x16x32_bf16 v[36:39], v[150:153], v[186:189], 0
	v_mfma_f32_16x16x32_bf16 v[32:35], v[170:173], v[186:189], 0
	v_mfma_f32_16x16x32_bf16 v[20:23], v[150:153], v[194:197], 0
	v_mfma_f32_16x16x32_bf16 v[16:19], v[170:173], v[194:197], 0
	v_mfma_f32_16x16x32_bf16 v[4:7], v[150:153], v[202:205], 0
	v_mfma_f32_16x16x32_bf16 v[0:3], v[170:173], v[202:205], 0
	v_mfma_f32_16x16x32_bf16 v[52:55], v[166:169], v[182:185], v[52:55]
	v_mfma_f32_16x16x32_bf16 v[48:51], v[174:177], v[182:185], v[48:51]
	v_mfma_f32_16x16x32_bf16 v[36:39], v[166:169], v[190:193], v[36:39]
	v_mfma_f32_16x16x32_bf16 v[32:35], v[174:177], v[190:193], v[32:35]
	v_mfma_f32_16x16x32_bf16 v[20:23], v[166:169], v[198:201], v[20:23]
	v_mfma_f32_16x16x32_bf16 v[16:19], v[174:177], v[198:201], v[16:19]
	v_mfma_f32_16x16x32_bf16 v[4:7], v[166:169], v[206:209], v[4:7]
	v_mfma_f32_16x16x32_bf16 v[0:3], v[174:177], v[206:209], v[0:3]
	s_barrier
; #define PG8_STAGE(bufoff, gbase, voff) do { _Pragma("unroll") for (int _i = 0; _i < 2; ++_i) \
;         __builtin_amdgcn_global_load_lds((const unsigned*)((const char*)(gbase) + (voff)[_i]), (PG8_LAS unsigned*)(lds + (bufoff) + ldsw + _i * 8192), 16, 0, 0); } while (0)
; #define PG8_LDA(dst, b, h) do { _Pragma("unroll") for (int m = 0; m < 4; ++m) _Pragma("unroll") for (int k = 0; k < 2; ++k) dst[m][k] = *(const PG8_LAS bf16x8*)(lds + PG8_SA(b, h) + aoff + m * 2048 + k * 1024); } while (0)
; #define PG8_LDB(dst, b, h) do { _Pragma("unroll") for (int n = 0; n < 2; ++n) _Pragma("unroll") for (int k = 0; k < 2; ++k) dst[n][k] = *(const PG8_LAS bf16x8*)(lds + PG8_SB(b, h) + boff + n * 2048 + k * 1024); } while (0)
; #define PG8_MMA(ai, bj, At, Bt) do { __builtin_amdgcn_s_setprio(1); _Pragma("unroll") for (int m = 0; m < 4; ++m) _Pragma("unroll") for (int n = 0; n < 2; ++n) _Pragma("unroll") for (int k = 0; k < 2; ++k) \
;         acc[ai][bj][m][n] = __builtin_amdgcn_mfma_f32_16x16x32_bf16(Bt[n][k], At[m][k], acc[ai][bj][m][n], 0, 0, 0); __builtin_amdgcn_s_setprio(0); } while (0)
; #define PG8_WAIT_V(n) asm volatile("s_waitcnt vmcnt(" #n ")" ::: "memory")
; #define PG8_WAIT_L(n) asm volatile("s_waitcnt lgkmcnt(" #n ")" ::: "memory")
; #define PG8_BAR __builtin_amdgcn_s_barrier()
; #define PG8_SCHED __builtin_amdgcn_sched_barrier(0)
; template <class Epi, class Sched, bool ALIGN_EPI = false, bool SP2 = false>
; __device__ __forceinline__ void gemm_phase(PG8_LAS unsigned char* lds, const Gemm g, const Sched& S, const Epi& E, int tid_in) {
;     ...
;             PG8_LDB(B0, 1, 0); PG8_LDB(B1, 1, 1); PG8_SCHED; PG8_LDA(At, 1, 0); PG8_STAGE(PG8_SA(0, 1), a2 + hstep, voffA);
;             PG8_WAIT_V(8); PG8_WAIT_L(0); PG8_BAR; PG8_MMA(0, 0, At, B0); PG8_MMA(0, 1, At, B1); PG8_BAR; PG8_SCHED;
;             PG8_LDA(At, 1, 1); PG8_STAGE(PG8_SB(1, 0), b3, voffB); PG8_STAGE(PG8_SB(1, 1), b3 + hstep, voffB); PG8_STAGE(PG8_SA(1, 0), a3, voffA);
;             PG8_WAIT_V(8); PG8_WAIT_L(0); PG8_BAR; PG8_MMA(1, 0, At, B0); PG8_MMA(1, 1, At, B1); PG8_BAR; PG8_SCHED;
	s_add_i32 s37, 0, 0x18000
	s_add_i32 vcc_hi, 0, 0x1c000
	v_add_u32_e32 v146, s37, v237
	v_add_u32_e32 v174, vcc_hi, v237
	ds_read_b128 v[134:137], v146
	ds_read_b128 v[138:141], v146 offset:1024
	ds_read_b128 v[142:145], v146 offset:2048
	ds_read_b128 v[146:149], v146 offset:3072
	ds_read_b128 v[150:153], v174
	ds_read_b128 v[166:169], v174 offset:1024
	ds_read_b128 v[170:173], v174 offset:2048
	ds_read_b128 v[174:177], v174 offset:3072
	s_add_u32 s2, s22, s12
	s_addc_u32 s3, s23, s13
	s_mov_b32 m0, s53
	v_lshl_add_u64 v[218:219], s[2:3], 0, v[156:157]
	ds_read_b128 v[178:181], v241 offset:32768
	ds_read_b128 v[182:185], v241 offset:33792
	ds_read_b128 v[186:189], v241 offset:34816
	ds_read_b128 v[190:193], v241 offset:35840
	ds_read_b128 v[194:197], v241 offset:36864
	ds_read_b128 v[198:201], v241 offset:37888
	ds_read_b128 v[202:205], v241 offset:38912
	ds_read_b128 v[206:209], v241 offset:39936
	global_load_lds_dwordx4 v[218:219], off
	v_lshl_add_u64 v[218:219], s[2:3], 0, v[128:129]
	s_mov_b32 m0, s56
	s_nop 0
	global_load_lds_dwordx4 v[218:219], off
	s_waitcnt vmcnt(8)
	s_waitcnt lgkmcnt(0)
	s_barrier
	s_waitcnt lgkmcnt(0)
	v_mfma_f32_16x16x32_bf16 v[124:127], v[134:137], v[178:181], v[124:127]
	v_mfma_f32_16x16x32_bf16 v[120:123], v[142:145], v[178:181], v[120:123]
	v_mfma_f32_16x16x32_bf16 v[108:111], v[134:137], v[186:189], v[108:111]
	v_mfma_f32_16x16x32_bf16 v[104:107], v[142:145], v[186:189], v[104:107]
	v_mfma_f32_16x16x32_bf16 v[92:95], v[134:137], v[194:197], v[92:95]
	v_mfma_f32_16x16x32_bf16 v[88:91], v[142:145], v[194:197], v[88:91]
	v_mfma_f32_16x16x32_bf16 v[76:79], v[134:137], v[202:205], v[76:79]
	v_mfma_f32_16x16x32_bf16 v[72:75], v[142:145], v[202:205], v[72:75]
	v_mfma_f32_16x16x32_bf16 v[124:127], v[138:141], v[182:185], v[124:127]
	v_mfma_f32_16x16x32_bf16 v[120:123], v[146:149], v[182:185], v[120:123]
	v_mfma_f32_16x16x32_bf16 v[108:111], v[138:141], v[190:193], v[108:111]
	v_mfma_f32_16x16x32_bf16 v[104:107], v[146:149], v[190:193], v[104:107]
	v_mfma_f32_16x16x32_bf16 v[92:95], v[138:141], v[198:201], v[92:95]
	v_mfma_f32_16x16x32_bf16 v[88:91], v[146:149], v[198:201], v[88:91]
	v_mfma_f32_16x16x32_bf16 v[76:79], v[138:141], v[206:209], v[76:79]
	v_mfma_f32_16x16x32_bf16 v[72:75], v[146:149], v[206:209], v[72:75]
	v_mfma_f32_16x16x32_bf16 v[116:119], v[150:153], v[178:181], v[116:119]
	v_mfma_f32_16x16x32_bf16 v[112:115], v[170:173], v[178:181], v[112:115]
	v_mfma_f32_16x16x32_bf16 v[100:103], v[150:153], v[186:189], v[100:103]
	v_mfma_f32_16x16x32_bf16 v[96:99], v[170:173], v[186:189], v[96:99]
	v_mfma_f32_16x16x32_bf16 v[84:87], v[150:153], v[194:197], v[84:87]
	v_mfma_f32_16x16x32_bf16 v[80:83], v[170:173], v[194:197], v[80:83]
	v_mfma_f32_16x16x32_bf16 v[68:71], v[150:153], v[202:205], v[68:71]
	v_mfma_f32_16x16x32_bf16 v[64:67], v[170:173], v[202:205], v[64:67]
	v_mfma_f32_16x16x32_bf16 v[116:119], v[166:169], v[182:185], v[116:119]
	v_mfma_f32_16x16x32_bf16 v[112:115], v[174:177], v[182:185], v[112:115]
	v_mfma_f32_16x16x32_bf16 v[100:103], v[166:169], v[190:193], v[100:103]
	v_mfma_f32_16x16x32_bf16 v[96:99], v[174:177], v[190:193], v[96:99]
	v_mfma_f32_16x16x32_bf16 v[84:87], v[166:169], v[198:201], v[84:87]
	v_mfma_f32_16x16x32_bf16 v[80:83], v[174:177], v[198:201], v[80:83]
	v_mfma_f32_16x16x32_bf16 v[68:71], v[166:169], v[206:209], v[68:71]
	v_mfma_f32_16x16x32_bf16 v[64:67], v[174:177], v[206:209], v[64:67]
	s_barrier
	s_add_i32 s2, s37, s46
	v_lshl_add_u64 v[154:155], v[154:155], 0, s[64:65]
	s_mov_b32 m0, s2
	ds_read_b128 v[178:181], v241 offset:49152
	ds_read_b128 v[182:185], v241 offset:50176
	ds_read_b128 v[186:189], v241 offset:51200
	ds_read_b128 v[190:193], v241 offset:52224
	ds_read_b128 v[194:197], v241 offset:53248
	ds_read_b128 v[198:201], v241 offset:54272
	ds_read_b128 v[202:205], v241 offset:55296
	ds_read_b128 v[206:209], v241 offset:56320
	global_load_lds_dwordx4 v[154:155], off
	v_lshl_add_u64 v[154:155], v[162:163], 0, s[64:65]
	s_add_i32 m0, s2, 0x2000
	s_add_i32 s2, vcc_hi, s46
	global_load_lds_dwordx4 v[154:155], off
	v_lshl_add_u64 v[154:155], v[210:211], 0, s[64:65]
	s_mov_b32 m0, s2
	s_nop 0
	global_load_lds_dwordx4 v[154:155], off
	v_lshl_add_u64 v[154:155], v[212:213], 0, s[64:65]
	s_add_i32 m0, s2, 0x2000
	s_nop 0
	global_load_lds_dwordx4 v[154:155], off
	v_lshl_add_u64 v[154:155], v[214:215], 0, s[64:65]
	s_mov_b32 m0, s88
	s_nop 0
	global_load_lds_dwordx4 v[154:155], off
	v_lshl_add_u64 v[154:155], v[216:217], 0, s[64:65]
	s_mov_b32 m0, s89
	s_nop 0
	global_load_lds_dwordx4 v[154:155], off
	s_waitcnt vmcnt(8)
	s_waitcnt lgkmcnt(0)
	s_barrier
	s_waitcnt lgkmcnt(0)
	v_mfma_f32_16x16x32_bf16 v[60:63], v[134:137], v[178:181], v[60:63]
	v_mfma_f32_16x16x32_bf16 v[56:59], v[142:145], v[178:181], v[56:59]
	v_mfma_f32_16x16x32_bf16 v[44:47], v[134:137], v[186:189], v[44:47]
	v_mfma_f32_16x16x32_bf16 v[40:43], v[142:145], v[186:189], v[40:43]
	v_mfma_f32_16x16x32_bf16 v[28:31], v[134:137], v[194:197], v[28:31]
	v_mfma_f32_16x16x32_bf16 v[24:27], v[142:145], v[194:197], v[24:27]
	v_mfma_f32_16x16x32_bf16 v[12:15], v[134:137], v[202:205], v[12:15]
	v_mfma_f32_16x16x32_bf16 v[8:11], v[142:145], v[202:205], v[8:11]
	v_mfma_f32_16x16x32_bf16 v[60:63], v[138:141], v[182:185], v[60:63]
	v_mfma_f32_16x16x32_bf16 v[56:59], v[146:149], v[182:185], v[56:59]
	v_mfma_f32_16x16x32_bf16 v[44:47], v[138:141], v[190:193], v[44:47]
	v_mfma_f32_16x16x32_bf16 v[40:43], v[146:149], v[190:193], v[40:43]
	v_mfma_f32_16x16x32_bf16 v[28:31], v[138:141], v[198:201], v[28:31]
	v_mfma_f32_16x16x32_bf16 v[24:27], v[146:149], v[198:201], v[24:27]
	v_mfma_f32_16x16x32_bf16 v[12:15], v[138:141], v[206:209], v[12:15]
	v_mfma_f32_16x16x32_bf16 v[8:11], v[146:149], v[206:209], v[8:11]
	v_mfma_f32_16x16x32_bf16 v[52:55], v[150:153], v[178:181], v[52:55]
	v_mfma_f32_16x16x32_bf16 v[48:51], v[170:173], v[178:181], v[48:51]
	v_mfma_f32_16x16x32_bf16 v[36:39], v[150:153], v[186:189], v[36:39]
	v_mfma_f32_16x16x32_bf16 v[32:35], v[170:173], v[186:189], v[32:35]
	v_mfma_f32_16x16x32_bf16 v[20:23], v[150:153], v[194:197], v[20:23]
	v_mfma_f32_16x16x32_bf16 v[16:19], v[170:173], v[194:197], v[16:19]
	v_mfma_f32_16x16x32_bf16 v[4:7], v[150:153], v[202:205], v[4:7]
	v_mfma_f32_16x16x32_bf16 v[0:3], v[170:173], v[202:205], v[0:3]
	v_mfma_f32_16x16x32_bf16 v[52:55], v[166:169], v[182:185], v[52:55]
	v_mfma_f32_16x16x32_bf16 v[48:51], v[174:177], v[182:185], v[48:51]
	v_mfma_f32_16x16x32_bf16 v[36:39], v[166:169], v[190:193], v[36:39]
	v_mfma_f32_16x16x32_bf16 v[32:35], v[174:177], v[190:193], v[32:35]
	v_mfma_f32_16x16x32_bf16 v[20:23], v[166:169], v[198:201], v[20:23]
	v_mfma_f32_16x16x32_bf16 v[16:19], v[174:177], v[198:201], v[16:19]
	v_mfma_f32_16x16x32_bf16 v[4:7], v[166:169], v[206:209], v[4:7]
	v_mfma_f32_16x16x32_bf16 v[0:3], v[174:177], v[206:209], v[0:3]
	s_barrier
	s_add_u32 s0, s0, 0x100
	s_addc_u32 s1, s1, 0
	s_add_u32 s63, s63, 0x100
	s_addc_u32 vcc_lo, vcc_lo, 0
	s_cmp_ge_i32 s36, s67
	s_mov_b32 s22, s36
	s_cbranch_scc0 .LBB0_820
	s_branch .Lpeel_exit_g2

; #define PG8_BAR __builtin_amdgcn_s_barrier()
; template <class Epi, class Sched, bool ALIGN_EPI = false, bool SP2 = false>
; __device__ __forceinline__ void gemm_phase(PG8_LAS unsigned char* lds, const Gemm g, const Sched& S, const Epi& E, int tid_in) {
;     ...
;         if constexpr (ALIGN_EPI) { if (wr == 0) PG8_BAR; }
;         if constexpr (!Epi::AFTER_DRAIN) { E(acc, cur, wr, wc, fr, fq); S.done(cur); }
.Lpeel_exit_g2:
.LBB0_821:
	s_and_b64 vcc, exec, s[44:45]
	s_cbranch_vccz .LBB0_823
	s_barrier

; #define PG8_STAGE(bufoff, gbase, voff) do { _Pragma("unroll") for (int _i = 0; _i < 2; ++_i) \
;         __builtin_amdgcn_global_load_lds((const unsigned*)((const char*)(gbase) + (voff)[_i]), (PG8_LAS unsigned*)(lds + (bufoff) + ldsw + _i * 8192), 16, 0, 0); } while (0)
; #define PG8_WAIT_V(n) asm volatile("s_waitcnt vmcnt(" #n ")" ::: "memory")
; #define PG8_BAR __builtin_amdgcn_s_barrier()
; template <class Epi, class Sched, bool ALIGN_EPI = false, bool SP2 = false>
; __device__ __forceinline__ void gemm_phase(PG8_LAS unsigned char* lds, const Gemm g, const Sched& S, const Epi& E, int tid_in) {
;     ...
;     const int tid = tid_, wid = __builtin_amdgcn_readfirstlane(tid >> 6), lane = tid & 63, wr = wid >> 2, wc = wid & 3, fr = lane & 15, fq = lane >> 4;
;     int K_ = g.K; asm volatile("" : "+s"(K_));
;     const int K = K_, nt = K / BK;
;     unsigned voffA[2], voffB[2];
; #pragma unroll
;     for (int i = 0; i < 2; ++i) { int R, C; stage_rc(tid * 16 + i * 8192, R, C); const int Rb = Epi::PERM ? ((R & ~31) + perm32(R & 31)) : R;
;         voffA[i] = (unsigned)(R * K + C) * 2u; voffB[i] = (unsigned)(Rb * K + C) * 2u; }
;     const size_t kstep = (size_t)(BK * 2);
;     const size_t hstep = (size_t)HALF * K * 2;
;     const size_t tstep = 2 * hstep;
;     const unsigned ldsw = (unsigned)wid * 1024u;
;     const int aoff = lds_byte(wr * 64 + fr, fq * 8), boff = lds_byte(wc * 32 + fr, fq * 8);
;     ...
;         PG8_STAGE(PG8_SB(1, 0), cB + kstep, voffB); PG8_STAGE(PG8_SA(1, 0), cA + kstep, voffA); PG8_STAGE(PG8_SB(1, 1), cB + hstep + kstep, voffB);
;         PG8_WAIT_V(6); PG8_BAR;
.LBB0_917:
	s_add_u32 s16, s4, 0x14000000
	s_addc_u32 s17, s5, 0
	s_add_i32 m0, s43, 0x18000
	v_lshl_add_u64 v[0:1], v[0:1], 0, s[64:65]
	s_waitcnt vmcnt(2)
	s_mov_b32 s100, -1
	s_barrier
	global_load_lds_dwordx4 v[0:1], off
	v_lshl_add_u64 v[0:1], v[2:3], 0, s[64:65]
	s_add_i32 m0, s43, 0x1a000
	s_add_i32 s56, s43, 0x8000
	global_load_lds_dwordx4 v[0:1], off
	v_lshl_add_u64 v[0:1], v[8:9], 0, s[64:65]
	s_mov_b32 m0, s56
	s_add_i32 s57, s43, 0xa000
	global_load_lds_dwordx4 v[0:1], off
	v_lshl_add_u64 v[0:1], v[10:11], 0, s[64:65]
	s_mov_b32 m0, s57
	v_and_b32_e32 v145, 15, v12
	global_load_lds_dwordx4 v[0:1], off
	s_add_i32 m0, s43, 0x1c000
	v_lshl_add_u64 v[0:1], v[4:5], 0, s[64:65]
	global_load_lds_dwordx4 v[0:1], off
	v_lshl_add_u64 v[0:1], v[6:7], 0, s[64:65]
	s_add_i32 m0, s43, 0x1e000
	v_bfe_u32 v19, v12, 4, 2
	global_load_lds_dwordx4 v[0:1], off
	s_lshr_b32 s2, s7, 26
	s_add_i32 s2, s6, s2
	v_lshlrev_b32_e32 v20, 4, v19
	v_lshlrev_b32_e32 v149, 2, v145
	s_ashr_i32 s52, s2, 6
	v_lshl_or_b32 v20, v145, 6, v20
	s_lshl_b32 s2, s36, 13
	v_and_b32_e32 v21, 32, v149
	v_and_b32_e32 v0, 63, v12
	v_bitop3_b32 v22, v20, s2, v21 bitop3:0xde
	s_lshl_b32 s2, s35, 5
	v_lshlrev_b32_e32 v0, 2, v0
	v_mov_b32_e32 v1, v157
	s_and_b32 s2, s2, 0x60
	v_lshl_add_u64 v[0:1], s[4:5], 0, v[0:1]
	s_mov_b64 s[4:5], 0x30000000
	s_waitcnt lgkmcnt(0)
	s_ashr_i32 s47, s41, 31
	s_lshl_b32 s53, s36, 6
	s_lshl_b32 s3, s2, 7
	v_lshl_add_u64 v[134:135], v[0:1], 0, s[4:5]
	v_add_u32_e32 v0, v18, v16
	s_cmp_gt_i32 s6, 63
	v_add_lshl_u32 v0, v0, v17, 1
	v_mov_b32_e32 v1, v157
	s_waitcnt vmcnt(6)
	s_cselect_b64 s[38:39], -1, 0
	s_add_i32 s60, s52, -2
	v_lshl_add_u64 v[136:137], s[10:11], 0, v[0:1]
	v_add_u32_e32 v0, v15, v13
	s_cmpk_lt_u32 s34, 0x100
	v_add_lshl_u32 v0, v0, v14, 1
	v_bitop3_b32 v151, v20, s3, v21 bitop3:0xde
	s_cselect_b64 s[54:55], -1, 0
	v_or_b32_e32 v153, 64, v149
	v_or_b32_e32 v155, 0x80, v149
	v_or_b32_e32 v161, 0xc0, v149
	v_lshl_or_b32 v166, v19, 3, s2
	v_lshl_add_u64 v[138:139], s[10:11], 0, v[0:1]
	s_mov_b32 s88, 0
	v_add_u32_e32 v167, 0, v22
	v_readlane_b32 s34, v254, 35
	v_readlane_b32 s35, v254, 36
	s_barrier
	s_branch .LBB0_920

; #define PG8_STAGE(bufoff, gbase, voff) do { _Pragma("unroll") for (int _i = 0; _i < 2; ++_i) \
;         __builtin_amdgcn_global_load_lds((const unsigned*)((const char*)(gbase) + (voff)[_i]), (PG8_LAS unsigned*)(lds + (bufoff) + ldsw + _i * 8192), 16, 0, 0); } while (0)
; #define PG8_LDA(dst, b, h) do { _Pragma("unroll") for (int m = 0; m < 4; ++m) _Pragma("unroll") for (int k = 0; k < 2; ++k) dst[m][k] = *(const PG8_LAS bf16x8*)(lds + PG8_SA(b, h) + aoff + m * 2048 + k * 1024); } while (0)
; #define PG8_LDB(dst, b, h) do { _Pragma("unroll") for (int n = 0; n < 2; ++n) _Pragma("unroll") for (int k = 0; k < 2; ++k) dst[n][k] = *(const PG8_LAS bf16x8*)(lds + PG8_SB(b, h) + boff + n * 2048 + k * 1024); } while (0)
; #define PG8_MMA(ai, bj, At, Bt) do { __builtin_amdgcn_s_setprio(1); _Pragma("unroll") for (int m = 0; m < 4; ++m) _Pragma("unroll") for (int n = 0; n < 2; ++n) _Pragma("unroll") for (int k = 0; k < 2; ++k) \
;         acc[ai][bj][m][n] = __builtin_amdgcn_mfma_f32_16x16x32_bf16(Bt[n][k], At[m][k], acc[ai][bj][m][n], 0, 0, 0); __builtin_amdgcn_s_setprio(0); } while (0)
; #define PG8_WAIT_V(n) asm volatile("s_waitcnt vmcnt(" #n ")" ::: "memory")
; #define PG8_WAIT_L(n) asm volatile("s_waitcnt lgkmcnt(" #n ")" ::: "memory")
; template <class Epi, class Sched, bool ALIGN_EPI = false, bool SP2 = false>
; __device__ __forceinline__ void gemm_phase(PG8_LAS unsigned char* lds, const Gemm g, const Sched& S, const Epi& E, int tid_in) {
;     ...
;             const bool last = (t == nt - 2);
;             const char* a1 = cA + (size_t)(t + 1) * kstep;
;             const char* a2 = last ? nA : cA + (size_t)(t + 2) * kstep; const char* b2 = last ? nB : cB + (size_t)(t + 2) * kstep;
;             const char* a3 = a2 + kstep; const char* b3 = b2 + kstep;
;             if (last && has_next) S.a_ready(nxt);
;             if constexpr (SP2) {
;             PG8_LDB(B0, 0, 0); PG8_LDB(B1, 0, 1); PG8_SCHED; PG8_LDA(At, 0, 0); PG8_STAGE(PG8_SA(1, 1), a1 + hstep, voffA);
;             PG8_WAIT_V(8); PG8_WAIT_L(0); PG8_BAR; PG8_MMA(0, 0, At, B0); PG8_MMA(0, 1, At, B1); PG8_BAR; PG8_SCHED;
;     ...
;         for (int a = 0; a < 2; ++a)
; #pragma unroll
;             for (int b = 0; b < 2; ++b)
; #pragma unroll
;                 for (int m = 0; m < 4; ++m)
; #pragma unroll
;                     for (int n = 0; n < 2; ++n) acc[a][b][m][n] = (f32x4){0.f, 0.f, 0.f, 0.f};
.LBB0_926:
	s_andn2_b64 vcc, exec, s[38:39]
	s_cbranch_vccz .Lpeel_enter_g3
	v_mov_b32_e32 v127, 0
	v_mov_b32_e32 v126, v127
	v_mov_b32_e32 v125, v127
	v_mov_b32_e32 v124, v127
	v_mov_b32_e32 v123, v127
	v_mov_b32_e32 v122, v127
	v_mov_b32_e32 v121, v127
	v_mov_b32_e32 v120, v127
	v_mov_b32_e32 v111, v127
	v_mov_b32_e32 v110, v127
	v_mov_b32_e32 v109, v127
	v_mov_b32_e32 v108, v127
	v_mov_b32_e32 v107, v127
	v_mov_b32_e32 v106, v127
	v_mov_b32_e32 v105, v127
	v_mov_b32_e32 v104, v127
	v_mov_b32_e32 v95, v127
	v_mov_b32_e32 v94, v127
	v_mov_b32_e32 v93, v127
	v_mov_b32_e32 v92, v127
	v_mov_b32_e32 v91, v127
	v_mov_b32_e32 v90, v127
	v_mov_b32_e32 v89, v127
	v_mov_b32_e32 v88, v127
	v_mov_b32_e32 v79, v127
	v_mov_b32_e32 v78, v127
	v_mov_b32_e32 v77, v127
	v_mov_b32_e32 v76, v127
	v_mov_b32_e32 v75, v127
	v_mov_b32_e32 v74, v127
	v_mov_b32_e32 v73, v127
	v_mov_b32_e32 v72, v127
	v_mov_b32_e32 v119, v127
	v_mov_b32_e32 v118, v127
	v_mov_b32_e32 v117, v127
	v_mov_b32_e32 v116, v127
	v_mov_b32_e32 v115, v127
	v_mov_b32_e32 v114, v127
	v_mov_b32_e32 v113, v127
	v_mov_b32_e32 v112, v127
	v_mov_b32_e32 v103, v127
	v_mov_b32_e32 v102, v127
	v_mov_b32_e32 v101, v127
	v_mov_b32_e32 v100, v127
	v_mov_b32_e32 v99, v127
	v_mov_b32_e32 v98, v127
	v_mov_b32_e32 v97, v127
	v_mov_b32_e32 v96, v127
	v_mov_b32_e32 v87, v127
	v_mov_b32_e32 v86, v127
	v_mov_b32_e32 v85, v127
	v_mov_b32_e32 v84, v127
	v_mov_b32_e32 v83, v127
	v_mov_b32_e32 v82, v127
	v_mov_b32_e32 v81, v127
	v_mov_b32_e32 v80, v127
	v_mov_b32_e32 v71, v127
	v_mov_b32_e32 v70, v127
	v_mov_b32_e32 v69, v127
	v_mov_b32_e32 v68, v127
	v_mov_b32_e32 v67, v127
	v_mov_b32_e32 v66, v127
	v_mov_b32_e32 v65, v127
	v_mov_b32_e32 v64, v127
	v_mov_b32_e32 v63, v127
	v_mov_b32_e32 v62, v127
	v_mov_b32_e32 v61, v127
	v_mov_b32_e32 v60, v127
	v_mov_b32_e32 v59, v127
	v_mov_b32_e32 v58, v127
	v_mov_b32_e32 v57, v127
	v_mov_b32_e32 v56, v127
	v_mov_b32_e32 v47, v127
	v_mov_b32_e32 v46, v127
	v_mov_b32_e32 v45, v127
	v_mov_b32_e32 v44, v127
	v_mov_b32_e32 v43, v127
	v_mov_b32_e32 v42, v127
	v_mov_b32_e32 v41, v127
	v_mov_b32_e32 v40, v127
	v_mov_b32_e32 v31, v127
	v_mov_b32_e32 v30, v127
	v_mov_b32_e32 v29, v127
	v_mov_b32_e32 v28, v127
	v_mov_b32_e32 v27, v127
	v_mov_b32_e32 v26, v127
	v_mov_b32_e32 v25, v127
	v_mov_b32_e32 v24, v127
	v_mov_b32_e32 v15, v127
	v_mov_b32_e32 v14, v127
	v_mov_b32_e32 v13, v127
	v_mov_b32_e32 v12, v127
	v_mov_b32_e32 v11, v127
	v_mov_b32_e32 v10, v127
	v_mov_b32_e32 v9, v127
	v_mov_b32_e32 v8, v127
	v_mov_b32_e32 v55, v127
	v_mov_b32_e32 v54, v127
	v_mov_b32_e32 v53, v127
	v_mov_b32_e32 v52, v127
	v_mov_b32_e32 v51, v127
	v_mov_b32_e32 v50, v127
	v_mov_b32_e32 v49, v127
	v_mov_b32_e32 v48, v127
	v_mov_b32_e32 v39, v127
	v_mov_b32_e32 v38, v127
	v_mov_b32_e32 v37, v127
	v_mov_b32_e32 v36, v127
	v_mov_b32_e32 v35, v127
	v_mov_b32_e32 v34, v127
	v_mov_b32_e32 v33, v127
	v_mov_b32_e32 v32, v127
	v_mov_b32_e32 v23, v127
	v_mov_b32_e32 v22, v127
	v_mov_b32_e32 v21, v127
	v_mov_b32_e32 v20, v127
	v_mov_b32_e32 v19, v127
	v_mov_b32_e32 v18, v127
	v_mov_b32_e32 v17, v127
	v_mov_b32_e32 v16, v127
	v_mov_b32_e32 v7, v127
	v_mov_b32_e32 v6, v127
	v_mov_b32_e32 v5, v127
	v_mov_b32_e32 v4, v127
	v_mov_b32_e32 v3, v127
	v_mov_b32_e32 v2, v127
	v_mov_b32_e32 v1, v127
	v_mov_b32_e32 v0, v127
	s_branch .LBB0_929
.Lpeel_enter_g3:
	s_add_u32 s0, s0, 0x80
	s_addc_u32 s1, s1, 0
	s_add_u32 s22, s22, 0x100
	s_addc_u32 s23, s23, 0
	s_mov_b32 s6, 0
	s_add_i32 s36, s6, 2
	s_add_u32 s2, s0, 0x80
	s_addc_u32 s3, s1, 0
	s_add_i32 s37, 0, 0x10000
	s_cmp_eq_u32 s60, s6
	s_cselect_b32 s7, s63, s3
	s_cselect_b32 s6, s62, s2
	v_add_u32_e32 v144, s37, v151
	s_cselect_b32 s3, s67, s23
	s_cselect_b32 s2, s66, s22
	s_add_i32 s91, 0, 0x14000
	ds_read_b128 v[140:143], v144
	ds_read_b128 v[168:171], v144 offset:1024
	ds_read_b128 v[172:175], v144 offset:2048
	ds_read_b128 v[176:179], v144 offset:3072
	v_add_u32_e32 v144, s91, v151
	ds_read_b128 v[180:183], v144
	ds_read_b128 v[184:187], v144 offset:1024
	ds_read_b128 v[188:191], v144 offset:2048
	ds_read_b128 v[192:195], v144 offset:3072
	v_lshl_add_u64 v[146:147], s[0:1], 0, v[136:137]
	s_add_i32 m0, s43, 0xc000
	ds_read_b128 v[196:199], v167
	ds_read_b128 v[200:203], v167 offset:1024
	ds_read_b128 v[204:207], v167 offset:2048
	ds_read_b128 v[208:211], v167 offset:3072
	ds_read_b128 v[212:215], v167 offset:4096
	ds_read_b128 v[216:219], v167 offset:5120
	ds_read_b128 v[220:223], v167 offset:6144
	ds_read_b128 v[224:227], v167 offset:7168
	global_load_lds_dwordx4 v[146:147], off
	v_lshl_add_u64 v[146:147], s[0:1], 0, v[138:139]
	s_add_i32 m0, s43, 0xe000
	s_nop 0
	global_load_lds_dwordx4 v[146:147], off
	s_waitcnt vmcnt(8)
	s_waitcnt lgkmcnt(0)
	s_barrier
; #define PG8_STAGE(bufoff, gbase, voff) do { _Pragma("unroll") for (int _i = 0; _i < 2; ++_i) \
;         __builtin_amdgcn_global_load_lds((const unsigned*)((const char*)(gbase) + (voff)[_i]), (PG8_LAS unsigned*)(lds + (bufoff) + ldsw + _i * 8192), 16, 0, 0); } while (0)
; #define PG8_LDA(dst, b, h) do { _Pragma("unroll") for (int m = 0; m < 4; ++m) _Pragma("unroll") for (int k = 0; k < 2; ++k) dst[m][k] = *(const PG8_LAS bf16x8*)(lds + PG8_SA(b, h) + aoff + m * 2048 + k * 1024); } while (0)
; #define PG8_MMA(ai, bj, At, Bt) do { __builtin_amdgcn_s_setprio(1); _Pragma("unroll") for (int m = 0; m < 4; ++m) _Pragma("unroll") for (int n = 0; n < 2; ++n) _Pragma("unroll") for (int k = 0; k < 2; ++k) \
;         acc[ai][bj][m][n] = __builtin_amdgcn_mfma_f32_16x16x32_bf16(Bt[n][k], At[m][k], acc[ai][bj][m][n], 0, 0, 0); __builtin_amdgcn_s_setprio(0); } while (0)
; #define PG8_WAIT_V(n) asm volatile("s_waitcnt vmcnt(" #n ")" ::: "memory")
; #define PG8_WAIT_L(n) asm volatile("s_waitcnt lgkmcnt(" #n ")" ::: "memory")
; #define PG8_BAR __builtin_amdgcn_s_barrier()
; #define PG8_SCHED __builtin_amdgcn_sched_barrier(0)
; template <class Epi, class Sched, bool ALIGN_EPI = false, bool SP2 = false>
; __device__ __forceinline__ void gemm_phase(PG8_LAS unsigned char* lds, const Gemm g, const Sched& S, const Epi& E, int tid_in) {
;     ...
;             PG8_WAIT_V(8); PG8_WAIT_L(0); PG8_BAR; PG8_MMA(0, 0, At, B0); PG8_MMA(0, 1, At, B1); PG8_BAR; PG8_SCHED;
;             PG8_LDA(At, 0, 1); PG8_STAGE(PG8_SB(0, 0), b2, voffB); PG8_STAGE(PG8_SB(0, 1), b2 + hstep, voffB); PG8_STAGE(PG8_SA(0, 0), a2, voffA);
;             PG8_WAIT_V(8); PG8_WAIT_L(0); PG8_BAR; PG8_MMA(1, 0, At, B0); PG8_MMA(1, 1, At, B1); PG8_BAR; PG8_SCHED;
	s_waitcnt lgkmcnt(0)
	v_mfma_f32_16x16x32_bf16 v[124:127], v[140:143], v[196:199], 0
	v_mfma_f32_16x16x32_bf16 v[120:123], v[172:175], v[196:199], 0
	v_mfma_f32_16x16x32_bf16 v[108:111], v[140:143], v[204:207], 0
	v_mfma_f32_16x16x32_bf16 v[104:107], v[172:175], v[204:207], 0
	v_mfma_f32_16x16x32_bf16 v[92:95], v[140:143], v[212:215], 0
	v_mfma_f32_16x16x32_bf16 v[88:91], v[172:175], v[212:215], 0
	v_mfma_f32_16x16x32_bf16 v[76:79], v[140:143], v[220:223], 0
	v_mfma_f32_16x16x32_bf16 v[72:75], v[172:175], v[220:223], 0
	v_mfma_f32_16x16x32_bf16 v[124:127], v[168:171], v[200:203], v[124:127]
	v_mfma_f32_16x16x32_bf16 v[120:123], v[176:179], v[200:203], v[120:123]
	v_mfma_f32_16x16x32_bf16 v[108:111], v[168:171], v[208:211], v[108:111]
	v_mfma_f32_16x16x32_bf16 v[104:107], v[176:179], v[208:211], v[104:107]
	v_mfma_f32_16x16x32_bf16 v[92:95], v[168:171], v[216:219], v[92:95]
	v_mfma_f32_16x16x32_bf16 v[88:91], v[176:179], v[216:219], v[88:91]
	v_mfma_f32_16x16x32_bf16 v[76:79], v[168:171], v[224:227], v[76:79]
	v_mfma_f32_16x16x32_bf16 v[72:75], v[176:179], v[224:227], v[72:75]
	v_mfma_f32_16x16x32_bf16 v[116:119], v[180:183], v[196:199], 0
	v_mfma_f32_16x16x32_bf16 v[112:115], v[188:191], v[196:199], 0
	v_mfma_f32_16x16x32_bf16 v[100:103], v[180:183], v[204:207], 0
	v_mfma_f32_16x16x32_bf16 v[96:99], v[188:191], v[204:207], 0
	v_mfma_f32_16x16x32_bf16 v[84:87], v[180:183], v[212:215], 0
	v_mfma_f32_16x16x32_bf16 v[80:83], v[188:191], v[212:215], 0
	v_mfma_f32_16x16x32_bf16 v[68:71], v[180:183], v[220:223], 0
	v_mfma_f32_16x16x32_bf16 v[64:67], v[188:191], v[220:223], 0
	v_mfma_f32_16x16x32_bf16 v[116:119], v[184:187], v[200:203], v[116:119]
	v_mfma_f32_16x16x32_bf16 v[112:115], v[192:195], v[200:203], v[112:115]
	v_mfma_f32_16x16x32_bf16 v[100:103], v[184:187], v[208:211], v[100:103]
	v_mfma_f32_16x16x32_bf16 v[96:99], v[192:195], v[208:211], v[96:99]
	v_mfma_f32_16x16x32_bf16 v[84:87], v[184:187], v[216:219], v[84:87]
	v_mfma_f32_16x16x32_bf16 v[80:83], v[192:195], v[216:219], v[80:83]
	v_mfma_f32_16x16x32_bf16 v[68:71], v[184:187], v[224:227], v[68:71]
	v_mfma_f32_16x16x32_bf16 v[64:67], v[192:195], v[224:227], v[64:67]
	s_barrier
	s_add_i32 s37, s37, s42
	v_lshl_add_u64 v[146:147], s[2:3], 0, v[156:157]
	s_mov_b32 m0, s37
	ds_read_b128 v[196:199], v167 offset:16384
	ds_read_b128 v[200:203], v167 offset:17408
	ds_read_b128 v[204:207], v167 offset:18432
	ds_read_b128 v[208:211], v167 offset:19456
	ds_read_b128 v[212:215], v167 offset:20480
	ds_read_b128 v[216:219], v167 offset:21504
	ds_read_b128 v[220:223], v167 offset:22528
	ds_read_b128 v[224:227], v167 offset:23552
	global_load_lds_dwordx4 v[146:147], off
	s_add_i32 m0, s37, 0x2000
	v_lshl_add_u64 v[162:163], s[2:3], 0, v[128:129]
	s_add_u32 s2, s2, s10
	s_addc_u32 s3, s3, s11
	s_add_i32 s37, s91, s42
	global_load_lds_dwordx4 v[162:163], off
	v_lshl_add_u64 v[228:229], s[2:3], 0, v[156:157]
	s_mov_b32 m0, s37
	v_lshl_add_u64 v[230:231], s[2:3], 0, v[128:129]
	global_load_lds_dwordx4 v[228:229], off
	s_add_i32 m0, s37, 0x2000
	v_lshl_add_u64 v[238:239], s[6:7], 0, v[132:133]
	global_load_lds_dwordx4 v[230:231], off
	s_mov_b32 m0, s43
	v_lshl_add_u64 v[240:241], s[6:7], 0, v[130:131]
	global_load_lds_dwordx4 v[238:239], off
	s_mov_b32 m0, s44
	s_nop 0
	global_load_lds_dwordx4 v[240:241], off
	s_waitcnt vmcnt(8)
	s_waitcnt lgkmcnt(0)
	s_barrier
	s_waitcnt lgkmcnt(0)
	v_mfma_f32_16x16x32_bf16 v[60:63], v[140:143], v[196:199], 0
	v_mfma_f32_16x16x32_bf16 v[56:59], v[172:175], v[196:199], 0
	v_mfma_f32_16x16x32_bf16 v[44:47], v[140:143], v[204:207], 0
	v_mfma_f32_16x16x32_bf16 v[40:43], v[172:175], v[204:207], 0
	v_mfma_f32_16x16x32_bf16 v[28:31], v[140:143], v[212:215], 0
	v_mfma_f32_16x16x32_bf16 v[24:27], v[172:175], v[212:215], 0
	v_mfma_f32_16x16x32_bf16 v[12:15], v[140:143], v[220:223], 0
	v_mfma_f32_16x16x32_bf16 v[8:11], v[172:175], v[220:223], 0
	v_mfma_f32_16x16x32_bf16 v[60:63], v[168:171], v[200:203], v[60:63]
	v_mfma_f32_16x16x32_bf16 v[56:59], v[176:179], v[200:203], v[56:59]
	v_mfma_f32_16x16x32_bf16 v[44:47], v[168:171], v[208:211], v[44:47]
	v_mfma_f32_16x16x32_bf16 v[40:43], v[176:179], v[208:211], v[40:43]
	v_mfma_f32_16x16x32_bf16 v[28:31], v[168:171], v[216:219], v[28:31]
	v_mfma_f32_16x16x32_bf16 v[24:27], v[176:179], v[216:219], v[24:27]
	v_mfma_f32_16x16x32_bf16 v[12:15], v[168:171], v[224:227], v[12:15]
	v_mfma_f32_16x16x32_bf16 v[8:11], v[176:179], v[224:227], v[8:11]
	v_mfma_f32_16x16x32_bf16 v[52:55], v[180:183], v[196:199], 0
	v_mfma_f32_16x16x32_bf16 v[48:51], v[188:191], v[196:199], 0
	v_mfma_f32_16x16x32_bf16 v[36:39], v[180:183], v[204:207], 0
	v_mfma_f32_16x16x32_bf16 v[32:35], v[188:191], v[204:207], 0
	v_mfma_f32_16x16x32_bf16 v[20:23], v[180:183], v[212:215], 0
	v_mfma_f32_16x16x32_bf16 v[16:19], v[188:191], v[212:215], 0
	v_mfma_f32_16x16x32_bf16 v[4:7], v[180:183], v[220:223], 0
	v_mfma_f32_16x16x32_bf16 v[0:3], v[188:191], v[220:223], 0
	v_mfma_f32_16x16x32_bf16 v[52:55], v[184:187], v[200:203], v[52:55]
	v_mfma_f32_16x16x32_bf16 v[48:51], v[192:195], v[200:203], v[48:51]
	v_mfma_f32_16x16x32_bf16 v[36:39], v[184:187], v[208:211], v[36:39]
	v_mfma_f32_16x16x32_bf16 v[32:35], v[192:195], v[208:211], v[32:35]
	v_mfma_f32_16x16x32_bf16 v[20:23], v[184:187], v[216:219], v[20:23]
	v_mfma_f32_16x16x32_bf16 v[16:19], v[192:195], v[216:219], v[16:19]
	v_mfma_f32_16x16x32_bf16 v[4:7], v[184:187], v[224:227], v[4:7]
	v_mfma_f32_16x16x32_bf16 v[0:3], v[192:195], v[224:227], v[0:3]
	s_barrier
; #define PG8_STAGE(bufoff, gbase, voff) do { _Pragma("unroll") for (int _i = 0; _i < 2; ++_i) \
;         __builtin_amdgcn_global_load_lds((const unsigned*)((const char*)(gbase) + (voff)[_i]), (PG8_LAS unsigned*)(lds + (bufoff) + ldsw + _i * 8192), 16, 0, 0); } while (0)
; #define PG8_LDA(dst, b, h) do { _Pragma("unroll") for (int m = 0; m < 4; ++m) _Pragma("unroll") for (int k = 0; k < 2; ++k) dst[m][k] = *(const PG8_LAS bf16x8*)(lds + PG8_SA(b, h) + aoff + m * 2048 + k * 1024); } while (0)
; #define PG8_LDB(dst, b, h) do { _Pragma("unroll") for (int n = 0; n < 2; ++n) _Pragma("unroll") for (int k = 0; k < 2; ++k) dst[n][k] = *(const PG8_LAS bf16x8*)(lds + PG8_SB(b, h) + boff + n * 2048 + k * 1024); } while (0)
; #define PG8_MMA(ai, bj, At, Bt) do { __builtin_amdgcn_s_setprio(1); _Pragma("unroll") for (int m = 0; m < 4; ++m) _Pragma("unroll") for (int n = 0; n < 2; ++n) _Pragma("unroll") for (int k = 0; k < 2; ++k) \
;         acc[ai][bj][m][n] = __builtin_amdgcn_mfma_f32_16x16x32_bf16(Bt[n][k], At[m][k], acc[ai][bj][m][n], 0, 0, 0); __builtin_amdgcn_s_setprio(0); } while (0)
; #define PG8_WAIT_V(n) asm volatile("s_waitcnt vmcnt(" #n ")" ::: "memory")
; #define PG8_WAIT_L(n) asm volatile("s_waitcnt lgkmcnt(" #n ")" ::: "memory")
; #define PG8_BAR __builtin_amdgcn_s_barrier()
; #define PG8_SCHED __builtin_amdgcn_sched_barrier(0)
; template <class Epi, class Sched, bool ALIGN_EPI = false, bool SP2 = false>
; __device__ __forceinline__ void gemm_phase(PG8_LAS unsigned char* lds, const Gemm g, const Sched& S, const Epi& E, int tid_in) {
;     ...
;             PG8_LDB(B0, 1, 0); PG8_LDB(B1, 1, 1); PG8_SCHED; PG8_LDA(At, 1, 0); PG8_STAGE(PG8_SA(0, 1), a2 + hstep, voffA);
;             PG8_WAIT_V(8); PG8_WAIT_L(0); PG8_BAR; PG8_MMA(0, 0, At, B0); PG8_MMA(0, 1, At, B1); PG8_BAR; PG8_SCHED;
;             PG8_LDA(At, 1, 1); PG8_STAGE(PG8_SB(1, 0), b3, voffB); PG8_STAGE(PG8_SB(1, 1), b3 + hstep, voffB); PG8_STAGE(PG8_SA(1, 0), a3, voffA);
;             PG8_WAIT_V(8); PG8_WAIT_L(0); PG8_BAR; PG8_MMA(1, 0, At, B0); PG8_MMA(1, 1, At, B1); PG8_BAR; PG8_SCHED;
	s_add_i32 s37, 0, 0x18000
	v_add_u32_e32 v144, s37, v151
	s_add_i32 s91, 0, 0x1c000
	ds_read_b128 v[140:143], v144
	ds_read_b128 v[168:171], v144 offset:1024
	ds_read_b128 v[172:175], v144 offset:2048
	ds_read_b128 v[176:179], v144 offset:3072
	v_add_u32_e32 v144, s91, v151
	ds_read_b128 v[180:183], v144
	ds_read_b128 v[184:187], v144 offset:1024
	ds_read_b128 v[188:191], v144 offset:2048
	ds_read_b128 v[192:195], v144 offset:3072
	s_add_u32 s2, s6, s10
	s_addc_u32 s3, s7, s11
	s_mov_b32 m0, s45
	v_lshl_add_u64 v[242:243], s[2:3], 0, v[132:133]
	ds_read_b128 v[196:199], v167 offset:32768
	ds_read_b128 v[200:203], v167 offset:33792
	ds_read_b128 v[204:207], v167 offset:34816
	ds_read_b128 v[208:211], v167 offset:35840
	ds_read_b128 v[212:215], v167 offset:36864
	ds_read_b128 v[216:219], v167 offset:37888
	ds_read_b128 v[220:223], v167 offset:38912
	ds_read_b128 v[224:227], v167 offset:39936
	global_load_lds_dwordx4 v[242:243], off
	v_lshl_add_u64 v[242:243], s[2:3], 0, v[130:131]
	s_mov_b32 m0, s46
	s_nop 0
	global_load_lds_dwordx4 v[242:243], off
	s_waitcnt vmcnt(8)
	s_waitcnt lgkmcnt(0)
	s_barrier
	s_waitcnt lgkmcnt(0)
	v_mfma_f32_16x16x32_bf16 v[124:127], v[140:143], v[196:199], v[124:127]
	v_mfma_f32_16x16x32_bf16 v[120:123], v[172:175], v[196:199], v[120:123]
	v_mfma_f32_16x16x32_bf16 v[108:111], v[140:143], v[204:207], v[108:111]
	v_mfma_f32_16x16x32_bf16 v[104:107], v[172:175], v[204:207], v[104:107]
	v_mfma_f32_16x16x32_bf16 v[92:95], v[140:143], v[212:215], v[92:95]
	v_mfma_f32_16x16x32_bf16 v[88:91], v[172:175], v[212:215], v[88:91]
	v_mfma_f32_16x16x32_bf16 v[76:79], v[140:143], v[220:223], v[76:79]
	v_mfma_f32_16x16x32_bf16 v[72:75], v[172:175], v[220:223], v[72:75]
	v_mfma_f32_16x16x32_bf16 v[124:127], v[168:171], v[200:203], v[124:127]
	v_mfma_f32_16x16x32_bf16 v[120:123], v[176:179], v[200:203], v[120:123]
	v_mfma_f32_16x16x32_bf16 v[108:111], v[168:171], v[208:211], v[108:111]
	v_mfma_f32_16x16x32_bf16 v[104:107], v[176:179], v[208:211], v[104:107]
	v_mfma_f32_16x16x32_bf16 v[92:95], v[168:171], v[216:219], v[92:95]
	v_mfma_f32_16x16x32_bf16 v[88:91], v[176:179], v[216:219], v[88:91]
	v_mfma_f32_16x16x32_bf16 v[76:79], v[168:171], v[224:227], v[76:79]
	v_mfma_f32_16x16x32_bf16 v[72:75], v[176:179], v[224:227], v[72:75]
	v_mfma_f32_16x16x32_bf16 v[116:119], v[180:183], v[196:199], v[116:119]
	v_mfma_f32_16x16x32_bf16 v[112:115], v[188:191], v[196:199], v[112:115]
	v_mfma_f32_16x16x32_bf16 v[100:103], v[180:183], v[204:207], v[100:103]
	v_mfma_f32_16x16x32_bf16 v[96:99], v[188:191], v[204:207], v[96:99]
	v_mfma_f32_16x16x32_bf16 v[84:87], v[180:183], v[212:215], v[84:87]
	v_mfma_f32_16x16x32_bf16 v[80:83], v[188:191], v[212:215], v[80:83]
	v_mfma_f32_16x16x32_bf16 v[68:71], v[180:183], v[220:223], v[68:71]
	v_mfma_f32_16x16x32_bf16 v[64:67], v[188:191], v[220:223], v[64:67]
	v_mfma_f32_16x16x32_bf16 v[116:119], v[184:187], v[200:203], v[116:119]
	v_mfma_f32_16x16x32_bf16 v[112:115], v[192:195], v[200:203], v[112:115]
	v_mfma_f32_16x16x32_bf16 v[100:103], v[184:187], v[208:211], v[100:103]
	v_mfma_f32_16x16x32_bf16 v[96:99], v[192:195], v[208:211], v[96:99]
	v_mfma_f32_16x16x32_bf16 v[84:87], v[184:187], v[216:219], v[84:87]
	v_mfma_f32_16x16x32_bf16 v[80:83], v[192:195], v[216:219], v[80:83]
	v_mfma_f32_16x16x32_bf16 v[68:71], v[184:187], v[224:227], v[68:71]
	v_mfma_f32_16x16x32_bf16 v[64:67], v[192:195], v[224:227], v[64:67]
	s_barrier
	s_add_i32 s2, s37, s42
	v_lshl_add_u64 v[146:147], v[146:147], 0, s[64:65]
	s_mov_b32 m0, s2
	ds_read_b128 v[196:199], v167 offset:49152
	ds_read_b128 v[200:203], v167 offset:50176
	ds_read_b128 v[204:207], v167 offset:51200
	ds_read_b128 v[208:211], v167 offset:52224
	ds_read_b128 v[212:215], v167 offset:53248
	ds_read_b128 v[216:219], v167 offset:54272
	ds_read_b128 v[220:223], v167 offset:55296
	ds_read_b128 v[224:227], v167 offset:56320
	global_load_lds_dwordx4 v[146:147], off
	v_lshl_add_u64 v[146:147], v[162:163], 0, s[64:65]
	s_add_i32 m0, s2, 0x2000
	s_add_i32 s2, s91, s42
	global_load_lds_dwordx4 v[146:147], off
	v_lshl_add_u64 v[146:147], v[228:229], 0, s[64:65]
	s_mov_b32 m0, s2
	s_nop 0
	global_load_lds_dwordx4 v[146:147], off
	v_lshl_add_u64 v[146:147], v[230:231], 0, s[64:65]
	s_add_i32 m0, s2, 0x2000
	s_nop 0
	global_load_lds_dwordx4 v[146:147], off
	v_lshl_add_u64 v[146:147], v[238:239], 0, s[64:65]
	s_mov_b32 m0, s56
	s_nop 0
	global_load_lds_dwordx4 v[146:147], off
	v_lshl_add_u64 v[146:147], v[240:241], 0, s[64:65]
	s_mov_b32 m0, s57
	s_nop 0
	global_load_lds_dwordx4 v[146:147], off
	s_waitcnt vmcnt(8)
	s_waitcnt lgkmcnt(0)
	s_barrier
	s_waitcnt lgkmcnt(0)
	v_mfma_f32_16x16x32_bf16 v[60:63], v[140:143], v[196:199], v[60:63]
	v_mfma_f32_16x16x32_bf16 v[56:59], v[172:175], v[196:199], v[56:59]
	v_mfma_f32_16x16x32_bf16 v[44:47], v[140:143], v[204:207], v[44:47]
	v_mfma_f32_16x16x32_bf16 v[40:43], v[172:175], v[204:207], v[40:43]
	v_mfma_f32_16x16x32_bf16 v[28:31], v[140:143], v[212:215], v[28:31]
	v_mfma_f32_16x16x32_bf16 v[24:27], v[172:175], v[212:215], v[24:27]
	v_mfma_f32_16x16x32_bf16 v[12:15], v[140:143], v[220:223], v[12:15]
	v_mfma_f32_16x16x32_bf16 v[8:11], v[172:175], v[220:223], v[8:11]
	v_mfma_f32_16x16x32_bf16 v[60:63], v[168:171], v[200:203], v[60:63]
	v_mfma_f32_16x16x32_bf16 v[56:59], v[176:179], v[200:203], v[56:59]
	v_mfma_f32_16x16x32_bf16 v[44:47], v[168:171], v[208:211], v[44:47]
	v_mfma_f32_16x16x32_bf16 v[40:43], v[176:179], v[208:211], v[40:43]
	v_mfma_f32_16x16x32_bf16 v[28:31], v[168:171], v[216:219], v[28:31]
	v_mfma_f32_16x16x32_bf16 v[24:27], v[176:179], v[216:219], v[24:27]
	v_mfma_f32_16x16x32_bf16 v[12:15], v[168:171], v[224:227], v[12:15]
	v_mfma_f32_16x16x32_bf16 v[8:11], v[176:179], v[224:227], v[8:11]
	v_mfma_f32_16x16x32_bf16 v[52:55], v[180:183], v[196:199], v[52:55]
	v_mfma_f32_16x16x32_bf16 v[48:51], v[188:191], v[196:199], v[48:51]
	v_mfma_f32_16x16x32_bf16 v[36:39], v[180:183], v[204:207], v[36:39]
	v_mfma_f32_16x16x32_bf16 v[32:35], v[188:191], v[204:207], v[32:35]
	v_mfma_f32_16x16x32_bf16 v[20:23], v[180:183], v[212:215], v[20:23]
	v_mfma_f32_16x16x32_bf16 v[16:19], v[188:191], v[212:215], v[16:19]
	v_mfma_f32_16x16x32_bf16 v[4:7], v[180:183], v[220:223], v[4:7]
	v_mfma_f32_16x16x32_bf16 v[0:3], v[188:191], v[220:223], v[0:3]
	v_mfma_f32_16x16x32_bf16 v[52:55], v[184:187], v[200:203], v[52:55]
	v_mfma_f32_16x16x32_bf16 v[48:51], v[192:195], v[200:203], v[48:51]
	v_mfma_f32_16x16x32_bf16 v[36:39], v[184:187], v[208:211], v[36:39]
	v_mfma_f32_16x16x32_bf16 v[32:35], v[192:195], v[208:211], v[32:35]
	v_mfma_f32_16x16x32_bf16 v[20:23], v[184:187], v[216:219], v[20:23]
	v_mfma_f32_16x16x32_bf16 v[16:19], v[192:195], v[216:219], v[16:19]
	v_mfma_f32_16x16x32_bf16 v[4:7], v[184:187], v[224:227], v[4:7]
	v_mfma_f32_16x16x32_bf16 v[0:3], v[192:195], v[224:227], v[0:3]
	s_barrier
	s_add_u32 s0, s0, 0x100
	s_addc_u32 s1, s1, 0
	s_add_u32 s22, s22, 0x100
	s_addc_u32 s23, s23, 0
	s_cmp_ge_i32 s36, s52
	s_mov_b32 s6, s36
	s_cbranch_scc0 .LBB0_928
	s_branch .Lpeel_exit_g3

; #define PG8_BAR __builtin_amdgcn_s_barrier()
; __device__ __forceinline__ void rows_rstd(const float* part, int M, int row0, int fr, int fq, float (&rs)[8]) {
;     const int L = fr | (fq << 4); const float* p = part + (row0 - fr) + L; float sa = 0.f, sb = 0.f;
; #pragma unroll
;     for (int i = 0; i < 32; ++i) { sa += p[(size_t)i * M]; sb += p[(size_t)i * M + HALF]; }
;     const int ra = __builtin_bit_cast(int, rsqrtf(sa * (1.0f / 2048.0f) + RMS_EPS)), rb = __builtin_bit_cast(int, rsqrtf(sb * (1.0f / 2048.0f) + RMS_EPS));
; template <class Epi, class Sched, bool ALIGN_EPI = false, bool SP2 = false>
; __device__ __forceinline__ void gemm_phase(PG8_LAS unsigned char* lds, const Gemm g, const Sched& S, const Epi& E, int tid_in) {
;     ...
;         if constexpr (ALIGN_EPI) { if (wr == 0) PG8_BAR; }
;         if constexpr (!Epi::AFTER_DRAIN) { E(acc, cur, wr, wc, fr, fq); S.done(cur); }
.Lpeel_exit_g3:
.LBB0_929:
	s_and_b64 vcc, exec, s[54:55]
	s_cbranch_vccz .LBB0_931
	s_barrier
.LBB0_931:
	s_lshl_b32 s0, s35, 8
	s_add_i32 s0, s0, s53
	v_or_b32_e32 v150, s0, v145
	v_mul_lo_u32 v150, v150, s82
	v_lshl_or_b32 v143, s34, 7, v166
	v_lshl_add_u32 v150, v143, 1, v150
	v_and_b32_e32 v148, 0x60, v166
	v_lshlrev_b32_e32 v148, 4, v148
	s_lshl_b32 s1, s53, 5
	s_add_i32 s1, s1, 0x21000
	v_add_u32_e32 v146, s1, v148
	v_lshl_add_u32 v148, v145, 2, v146
	s_cmp_eq_u32 s100, s35
	s_cbranch_scc1 .Lepi_g3_cached
	v_readfirstlane_b32 s98, v134
	v_readfirstlane_b32 s99, v135
	v_lshlrev_b32_e32 v142, 2, v145
	v_and_b32_e32 v143, 0x18, v166
	v_lshl_add_u32 v142, v143, 3, v142
	v_add_u32_e32 v146, v146, v142
	s_lshl_b32 s0, s0, 2
	v_add_u32_e32 v142, s0, v142
	s_nop 1
	global_load_dword v168, v142, s[98:99]
	global_load_dword v169, v142, s[98:99] offset:512
	s_add_u32 s98, s98, 0x20000
	s_addc_u32 s99, s99, 0
	global_load_dword v170, v142, s[98:99]
	global_load_dword v171, v142, s[98:99] offset:512
	s_add_u32 s98, s98, 0x20000
	s_addc_u32 s99, s99, 0
	global_load_dword v172, v142, s[98:99]
	global_load_dword v173, v142, s[98:99] offset:512
	s_add_u32 s98, s98, 0x20000
	s_addc_u32 s99, s99, 0
	global_load_dword v174, v142, s[98:99]
	global_load_dword v175, v142, s[98:99] offset:512
	s_add_u32 s98, s98, 0x20000
	s_addc_u32 s99, s99, 0
	global_load_dword v176, v142, s[98:99]
	global_load_dword v177, v142, s[98:99] offset:512
	s_add_u32 s98, s98, 0x20000
	s_addc_u32 s99, s99, 0
	global_load_dword v178, v142, s[98:99]
	global_load_dword v179, v142, s[98:99] offset:512
	s_add_u32 s98, s98, 0x20000
	s_addc_u32 s99, s99, 0
	global_load_dword v180, v142, s[98:99]
	global_load_dword v181, v142, s[98:99] offset:512
	s_add_u32 s98, s98, 0x20000
	s_addc_u32 s99, s99, 0
	global_load_dword v182, v142, s[98:99]
	global_load_dword v183, v142, s[98:99] offset:512
	s_add_u32 s98, s98, 0x20000
	s_addc_u32 s99, s99, 0
	global_load_dword v184, v142, s[98:99]
	global_load_dword v185, v142, s[98:99] offset:512
	s_add_u32 s98, s98, 0x20000
	s_addc_u32 s99, s99, 0
	global_load_dword v186, v142, s[98:99]
	global_load_dword v187, v142, s[98:99] offset:512
	s_add_u32 s98, s98, 0x20000
	s_addc_u32 s99, s99, 0
	global_load_dword v188, v142, s[98:99]
	global_load_dword v189, v142, s[98:99] offset:512
	s_add_u32 s98, s98, 0x20000
	s_addc_u32 s99, s99, 0
	global_load_dword v190, v142, s[98:99]
	global_load_dword v191, v142, s[98:99] offset:512
	s_add_u32 s98, s98, 0x20000
	s_addc_u32 s99, s99, 0
	global_load_dword v192, v142, s[98:99]
	global_load_dword v193, v142, s[98:99] offset:512
	s_add_u32 s98, s98, 0x20000
	s_addc_u32 s99, s99, 0
	global_load_dword v194, v142, s[98:99]
	global_load_dword v195, v142, s[98:99] offset:512
	s_add_u32 s98, s98, 0x20000
	s_addc_u32 s99, s99, 0
	global_load_dword v196, v142, s[98:99]
	global_load_dword v197, v142, s[98:99] offset:512
	s_add_u32 s98, s98, 0x20000
	s_addc_u32 s99, s99, 0
	global_load_dword v198, v142, s[98:99]
	global_load_dword v199, v142, s[98:99] offset:512
	s_add_u32 s98, s98, 0x20000
	s_addc_u32 s99, s99, 0
	global_load_dword v200, v142, s[98:99]
	global_load_dword v201, v142, s[98:99] offset:512
	s_add_u32 s98, s98, 0x20000
	s_addc_u32 s99, s99, 0
	global_load_dword v202, v142, s[98:99]
	global_load_dword v203, v142, s[98:99] offset:512
	s_add_u32 s98, s98, 0x20000
	s_addc_u32 s99, s99, 0
	global_load_dword v204, v142, s[98:99]
	global_load_dword v205, v142, s[98:99] offset:512
	s_add_u32 s98, s98, 0x20000
	s_addc_u32 s99, s99, 0
	global_load_dword v206, v142, s[98:99]
	global_load_dword v207, v142, s[98:99] offset:512
	s_add_u32 s98, s98, 0x20000
	s_addc_u32 s99, s99, 0
	global_load_dword v208, v142, s[98:99]
	global_load_dword v209, v142, s[98:99] offset:512
	s_add_u32 s98, s98, 0x20000
	s_addc_u32 s99, s99, 0
	global_load_dword v210, v142, s[98:99]
	global_load_dword v211, v142, s[98:99] offset:512
	s_add_u32 s98, s98, 0x20000
	s_addc_u32 s99, s99, 0
	global_load_dword v212, v142, s[98:99]
	global_load_dword v213, v142, s[98:99] offset:512
	s_add_u32 s98, s98, 0x20000
	s_addc_u32 s99, s99, 0
	global_load_dword v214, v142, s[98:99]
	global_load_dword v215, v142, s[98:99] offset:512
	s_add_u32 s98, s98, 0x20000
	s_addc_u32 s99, s99, 0
	global_load_dword v216, v142, s[98:99]
	global_load_dword v217, v142, s[98:99] offset:512
	s_add_u32 s98, s98, 0x20000
	s_addc_u32 s99, s99, 0
	global_load_dword v218, v142, s[98:99]
	global_load_dword v219, v142, s[98:99] offset:512
	s_add_u32 s98, s98, 0x20000
	s_addc_u32 s99, s99, 0
	global_load_dword v220, v142, s[98:99]
	global_load_dword v221, v142, s[98:99] offset:512
	s_add_u32 s98, s98, 0x20000
	s_addc_u32 s99, s99, 0
	global_load_dword v222, v142, s[98:99]
	global_load_dword v223, v142, s[98:99] offset:512
	s_add_u32 s98, s98, 0x20000
	s_addc_u32 s99, s99, 0
	global_load_dword v224, v142, s[98:99]
	global_load_dword v225, v142, s[98:99] offset:512
	s_add_u32 s98, s98, 0x20000
	s_addc_u32 s99, s99, 0
	global_load_dword v226, v142, s[98:99]
	global_load_dword v227, v142, s[98:99] offset:512
	s_add_u32 s98, s98, 0x20000
	s_addc_u32 s99, s99, 0
	global_load_dword v228, v142, s[98:99]
	global_load_dword v229, v142, s[98:99] offset:512
	s_add_u32 s98, s98, 0x20000
	s_addc_u32 s99, s99, 0
	global_load_dword v140, v142, s[98:99]
	global_load_dword v141, v142, s[98:99] offset:512
	s_waitcnt vmcnt(62)
	v_add_f32_e32 v143, 0, v168
	v_add_f32_e32 v144, 0, v169
	s_waitcnt vmcnt(60)
	v_add_f32_e32 v143, v143, v170
	v_add_f32_e32 v144, v144, v171
	s_waitcnt vmcnt(58)
	v_add_f32_e32 v143, v143, v172
	v_add_f32_e32 v144, v144, v173
	s_waitcnt vmcnt(56)
; __device__ __forceinline__ unsigned cvt_pk_bf16(float lo, float hi) { unsigned r; asm volatile("s_nop 0\n\tv_cvt_pk_bf16_f32 %0, %1, %2" : "=v"(r) : "v"(lo), "v"(hi)); return r; }
; __device__ __forceinline__ float silu_mul(float g, float u) { return g * u * __builtin_amdgcn_rcpf(1.0f + __expf(-g)); }
; __device__ __forceinline__ void rows_rstd(const float* part, int M, int row0, int fr, int fq, float (&rs)[8]) {
;     ...
;     for (int i = 0; i < 32; ++i) { sa += p[(size_t)i * M]; sb += p[(size_t)i * M + HALF]; }
;     const int ra = __builtin_bit_cast(int, rsqrtf(sa * (1.0f / 2048.0f) + RMS_EPS)), rb = __builtin_bit_cast(int, rsqrtf(sb * (1.0f / 2048.0f) + RMS_EPS));
; #pragma unroll
;     for (int r = 0; r < 8; ++r) rs[r] = __builtin_bit_cast(float, __builtin_amdgcn_ds_bpermute(((r & 3) * 16 + fr) << 2, (r >> 2) ? rb : ra));
; }
;     __device__ __forceinline__ void operator()(const f32x4 (&acc)[2][2][4][2], const Unit& u, int wr, int wc, int fr, int fq) const {
;     ...
; #pragma unroll
;         for (int ai = 0; ai < 2; ++ai)
; #pragma unroll
;             for (int m = 0; m < 4; ++m) { const int row = row0 + ai * HALF + m * 16; const float rs = rs8[ai * 4 + m];
;                 const f32x4 g0 = acc[ai][0][m][0] * rs, g1 = acc[ai][0][m][1] * rs, u0 = acc[ai][1][m][0] * rs, u1 = acc[ai][1][m][1] * rs;
;                 u32x4 w; w.x = cvt_pk_bf16(silu_mul(g0[0], u0[0]), silu_mul(g0[1], u0[1])); w.y = cvt_pk_bf16(silu_mul(g0[2], u0[2]), silu_mul(g0[3], u0[3]));
;                 w.z = cvt_pk_bf16(silu_mul(g1[0], u1[0]), silu_mul(g1[1], u1[1])); w.w = cvt_pk_bf16(silu_mul(g1[2], u1[2]), silu_mul(g1[3], u1[3]));
;                 *(u32x4*)(H + (size_t)row * ldh + col0) = w; }
	v_add_f32_e32 v143, v143, v174
	v_add_f32_e32 v144, v144, v175
	s_waitcnt vmcnt(54)
	v_add_f32_e32 v143, v143, v176
	v_add_f32_e32 v144, v144, v177
	s_waitcnt vmcnt(52)
	v_add_f32_e32 v143, v143, v178
	v_add_f32_e32 v144, v144, v179
	s_waitcnt vmcnt(50)
	v_add_f32_e32 v143, v143, v180
	v_add_f32_e32 v144, v144, v181
	s_waitcnt vmcnt(48)
	v_add_f32_e32 v143, v143, v182
	v_add_f32_e32 v144, v144, v183
	s_waitcnt vmcnt(46)
	v_add_f32_e32 v143, v143, v184
	v_add_f32_e32 v144, v144, v185
	s_waitcnt vmcnt(44)
	v_add_f32_e32 v143, v143, v186
	v_add_f32_e32 v144, v144, v187
	s_waitcnt vmcnt(42)
	v_add_f32_e32 v143, v143, v188
	v_add_f32_e32 v144, v144, v189
	s_waitcnt vmcnt(40)
	v_add_f32_e32 v143, v143, v190
	v_add_f32_e32 v144, v144, v191
	s_waitcnt vmcnt(38)
	v_add_f32_e32 v143, v143, v192
	v_add_f32_e32 v144, v144, v193
	s_waitcnt vmcnt(36)
	v_add_f32_e32 v143, v143, v194
	v_add_f32_e32 v144, v144, v195
	s_waitcnt vmcnt(34)
	v_add_f32_e32 v143, v143, v196
	v_add_f32_e32 v144, v144, v197
	s_waitcnt vmcnt(32)
	v_add_f32_e32 v143, v143, v198
	v_add_f32_e32 v144, v144, v199
	s_waitcnt vmcnt(30)
	v_add_f32_e32 v143, v143, v200
	v_add_f32_e32 v144, v144, v201
	s_waitcnt vmcnt(28)
	v_add_f32_e32 v143, v143, v202
	v_add_f32_e32 v144, v144, v203
	s_waitcnt vmcnt(26)
	v_add_f32_e32 v143, v143, v204
	v_add_f32_e32 v144, v144, v205
	s_waitcnt vmcnt(24)
	v_add_f32_e32 v143, v143, v206
	v_add_f32_e32 v144, v144, v207
	s_waitcnt vmcnt(22)
	v_add_f32_e32 v143, v143, v208
	v_add_f32_e32 v144, v144, v209
	s_waitcnt vmcnt(20)
	v_add_f32_e32 v143, v143, v210
	v_add_f32_e32 v144, v144, v211
	s_waitcnt vmcnt(18)
	v_add_f32_e32 v143, v143, v212
	v_add_f32_e32 v144, v144, v213
	s_waitcnt vmcnt(16)
	v_add_f32_e32 v143, v143, v214
	v_add_f32_e32 v144, v144, v215
	s_waitcnt vmcnt(14)
	v_add_f32_e32 v143, v143, v216
	v_add_f32_e32 v144, v144, v217
	s_waitcnt vmcnt(12)
	v_add_f32_e32 v143, v143, v218
	v_add_f32_e32 v144, v144, v219
	s_waitcnt vmcnt(10)
	v_add_f32_e32 v143, v143, v220
	v_add_f32_e32 v144, v144, v221
	s_waitcnt vmcnt(8)
	v_add_f32_e32 v143, v143, v222
	v_add_f32_e32 v144, v144, v223
	s_waitcnt vmcnt(6)
	v_add_f32_e32 v143, v143, v224
	v_add_f32_e32 v144, v144, v225
	s_waitcnt vmcnt(4)
	v_add_f32_e32 v143, v143, v226
	v_add_f32_e32 v144, v144, v227
	s_waitcnt vmcnt(2)
	v_add_f32_e32 v143, v143, v228
	v_add_f32_e32 v144, v144, v229
	s_waitcnt vmcnt(0)
	v_add_f32_e32 v143, v143, v140
	v_add_f32_e32 v144, v144, v141
	s_mov_b32 s1, 0x3a000000
	v_fma_f32 v143, v143, s1, v158
	v_fma_f32 v144, v144, s1, v158
	v_rsq_f32_e32 v143, v143
	v_rsq_f32_e32 v144, v144
	s_mov_b32 s100, s35
	s_nop 0
	ds_write_b32 v146, v143
	ds_write_b32 v146, v144 offset:256
.Lepi_g3_cached:
	ds_read_b32 v168, v148 offset:0
	ds_read_b32 v170, v148 offset:64
	ds_read_b32 v172, v148 offset:128
	ds_read_b32 v174, v148 offset:192
	ds_read_b32 v176, v148 offset:256
	ds_read_b32 v178, v148 offset:320
	ds_read_b32 v180, v148 offset:384
	ds_read_b32 v182, v148 offset:448
	s_lshl_b32 s0, s82, 4
	s_mul_i32 s1, s82, 0x50
	v_mov_b32_e32 v142, 0xbfb8aa3b
	s_waitcnt lgkmcnt(7)
	v_pk_mul_f32 v[124:125], v[124:125], v[168:169] op_sel_hi:[1,0]
	v_pk_mul_f32 v[126:127], v[126:127], v[168:169] op_sel_hi:[1,0]
	v_pk_mul_f32 v[120:121], v[120:121], v[168:169] op_sel_hi:[1,0]
	v_pk_mul_f32 v[122:123], v[122:123], v[168:169] op_sel_hi:[1,0]
	v_pk_mul_f32 v[116:117], v[116:117], v[168:169] op_sel_hi:[1,0]
	v_pk_mul_f32 v[118:119], v[118:119], v[168:169] op_sel_hi:[1,0]
	v_pk_mul_f32 v[112:113], v[112:113], v[168:169] op_sel_hi:[1,0]
	v_pk_mul_f32 v[114:115], v[114:115], v[168:169] op_sel_hi:[1,0]
	v_pk_mul_f32 v[184:185], v[124:125], v[142:143] op_sel_hi:[1,0]
	v_pk_mul_f32 v[186:187], v[126:127], v[142:143] op_sel_hi:[1,0]
	v_pk_mul_f32 v[188:189], v[120:121], v[142:143] op_sel_hi:[1,0]
	v_pk_mul_f32 v[190:191], v[122:123], v[142:143] op_sel_hi:[1,0]
	v_pk_mul_f32 v[116:117], v[124:125], v[116:117]
	v_pk_mul_f32 v[118:119], v[126:127], v[118:119]
	v_pk_mul_f32 v[112:113], v[120:121], v[112:113]
	v_pk_mul_f32 v[114:115], v[122:123], v[114:115]
	v_exp_f32_e32 v184, v184
	v_exp_f32_e32 v185, v185
	v_exp_f32_e32 v186, v186
	v_exp_f32_e32 v187, v187
	v_exp_f32_e32 v188, v188
	v_exp_f32_e32 v189, v189
	v_exp_f32_e32 v190, v190
	v_exp_f32_e32 v191, v191
	v_pk_add_f32 v[184:185], v[184:185], 1.0 op_sel_hi:[1,0]
	v_pk_add_f32 v[186:187], v[186:187], 1.0 op_sel_hi:[1,0]
	v_pk_add_f32 v[188:189], v[188:189], 1.0 op_sel_hi:[1,0]
	v_pk_add_f32 v[190:191], v[190:191], 1.0 op_sel_hi:[1,0]
	v_rcp_f32_e32 v184, v184
	v_rcp_f32_e32 v185, v185
	v_rcp_f32_e32 v186, v186
	v_rcp_f32_e32 v187, v187
	v_rcp_f32_e32 v188, v188
	v_rcp_f32_e32 v189, v189
	v_rcp_f32_e32 v190, v190
	v_rcp_f32_e32 v191, v191
	v_pk_mul_f32 v[116:117], v[116:117], v[184:185]
	v_pk_mul_f32 v[118:119], v[118:119], v[186:187]
	v_pk_mul_f32 v[112:113], v[112:113], v[188:189]
	v_pk_mul_f32 v[114:115], v[114:115], v[190:191]
	v_cvt_pk_bf16_f32 v192, v116, v117
	v_cvt_pk_bf16_f32 v193, v118, v119
	v_cvt_pk_bf16_f32 v194, v112, v113
	v_cvt_pk_bf16_f32 v195, v114, v115
	global_store_dwordx4 v150, v[192:195], s[16:17]
	v_add_u32_e32 v150, s0, v150
	s_waitcnt lgkmcnt(6)
; __device__ __forceinline__ unsigned cvt_pk_bf16(float lo, float hi) { unsigned r; asm volatile("s_nop 0\n\tv_cvt_pk_bf16_f32 %0, %1, %2" : "=v"(r) : "v"(lo), "v"(hi)); return r; }
; __device__ __forceinline__ float silu_mul(float g, float u) { return g * u * __builtin_amdgcn_rcpf(1.0f + __expf(-g)); }
;     __device__ __forceinline__ void operator()(const f32x4 (&acc)[2][2][4][2], const Unit& u, int wr, int wc, int fr, int fq) const {
;     ...
;             for (int m = 0; m < 4; ++m) { const int row = row0 + ai * HALF + m * 16; const float rs = rs8[ai * 4 + m];
;                 const f32x4 g0 = acc[ai][0][m][0] * rs, g1 = acc[ai][0][m][1] * rs, u0 = acc[ai][1][m][0] * rs, u1 = acc[ai][1][m][1] * rs;
;                 u32x4 w; w.x = cvt_pk_bf16(silu_mul(g0[0], u0[0]), silu_mul(g0[1], u0[1])); w.y = cvt_pk_bf16(silu_mul(g0[2], u0[2]), silu_mul(g0[3], u0[3]));
;                 w.z = cvt_pk_bf16(silu_mul(g1[0], u1[0]), silu_mul(g1[1], u1[1])); w.w = cvt_pk_bf16(silu_mul(g1[2], u1[2]), silu_mul(g1[3], u1[3]));
;                 *(u32x4*)(H + (size_t)row * ldh + col0) = w; }
	v_pk_mul_f32 v[108:109], v[108:109], v[170:171] op_sel_hi:[1,0]
	v_pk_mul_f32 v[110:111], v[110:111], v[170:171] op_sel_hi:[1,0]
	v_pk_mul_f32 v[104:105], v[104:105], v[170:171] op_sel_hi:[1,0]
	v_pk_mul_f32 v[106:107], v[106:107], v[170:171] op_sel_hi:[1,0]
	v_pk_mul_f32 v[100:101], v[100:101], v[170:171] op_sel_hi:[1,0]
	v_pk_mul_f32 v[102:103], v[102:103], v[170:171] op_sel_hi:[1,0]
	v_pk_mul_f32 v[96:97], v[96:97], v[170:171] op_sel_hi:[1,0]
	v_pk_mul_f32 v[98:99], v[98:99], v[170:171] op_sel_hi:[1,0]
	v_pk_mul_f32 v[184:185], v[108:109], v[142:143] op_sel_hi:[1,0]
	v_pk_mul_f32 v[186:187], v[110:111], v[142:143] op_sel_hi:[1,0]
	v_pk_mul_f32 v[188:189], v[104:105], v[142:143] op_sel_hi:[1,0]
	v_pk_mul_f32 v[190:191], v[106:107], v[142:143] op_sel_hi:[1,0]
	v_pk_mul_f32 v[100:101], v[108:109], v[100:101]
	v_pk_mul_f32 v[102:103], v[110:111], v[102:103]
	v_pk_mul_f32 v[96:97], v[104:105], v[96:97]
	v_pk_mul_f32 v[98:99], v[106:107], v[98:99]
	v_exp_f32_e32 v184, v184
	v_exp_f32_e32 v185, v185
	v_exp_f32_e32 v186, v186
	v_exp_f32_e32 v187, v187
	v_exp_f32_e32 v188, v188
	v_exp_f32_e32 v189, v189
	v_exp_f32_e32 v190, v190
	v_exp_f32_e32 v191, v191
	v_pk_add_f32 v[184:185], v[184:185], 1.0 op_sel_hi:[1,0]
	v_pk_add_f32 v[186:187], v[186:187], 1.0 op_sel_hi:[1,0]
	v_pk_add_f32 v[188:189], v[188:189], 1.0 op_sel_hi:[1,0]
	v_pk_add_f32 v[190:191], v[190:191], 1.0 op_sel_hi:[1,0]
	v_rcp_f32_e32 v184, v184
	v_rcp_f32_e32 v185, v185
	v_rcp_f32_e32 v186, v186
	v_rcp_f32_e32 v187, v187
	v_rcp_f32_e32 v188, v188
	v_rcp_f32_e32 v189, v189
	v_rcp_f32_e32 v190, v190
	v_rcp_f32_e32 v191, v191
	v_pk_mul_f32 v[100:101], v[100:101], v[184:185]
	v_pk_mul_f32 v[102:103], v[102:103], v[186:187]
	v_pk_mul_f32 v[96:97], v[96:97], v[188:189]
	v_pk_mul_f32 v[98:99], v[98:99], v[190:191]
	v_cvt_pk_bf16_f32 v196, v100, v101
	v_cvt_pk_bf16_f32 v197, v102, v103
	v_cvt_pk_bf16_f32 v198, v96, v97
	v_cvt_pk_bf16_f32 v199, v98, v99
	global_store_dwordx4 v150, v[196:199], s[16:17]
	v_add_u32_e32 v150, s0, v150
	s_waitcnt lgkmcnt(5)
	v_pk_mul_f32 v[92:93], v[92:93], v[172:173] op_sel_hi:[1,0]
	v_pk_mul_f32 v[94:95], v[94:95], v[172:173] op_sel_hi:[1,0]
	v_pk_mul_f32 v[88:89], v[88:89], v[172:173] op_sel_hi:[1,0]
	v_pk_mul_f32 v[90:91], v[90:91], v[172:173] op_sel_hi:[1,0]
	v_pk_mul_f32 v[84:85], v[84:85], v[172:173] op_sel_hi:[1,0]
	v_pk_mul_f32 v[86:87], v[86:87], v[172:173] op_sel_hi:[1,0]
	v_pk_mul_f32 v[80:81], v[80:81], v[172:173] op_sel_hi:[1,0]
	v_pk_mul_f32 v[82:83], v[82:83], v[172:173] op_sel_hi:[1,0]
	v_pk_mul_f32 v[184:185], v[92:93], v[142:143] op_sel_hi:[1,0]
	v_pk_mul_f32 v[186:187], v[94:95], v[142:143] op_sel_hi:[1,0]
	v_pk_mul_f32 v[188:189], v[88:89], v[142:143] op_sel_hi:[1,0]
	v_pk_mul_f32 v[190:191], v[90:91], v[142:143] op_sel_hi:[1,0]
	v_pk_mul_f32 v[84:85], v[92:93], v[84:85]
	v_pk_mul_f32 v[86:87], v[94:95], v[86:87]
	v_pk_mul_f32 v[80:81], v[88:89], v[80:81]
	v_pk_mul_f32 v[82:83], v[90:91], v[82:83]
	v_exp_f32_e32 v184, v184
	v_exp_f32_e32 v185, v185
	v_exp_f32_e32 v186, v186
	v_exp_f32_e32 v187, v187
	v_exp_f32_e32 v188, v188
	v_exp_f32_e32 v189, v189
	v_exp_f32_e32 v190, v190
	v_exp_f32_e32 v191, v191
	v_pk_add_f32 v[184:185], v[184:185], 1.0 op_sel_hi:[1,0]
	v_pk_add_f32 v[186:187], v[186:187], 1.0 op_sel_hi:[1,0]
	v_pk_add_f32 v[188:189], v[188:189], 1.0 op_sel_hi:[1,0]
	v_pk_add_f32 v[190:191], v[190:191], 1.0 op_sel_hi:[1,0]
	v_rcp_f32_e32 v184, v184
	v_rcp_f32_e32 v185, v185
	v_rcp_f32_e32 v186, v186
	v_rcp_f32_e32 v187, v187
	v_rcp_f32_e32 v188, v188
	v_rcp_f32_e32 v189, v189
	v_rcp_f32_e32 v190, v190
	v_rcp_f32_e32 v191, v191
	v_pk_mul_f32 v[84:85], v[84:85], v[184:185]
	v_pk_mul_f32 v[86:87], v[86:87], v[186:187]
	v_pk_mul_f32 v[80:81], v[80:81], v[188:189]
	v_pk_mul_f32 v[82:83], v[82:83], v[190:191]
	v_cvt_pk_bf16_f32 v192, v84, v85
	v_cvt_pk_bf16_f32 v193, v86, v87
	v_cvt_pk_bf16_f32 v194, v80, v81
	v_cvt_pk_bf16_f32 v195, v82, v83
	global_store_dwordx4 v150, v[192:195], s[16:17]
	v_add_u32_e32 v150, s0, v150
	s_waitcnt lgkmcnt(4)
	v_pk_mul_f32 v[76:77], v[76:77], v[174:175] op_sel_hi:[1,0]
	v_pk_mul_f32 v[78:79], v[78:79], v[174:175] op_sel_hi:[1,0]
	v_pk_mul_f32 v[72:73], v[72:73], v[174:175] op_sel_hi:[1,0]
	v_pk_mul_f32 v[74:75], v[74:75], v[174:175] op_sel_hi:[1,0]
	v_pk_mul_f32 v[68:69], v[68:69], v[174:175] op_sel_hi:[1,0]
	v_pk_mul_f32 v[70:71], v[70:71], v[174:175] op_sel_hi:[1,0]
	v_pk_mul_f32 v[64:65], v[64:65], v[174:175] op_sel_hi:[1,0]
	v_pk_mul_f32 v[66:67], v[66:67], v[174:175] op_sel_hi:[1,0]
	v_pk_mul_f32 v[184:185], v[76:77], v[142:143] op_sel_hi:[1,0]
	v_pk_mul_f32 v[186:187], v[78:79], v[142:143] op_sel_hi:[1,0]
	v_pk_mul_f32 v[188:189], v[72:73], v[142:143] op_sel_hi:[1,0]
	v_pk_mul_f32 v[190:191], v[74:75], v[142:143] op_sel_hi:[1,0]
	v_pk_mul_f32 v[68:69], v[76:77], v[68:69]
	v_pk_mul_f32 v[70:71], v[78:79], v[70:71]
	v_pk_mul_f32 v[64:65], v[72:73], v[64:65]
	v_pk_mul_f32 v[66:67], v[74:75], v[66:67]
	v_exp_f32_e32 v184, v184
	v_exp_f32_e32 v185, v185
	v_exp_f32_e32 v186, v186
	v_exp_f32_e32 v187, v187
	v_exp_f32_e32 v188, v188
	v_exp_f32_e32 v189, v189
	v_exp_f32_e32 v190, v190
	v_exp_f32_e32 v191, v191
	v_pk_add_f32 v[184:185], v[184:185], 1.0 op_sel_hi:[1,0]
	v_pk_add_f32 v[186:187], v[186:187], 1.0 op_sel_hi:[1,0]
	v_pk_add_f32 v[188:189], v[188:189], 1.0 op_sel_hi:[1,0]
	v_pk_add_f32 v[190:191], v[190:191], 1.0 op_sel_hi:[1,0]
	v_rcp_f32_e32 v184, v184
	v_rcp_f32_e32 v185, v185
	v_rcp_f32_e32 v186, v186
	v_rcp_f32_e32 v187, v187
	v_rcp_f32_e32 v188, v188
	v_rcp_f32_e32 v189, v189
	v_rcp_f32_e32 v190, v190
	v_rcp_f32_e32 v191, v191
	v_pk_mul_f32 v[68:69], v[68:69], v[184:185]
	v_pk_mul_f32 v[70:71], v[70:71], v[186:187]
	v_pk_mul_f32 v[64:65], v[64:65], v[188:189]
	v_pk_mul_f32 v[66:67], v[66:67], v[190:191]
	v_cvt_pk_bf16_f32 v196, v68, v69
	v_cvt_pk_bf16_f32 v197, v70, v71
	v_cvt_pk_bf16_f32 v198, v64, v65
	v_cvt_pk_bf16_f32 v199, v66, v67
	global_store_dwordx4 v150, v[196:199], s[16:17]
	v_add_u32_e32 v150, s1, v150
	s_waitcnt lgkmcnt(3)
; __device__ __forceinline__ unsigned cvt_pk_bf16(float lo, float hi) { unsigned r; asm volatile("s_nop 0\n\tv_cvt_pk_bf16_f32 %0, %1, %2" : "=v"(r) : "v"(lo), "v"(hi)); return r; }
; __device__ __forceinline__ float silu_mul(float g, float u) { return g * u * __builtin_amdgcn_rcpf(1.0f + __expf(-g)); }
;     __device__ __forceinline__ void operator()(const f32x4 (&acc)[2][2][4][2], const Unit& u, int wr, int wc, int fr, int fq) const {
;     ...
;             for (int m = 0; m < 4; ++m) { const int row = row0 + ai * HALF + m * 16; const float rs = rs8[ai * 4 + m];
;                 const f32x4 g0 = acc[ai][0][m][0] * rs, g1 = acc[ai][0][m][1] * rs, u0 = acc[ai][1][m][0] * rs, u1 = acc[ai][1][m][1] * rs;
;                 u32x4 w; w.x = cvt_pk_bf16(silu_mul(g0[0], u0[0]), silu_mul(g0[1], u0[1])); w.y = cvt_pk_bf16(silu_mul(g0[2], u0[2]), silu_mul(g0[3], u0[3]));
;                 w.z = cvt_pk_bf16(silu_mul(g1[0], u1[0]), silu_mul(g1[1], u1[1])); w.w = cvt_pk_bf16(silu_mul(g1[2], u1[2]), silu_mul(g1[3], u1[3]));
;                 *(u32x4*)(H + (size_t)row * ldh + col0) = w; }
	v_pk_mul_f32 v[60:61], v[60:61], v[176:177] op_sel_hi:[1,0]
	v_pk_mul_f32 v[62:63], v[62:63], v[176:177] op_sel_hi:[1,0]
	v_pk_mul_f32 v[56:57], v[56:57], v[176:177] op_sel_hi:[1,0]
	v_pk_mul_f32 v[58:59], v[58:59], v[176:177] op_sel_hi:[1,0]
	v_pk_mul_f32 v[52:53], v[52:53], v[176:177] op_sel_hi:[1,0]
	v_pk_mul_f32 v[54:55], v[54:55], v[176:177] op_sel_hi:[1,0]
	v_pk_mul_f32 v[48:49], v[48:49], v[176:177] op_sel_hi:[1,0]
	v_pk_mul_f32 v[50:51], v[50:51], v[176:177] op_sel_hi:[1,0]
	v_pk_mul_f32 v[184:185], v[60:61], v[142:143] op_sel_hi:[1,0]
	v_pk_mul_f32 v[186:187], v[62:63], v[142:143] op_sel_hi:[1,0]
	v_pk_mul_f32 v[188:189], v[56:57], v[142:143] op_sel_hi:[1,0]
	v_pk_mul_f32 v[190:191], v[58:59], v[142:143] op_sel_hi:[1,0]
	v_pk_mul_f32 v[52:53], v[60:61], v[52:53]
	v_pk_mul_f32 v[54:55], v[62:63], v[54:55]
	v_pk_mul_f32 v[48:49], v[56:57], v[48:49]
	v_pk_mul_f32 v[50:51], v[58:59], v[50:51]
	v_exp_f32_e32 v184, v184
	v_exp_f32_e32 v185, v185
	v_exp_f32_e32 v186, v186
	v_exp_f32_e32 v187, v187
	v_exp_f32_e32 v188, v188
	v_exp_f32_e32 v189, v189
	v_exp_f32_e32 v190, v190
	v_exp_f32_e32 v191, v191
	v_pk_add_f32 v[184:185], v[184:185], 1.0 op_sel_hi:[1,0]
	v_pk_add_f32 v[186:187], v[186:187], 1.0 op_sel_hi:[1,0]
	v_pk_add_f32 v[188:189], v[188:189], 1.0 op_sel_hi:[1,0]
	v_pk_add_f32 v[190:191], v[190:191], 1.0 op_sel_hi:[1,0]
	v_rcp_f32_e32 v184, v184
	v_rcp_f32_e32 v185, v185
	v_rcp_f32_e32 v186, v186
	v_rcp_f32_e32 v187, v187
	v_rcp_f32_e32 v188, v188
	v_rcp_f32_e32 v189, v189
	v_rcp_f32_e32 v190, v190
	v_rcp_f32_e32 v191, v191
	v_pk_mul_f32 v[52:53], v[52:53], v[184:185]
	v_pk_mul_f32 v[54:55], v[54:55], v[186:187]
	v_pk_mul_f32 v[48:49], v[48:49], v[188:189]
	v_pk_mul_f32 v[50:51], v[50:51], v[190:191]
	v_cvt_pk_bf16_f32 v192, v52, v53
	v_cvt_pk_bf16_f32 v193, v54, v55
	v_cvt_pk_bf16_f32 v194, v48, v49
	v_cvt_pk_bf16_f32 v195, v50, v51
	global_store_dwordx4 v150, v[192:195], s[16:17]
	v_add_u32_e32 v150, s0, v150
	s_waitcnt lgkmcnt(2)
	v_pk_mul_f32 v[44:45], v[44:45], v[178:179] op_sel_hi:[1,0]
	v_pk_mul_f32 v[46:47], v[46:47], v[178:179] op_sel_hi:[1,0]
	v_pk_mul_f32 v[40:41], v[40:41], v[178:179] op_sel_hi:[1,0]
	v_pk_mul_f32 v[42:43], v[42:43], v[178:179] op_sel_hi:[1,0]
	v_pk_mul_f32 v[36:37], v[36:37], v[178:179] op_sel_hi:[1,0]
	v_pk_mul_f32 v[38:39], v[38:39], v[178:179] op_sel_hi:[1,0]
	v_pk_mul_f32 v[32:33], v[32:33], v[178:179] op_sel_hi:[1,0]
	v_pk_mul_f32 v[34:35], v[34:35], v[178:179] op_sel_hi:[1,0]
	v_pk_mul_f32 v[184:185], v[44:45], v[142:143] op_sel_hi:[1,0]
	v_pk_mul_f32 v[186:187], v[46:47], v[142:143] op_sel_hi:[1,0]
	v_pk_mul_f32 v[188:189], v[40:41], v[142:143] op_sel_hi:[1,0]
	v_pk_mul_f32 v[190:191], v[42:43], v[142:143] op_sel_hi:[1,0]
	v_pk_mul_f32 v[36:37], v[44:45], v[36:37]
	v_pk_mul_f32 v[38:39], v[46:47], v[38:39]
	v_pk_mul_f32 v[32:33], v[40:41], v[32:33]
	v_pk_mul_f32 v[34:35], v[42:43], v[34:35]
	v_exp_f32_e32 v184, v184
	v_exp_f32_e32 v185, v185
	v_exp_f32_e32 v186, v186
	v_exp_f32_e32 v187, v187
	v_exp_f32_e32 v188, v188
	v_exp_f32_e32 v189, v189
	v_exp_f32_e32 v190, v190
	v_exp_f32_e32 v191, v191
	v_pk_add_f32 v[184:185], v[184:185], 1.0 op_sel_hi:[1,0]
	v_pk_add_f32 v[186:187], v[186:187], 1.0 op_sel_hi:[1,0]
	v_pk_add_f32 v[188:189], v[188:189], 1.0 op_sel_hi:[1,0]
	v_pk_add_f32 v[190:191], v[190:191], 1.0 op_sel_hi:[1,0]
	v_rcp_f32_e32 v184, v184
	v_rcp_f32_e32 v185, v185
	v_rcp_f32_e32 v186, v186
	v_rcp_f32_e32 v187, v187
	v_rcp_f32_e32 v188, v188
	v_rcp_f32_e32 v189, v189
	v_rcp_f32_e32 v190, v190
	v_rcp_f32_e32 v191, v191
	v_pk_mul_f32 v[36:37], v[36:37], v[184:185]
	v_pk_mul_f32 v[38:39], v[38:39], v[186:187]
	v_pk_mul_f32 v[32:33], v[32:33], v[188:189]
	v_pk_mul_f32 v[34:35], v[34:35], v[190:191]
	v_cvt_pk_bf16_f32 v196, v36, v37
	v_cvt_pk_bf16_f32 v197, v38, v39
	v_cvt_pk_bf16_f32 v198, v32, v33
	v_cvt_pk_bf16_f32 v199, v34, v35
	global_store_dwordx4 v150, v[196:199], s[16:17]
	v_add_u32_e32 v150, s0, v150
	s_waitcnt lgkmcnt(1)
; __device__ __forceinline__ unsigned cvt_pk_bf16(float lo, float hi) { unsigned r; asm volatile("s_nop 0\n\tv_cvt_pk_bf16_f32 %0, %1, %2" : "=v"(r) : "v"(lo), "v"(hi)); return r; }
; __device__ __forceinline__ float silu_mul(float g, float u) { return g * u * __builtin_amdgcn_rcpf(1.0f + __expf(-g)); }
;     __device__ __forceinline__ void operator()(const f32x4 (&acc)[2][2][4][2], const Unit& u, int wr, int wc, int fr, int fq) const {
;     ...
;             for (int m = 0; m < 4; ++m) { const int row = row0 + ai * HALF + m * 16; const float rs = rs8[ai * 4 + m];
;                 const f32x4 g0 = acc[ai][0][m][0] * rs, g1 = acc[ai][0][m][1] * rs, u0 = acc[ai][1][m][0] * rs, u1 = acc[ai][1][m][1] * rs;
;                 u32x4 w; w.x = cvt_pk_bf16(silu_mul(g0[0], u0[0]), silu_mul(g0[1], u0[1])); w.y = cvt_pk_bf16(silu_mul(g0[2], u0[2]), silu_mul(g0[3], u0[3]));
;                 w.z = cvt_pk_bf16(silu_mul(g1[0], u1[0]), silu_mul(g1[1], u1[1])); w.w = cvt_pk_bf16(silu_mul(g1[2], u1[2]), silu_mul(g1[3], u1[3]));
;                 *(u32x4*)(H + (size_t)row * ldh + col0) = w; }
	v_pk_mul_f32 v[28:29], v[28:29], v[180:181] op_sel_hi:[1,0]
	v_pk_mul_f32 v[30:31], v[30:31], v[180:181] op_sel_hi:[1,0]
	v_pk_mul_f32 v[24:25], v[24:25], v[180:181] op_sel_hi:[1,0]
	v_pk_mul_f32 v[26:27], v[26:27], v[180:181] op_sel_hi:[1,0]
	v_pk_mul_f32 v[20:21], v[20:21], v[180:181] op_sel_hi:[1,0]
	v_pk_mul_f32 v[22:23], v[22:23], v[180:181] op_sel_hi:[1,0]
	v_pk_mul_f32 v[16:17], v[16:17], v[180:181] op_sel_hi:[1,0]
	v_pk_mul_f32 v[18:19], v[18:19], v[180:181] op_sel_hi:[1,0]
	v_pk_mul_f32 v[184:185], v[28:29], v[142:143] op_sel_hi:[1,0]
	v_pk_mul_f32 v[186:187], v[30:31], v[142:143] op_sel_hi:[1,0]
	v_pk_mul_f32 v[188:189], v[24:25], v[142:143] op_sel_hi:[1,0]
	v_pk_mul_f32 v[190:191], v[26:27], v[142:143] op_sel_hi:[1,0]
	v_pk_mul_f32 v[20:21], v[28:29], v[20:21]
	v_pk_mul_f32 v[22:23], v[30:31], v[22:23]
	v_pk_mul_f32 v[16:17], v[24:25], v[16:17]
	v_pk_mul_f32 v[18:19], v[26:27], v[18:19]
	v_exp_f32_e32 v184, v184
	v_exp_f32_e32 v185, v185
	v_exp_f32_e32 v186, v186
	v_exp_f32_e32 v187, v187
	v_exp_f32_e32 v188, v188
	v_exp_f32_e32 v189, v189
	v_exp_f32_e32 v190, v190
	v_exp_f32_e32 v191, v191
	v_pk_add_f32 v[184:185], v[184:185], 1.0 op_sel_hi:[1,0]
	v_pk_add_f32 v[186:187], v[186:187], 1.0 op_sel_hi:[1,0]
	v_pk_add_f32 v[188:189], v[188:189], 1.0 op_sel_hi:[1,0]
	v_pk_add_f32 v[190:191], v[190:191], 1.0 op_sel_hi:[1,0]
	v_rcp_f32_e32 v184, v184
	v_rcp_f32_e32 v185, v185
	v_rcp_f32_e32 v186, v186
	v_rcp_f32_e32 v187, v187
	v_rcp_f32_e32 v188, v188
	v_rcp_f32_e32 v189, v189
	v_rcp_f32_e32 v190, v190
	v_rcp_f32_e32 v191, v191
	v_pk_mul_f32 v[20:21], v[20:21], v[184:185]
	v_pk_mul_f32 v[22:23], v[22:23], v[186:187]
	v_pk_mul_f32 v[16:17], v[16:17], v[188:189]
	v_pk_mul_f32 v[18:19], v[18:19], v[190:191]
	v_cvt_pk_bf16_f32 v192, v20, v21
	v_cvt_pk_bf16_f32 v193, v22, v23
	v_cvt_pk_bf16_f32 v194, v16, v17
	v_cvt_pk_bf16_f32 v195, v18, v19
	global_store_dwordx4 v150, v[192:195], s[16:17]
	v_add_u32_e32 v150, s0, v150
	s_waitcnt lgkmcnt(0)
	v_pk_mul_f32 v[12:13], v[12:13], v[182:183] op_sel_hi:[1,0]
	v_pk_mul_f32 v[14:15], v[14:15], v[182:183] op_sel_hi:[1,0]
	v_pk_mul_f32 v[8:9], v[8:9], v[182:183] op_sel_hi:[1,0]
	v_pk_mul_f32 v[10:11], v[10:11], v[182:183] op_sel_hi:[1,0]
	v_pk_mul_f32 v[4:5], v[4:5], v[182:183] op_sel_hi:[1,0]
	v_pk_mul_f32 v[6:7], v[6:7], v[182:183] op_sel_hi:[1,0]
	v_pk_mul_f32 v[0:1], v[0:1], v[182:183] op_sel_hi:[1,0]
	v_pk_mul_f32 v[2:3], v[2:3], v[182:183] op_sel_hi:[1,0]
	v_pk_mul_f32 v[184:185], v[12:13], v[142:143] op_sel_hi:[1,0]
	v_pk_mul_f32 v[186:187], v[14:15], v[142:143] op_sel_hi:[1,0]
	v_pk_mul_f32 v[188:189], v[8:9], v[142:143] op_sel_hi:[1,0]
	v_pk_mul_f32 v[190:191], v[10:11], v[142:143] op_sel_hi:[1,0]
	v_pk_mul_f32 v[4:5], v[12:13], v[4:5]
	v_pk_mul_f32 v[6:7], v[14:15], v[6:7]
	v_pk_mul_f32 v[0:1], v[8:9], v[0:1]
	v_pk_mul_f32 v[2:3], v[10:11], v[2:3]
	v_exp_f32_e32 v184, v184
	v_exp_f32_e32 v185, v185
	v_exp_f32_e32 v186, v186
	v_exp_f32_e32 v187, v187
	v_exp_f32_e32 v188, v188
	v_exp_f32_e32 v189, v189
	v_exp_f32_e32 v190, v190
	v_exp_f32_e32 v191, v191
	v_pk_add_f32 v[184:185], v[184:185], 1.0 op_sel_hi:[1,0]
	v_pk_add_f32 v[186:187], v[186:187], 1.0 op_sel_hi:[1,0]
	v_pk_add_f32 v[188:189], v[188:189], 1.0 op_sel_hi:[1,0]
	v_pk_add_f32 v[190:191], v[190:191], 1.0 op_sel_hi:[1,0]
	v_rcp_f32_e32 v184, v184
	v_rcp_f32_e32 v185, v185
	v_rcp_f32_e32 v186, v186
	v_rcp_f32_e32 v187, v187
	v_rcp_f32_e32 v188, v188
	v_rcp_f32_e32 v189, v189
	v_rcp_f32_e32 v190, v190
	v_rcp_f32_e32 v191, v191
	v_pk_mul_f32 v[4:5], v[4:5], v[184:185]
	v_pk_mul_f32 v[6:7], v[6:7], v[186:187]
	v_pk_mul_f32 v[0:1], v[0:1], v[188:189]
	v_pk_mul_f32 v[2:3], v[2:3], v[190:191]
	v_cvt_pk_bf16_f32 v196, v4, v5
	v_cvt_pk_bf16_f32 v197, v6, v7
	v_cvt_pk_bf16_f32 v198, v0, v1
	v_cvt_pk_bf16_f32 v199, v2, v3
	global_store_dwordx4 v150, v[196:199], s[16:17]
	s_and_b64 vcc, exec, s[4:5]
	s_mov_b64 s[0:1], -1
	s_cbranch_vccnz .LBB0_919
	s_andn2_b64 vcc, exec, s[14:15]
	s_cbranch_vccnz .LBB0_918
	s_barrier
	s_branch .LBB0_918

; #define PG8_STAGE(bufoff, gbase, voff) do { _Pragma("unroll") for (int _i = 0; _i < 2; ++_i) \
;         __builtin_amdgcn_global_load_lds((const unsigned*)((const char*)(gbase) + (voff)[_i]), (PG8_LAS unsigned*)(lds + (bufoff) + ldsw + _i * 8192), 16, 0, 0); } while (0)
; #define PG8_LDA(dst, b, h) do { _Pragma("unroll") for (int m = 0; m < 4; ++m) _Pragma("unroll") for (int k = 0; k < 2; ++k) dst[m][k] = *(const PG8_LAS bf16x8*)(lds + PG8_SA(b, h) + aoff + m * 2048 + k * 1024); } while (0)
; #define PG8_LDB(dst, b, h) do { _Pragma("unroll") for (int n = 0; n < 2; ++n) _Pragma("unroll") for (int k = 0; k < 2; ++k) dst[n][k] = *(const PG8_LAS bf16x8*)(lds + PG8_SB(b, h) + boff + n * 2048 + k * 1024); } while (0)
; #define PG8_MMA(ai, bj, At, Bt) do { __builtin_amdgcn_s_setprio(1); _Pragma("unroll") for (int m = 0; m < 4; ++m) _Pragma("unroll") for (int n = 0; n < 2; ++n) _Pragma("unroll") for (int k = 0; k < 2; ++k) \
;         acc[ai][bj][m][n] = __builtin_amdgcn_mfma_f32_16x16x32_bf16(Bt[n][k], At[m][k], acc[ai][bj][m][n], 0, 0, 0); __builtin_amdgcn_s_setprio(0); } while (0)
; #define PG8_WAIT_V(n) asm volatile("s_waitcnt vmcnt(" #n ")" ::: "memory")
; #define PG8_WAIT_L(n) asm volatile("s_waitcnt lgkmcnt(" #n ")" ::: "memory")
; #define PG8_BAR __builtin_amdgcn_s_barrier()
; #define PG8_SCHED __builtin_amdgcn_sched_barrier(0)
; template <class Epi, class Sched, bool ALIGN_EPI = false, bool SP2 = false>
; __device__ __forceinline__ void gemm_phase(PG8_LAS unsigned char* lds, const Gemm g, const Sched& S, const Epi& E, int tid_in) {
;     ...
;             PG8_LDB(B0, 0, 0); PG8_LDB(B1, 0, 1); PG8_SCHED; PG8_LDA(At, 0, 0); PG8_STAGE(PG8_SA(1, 1), a1 + hstep, voffA);
;             PG8_WAIT_V(8); PG8_WAIT_L(0); PG8_BAR; PG8_MMA(0, 0, At, B0); PG8_MMA(0, 1, At, B1); PG8_BAR; PG8_SCHED;
;     ...
; #pragma unroll
;         for (int a = 0; a < 2; ++a)
; #pragma unroll
;             for (int b = 0; b < 2; ++b)
; #pragma unroll
;                 for (int m = 0; m < 4; ++m)
; #pragma unroll
;                     for (int n = 0; n < 2; ++n) acc[a][b][m][n] = (f32x4){0.f, 0.f, 0.f, 0.f};
.LBB0_1022:
	s_andn2_b64 vcc, exec, s[24:25]
	s_waitcnt lgkmcnt(0)
	s_cbranch_vccz .Lpeel_enter_g4
	v_mov_b32_e32 v127, 0
	v_mov_b32_e32 v126, v127
	v_mov_b32_e32 v125, v127
	v_mov_b32_e32 v124, v127
	v_mov_b32_e32 v123, v127
	v_mov_b32_e32 v122, v127
	v_mov_b32_e32 v121, v127
	v_mov_b32_e32 v120, v127
	v_mov_b32_e32 v111, v127
	v_mov_b32_e32 v110, v127
	v_mov_b32_e32 v109, v127
	v_mov_b32_e32 v108, v127
	v_mov_b32_e32 v107, v127
	v_mov_b32_e32 v106, v127
	v_mov_b32_e32 v105, v127
	v_mov_b32_e32 v104, v127
	v_mov_b32_e32 v95, v127
	v_mov_b32_e32 v94, v127
	v_mov_b32_e32 v93, v127
	v_mov_b32_e32 v92, v127
	v_mov_b32_e32 v91, v127
	v_mov_b32_e32 v90, v127
	v_mov_b32_e32 v89, v127
	v_mov_b32_e32 v88, v127
	v_mov_b32_e32 v79, v127
	v_mov_b32_e32 v78, v127
	v_mov_b32_e32 v77, v127
	v_mov_b32_e32 v76, v127
	v_mov_b32_e32 v75, v127
	v_mov_b32_e32 v74, v127
	v_mov_b32_e32 v73, v127
	v_mov_b32_e32 v72, v127
	v_mov_b32_e32 v119, v127
	v_mov_b32_e32 v118, v127
	v_mov_b32_e32 v117, v127
	v_mov_b32_e32 v116, v127
	v_mov_b32_e32 v115, v127
	v_mov_b32_e32 v114, v127
	v_mov_b32_e32 v113, v127
	v_mov_b32_e32 v112, v127
	v_mov_b32_e32 v103, v127
	v_mov_b32_e32 v102, v127
	v_mov_b32_e32 v101, v127
	v_mov_b32_e32 v100, v127
	v_mov_b32_e32 v99, v127
	v_mov_b32_e32 v98, v127
	v_mov_b32_e32 v97, v127
	v_mov_b32_e32 v96, v127
	v_mov_b32_e32 v87, v127
	v_mov_b32_e32 v86, v127
	v_mov_b32_e32 v85, v127
	v_mov_b32_e32 v84, v127
	v_mov_b32_e32 v83, v127
	v_mov_b32_e32 v82, v127
	v_mov_b32_e32 v81, v127
	v_mov_b32_e32 v80, v127
	v_mov_b32_e32 v71, v127
	v_mov_b32_e32 v70, v127
	v_mov_b32_e32 v69, v127
	v_mov_b32_e32 v68, v127
	v_mov_b32_e32 v67, v127
	v_mov_b32_e32 v66, v127
	v_mov_b32_e32 v65, v127
	v_mov_b32_e32 v64, v127
	v_mov_b32_e32 v63, v127
	v_mov_b32_e32 v62, v127
	v_mov_b32_e32 v61, v127
	v_mov_b32_e32 v60, v127
	v_mov_b32_e32 v59, v127
	v_mov_b32_e32 v58, v127
	v_mov_b32_e32 v57, v127
	v_mov_b32_e32 v56, v127
	v_mov_b32_e32 v47, v127
	v_mov_b32_e32 v46, v127
	v_mov_b32_e32 v45, v127
	v_mov_b32_e32 v44, v127
	v_mov_b32_e32 v43, v127
	v_mov_b32_e32 v42, v127
	v_mov_b32_e32 v41, v127
	v_mov_b32_e32 v40, v127
	v_mov_b32_e32 v31, v127
	v_mov_b32_e32 v30, v127
	v_mov_b32_e32 v29, v127
	v_mov_b32_e32 v28, v127
	v_mov_b32_e32 v27, v127
	v_mov_b32_e32 v26, v127
	v_mov_b32_e32 v25, v127
	v_mov_b32_e32 v24, v127
	v_mov_b32_e32 v15, v127
	v_mov_b32_e32 v14, v127
	v_mov_b32_e32 v13, v127
	v_mov_b32_e32 v12, v127
	v_mov_b32_e32 v11, v127
	v_mov_b32_e32 v10, v127
	v_mov_b32_e32 v9, v127
	v_mov_b32_e32 v8, v127
	v_mov_b32_e32 v55, v127
	v_mov_b32_e32 v54, v127
	v_mov_b32_e32 v53, v127
	v_mov_b32_e32 v52, v127
	v_mov_b32_e32 v51, v127
	v_mov_b32_e32 v50, v127
	v_mov_b32_e32 v49, v127
	v_mov_b32_e32 v48, v127
	v_mov_b32_e32 v39, v127
	v_mov_b32_e32 v38, v127
	v_mov_b32_e32 v37, v127
	v_mov_b32_e32 v36, v127
	v_mov_b32_e32 v35, v127
	v_mov_b32_e32 v34, v127
	v_mov_b32_e32 v33, v127
	v_mov_b32_e32 v32, v127
	v_mov_b32_e32 v23, v127
	v_mov_b32_e32 v22, v127
	v_mov_b32_e32 v21, v127
	v_mov_b32_e32 v20, v127
	v_mov_b32_e32 v19, v127
	v_mov_b32_e32 v18, v127
	v_mov_b32_e32 v17, v127
	v_mov_b32_e32 v16, v127
	v_mov_b32_e32 v7, v127
	v_mov_b32_e32 v6, v127
	v_mov_b32_e32 v5, v127
	v_mov_b32_e32 v4, v127
	v_mov_b32_e32 v3, v127
	v_mov_b32_e32 v2, v127
	v_mov_b32_e32 v1, v127
	v_mov_b32_e32 v0, v127
	s_branch .LBB0_1025
.Lpeel_enter_g4:
	s_add_u32 s0, s0, 0x80
	s_addc_u32 s1, s1, 0
	s_add_u32 s55, s22, 0x100
	s_addc_u32 s92, s23, 0
	s_mov_b32 s22, 0
	s_add_i32 s36, s22, 2
	s_add_u32 s37, s0, 0x80
	s_addc_u32 s23, s1, 0
	s_add_i32 s93, 0, 0x10000
	s_cmp_eq_u32 s88, s22
	s_cselect_b32 s23, s7, s23
	s_cselect_b32 s22, s6, s37
	s_cselect_b32 vcc_hi, s45, s92
	s_cselect_b32 vcc_lo, s44, s55
	s_add_i32 s37, 0, 0x14000
	v_add_u32_e32 v146, s93, v237
	v_add_u32_e32 v154, s37, v237
	ds_read_b128 v[134:137], v146
	ds_read_b128 v[138:141], v146 offset:1024
	ds_read_b128 v[142:145], v146 offset:2048
	ds_read_b128 v[146:149], v146 offset:3072
	ds_read_b128 v[150:153], v154
	ds_read_b128 v[166:169], v154 offset:1024
	ds_read_b128 v[170:173], v154 offset:2048
	ds_read_b128 v[174:177], v154 offset:3072
	v_lshl_add_u64 v[154:155], s[0:1], 0, v[130:131]
	s_add_i32 m0, s47, 0xc000
	ds_read_b128 v[178:181], v241
	ds_read_b128 v[182:185], v241 offset:1024
	ds_read_b128 v[186:189], v241 offset:2048
	ds_read_b128 v[190:193], v241 offset:3072
	ds_read_b128 v[194:197], v241 offset:4096
	ds_read_b128 v[198:201], v241 offset:5120
	ds_read_b128 v[202:205], v241 offset:6144
	ds_read_b128 v[206:209], v241 offset:7168
	global_load_lds_dwordx4 v[154:155], off
	v_lshl_add_u64 v[154:155], s[0:1], 0, v[132:133]
	s_add_i32 m0, s47, 0xe000
	s_nop 0
	global_load_lds_dwordx4 v[154:155], off
	s_waitcnt vmcnt(8)
	s_waitcnt lgkmcnt(0)
	s_barrier
; #define PG8_STAGE(bufoff, gbase, voff) do { _Pragma("unroll") for (int _i = 0; _i < 2; ++_i) \
;         __builtin_amdgcn_global_load_lds((const unsigned*)((const char*)(gbase) + (voff)[_i]), (PG8_LAS unsigned*)(lds + (bufoff) + ldsw + _i * 8192), 16, 0, 0); } while (0)
; #define PG8_LDA(dst, b, h) do { _Pragma("unroll") for (int m = 0; m < 4; ++m) _Pragma("unroll") for (int k = 0; k < 2; ++k) dst[m][k] = *(const PG8_LAS bf16x8*)(lds + PG8_SA(b, h) + aoff + m * 2048 + k * 1024); } while (0)
; #define PG8_MMA(ai, bj, At, Bt) do { __builtin_amdgcn_s_setprio(1); _Pragma("unroll") for (int m = 0; m < 4; ++m) _Pragma("unroll") for (int n = 0; n < 2; ++n) _Pragma("unroll") for (int k = 0; k < 2; ++k) \
;         acc[ai][bj][m][n] = __builtin_amdgcn_mfma_f32_16x16x32_bf16(Bt[n][k], At[m][k], acc[ai][bj][m][n], 0, 0, 0); __builtin_amdgcn_s_setprio(0); } while (0)
; #define PG8_WAIT_V(n) asm volatile("s_waitcnt vmcnt(" #n ")" ::: "memory")
; #define PG8_WAIT_L(n) asm volatile("s_waitcnt lgkmcnt(" #n ")" ::: "memory")
; #define PG8_BAR __builtin_amdgcn_s_barrier()
; #define PG8_SCHED __builtin_amdgcn_sched_barrier(0)
; template <class Epi, class Sched, bool ALIGN_EPI = false, bool SP2 = false>
; __device__ __forceinline__ void gemm_phase(PG8_LAS unsigned char* lds, const Gemm g, const Sched& S, const Epi& E, int tid_in) {
;     ...
;             PG8_WAIT_V(8); PG8_WAIT_L(0); PG8_BAR; PG8_MMA(0, 0, At, B0); PG8_MMA(0, 1, At, B1); PG8_BAR; PG8_SCHED;
;             PG8_LDA(At, 0, 1); PG8_STAGE(PG8_SB(0, 0), b2, voffB); PG8_STAGE(PG8_SB(0, 1), b2 + hstep, voffB); PG8_STAGE(PG8_SA(0, 0), a2, voffA);
;             PG8_WAIT_V(8); PG8_WAIT_L(0); PG8_BAR; PG8_MMA(1, 0, At, B0); PG8_MMA(1, 1, At, B1); PG8_BAR; PG8_SCHED;
	s_waitcnt lgkmcnt(0)
	v_mfma_f32_16x16x32_bf16 v[124:127], v[134:137], v[178:181], 0
	v_mfma_f32_16x16x32_bf16 v[120:123], v[142:145], v[178:181], 0
	v_mfma_f32_16x16x32_bf16 v[108:111], v[134:137], v[186:189], 0
	v_mfma_f32_16x16x32_bf16 v[104:107], v[142:145], v[186:189], 0
	v_mfma_f32_16x16x32_bf16 v[92:95], v[134:137], v[194:197], 0
	v_mfma_f32_16x16x32_bf16 v[88:91], v[142:145], v[194:197], 0
	v_mfma_f32_16x16x32_bf16 v[76:79], v[134:137], v[202:205], 0
	v_mfma_f32_16x16x32_bf16 v[72:75], v[142:145], v[202:205], 0
	v_mfma_f32_16x16x32_bf16 v[124:127], v[138:141], v[182:185], v[124:127]
	v_mfma_f32_16x16x32_bf16 v[120:123], v[146:149], v[182:185], v[120:123]
	v_mfma_f32_16x16x32_bf16 v[108:111], v[138:141], v[190:193], v[108:111]
	v_mfma_f32_16x16x32_bf16 v[104:107], v[146:149], v[190:193], v[104:107]
	v_mfma_f32_16x16x32_bf16 v[92:95], v[138:141], v[198:201], v[92:95]
	v_mfma_f32_16x16x32_bf16 v[88:91], v[146:149], v[198:201], v[88:91]
	v_mfma_f32_16x16x32_bf16 v[76:79], v[138:141], v[206:209], v[76:79]
	v_mfma_f32_16x16x32_bf16 v[72:75], v[146:149], v[206:209], v[72:75]
	v_mfma_f32_16x16x32_bf16 v[116:119], v[150:153], v[178:181], 0
	v_mfma_f32_16x16x32_bf16 v[112:115], v[170:173], v[178:181], 0
	v_mfma_f32_16x16x32_bf16 v[100:103], v[150:153], v[186:189], 0
	v_mfma_f32_16x16x32_bf16 v[96:99], v[170:173], v[186:189], 0
	v_mfma_f32_16x16x32_bf16 v[84:87], v[150:153], v[194:197], 0
	v_mfma_f32_16x16x32_bf16 v[80:83], v[170:173], v[194:197], 0
	v_mfma_f32_16x16x32_bf16 v[68:71], v[150:153], v[202:205], 0
	v_mfma_f32_16x16x32_bf16 v[64:67], v[170:173], v[202:205], 0
	v_mfma_f32_16x16x32_bf16 v[116:119], v[166:169], v[182:185], v[116:119]
	v_mfma_f32_16x16x32_bf16 v[112:115], v[174:177], v[182:185], v[112:115]
	v_mfma_f32_16x16x32_bf16 v[100:103], v[166:169], v[190:193], v[100:103]
	v_mfma_f32_16x16x32_bf16 v[96:99], v[174:177], v[190:193], v[96:99]
	v_mfma_f32_16x16x32_bf16 v[84:87], v[166:169], v[198:201], v[84:87]
	v_mfma_f32_16x16x32_bf16 v[80:83], v[174:177], v[198:201], v[80:83]
	v_mfma_f32_16x16x32_bf16 v[68:71], v[166:169], v[206:209], v[68:71]
	v_mfma_f32_16x16x32_bf16 v[64:67], v[174:177], v[206:209], v[64:67]
	s_barrier
	s_add_i32 s93, s93, s46
	v_lshl_add_u64 v[154:155], vcc, 0, v[156:157]
	s_mov_b32 m0, s93
	ds_read_b128 v[178:181], v241 offset:16384
	ds_read_b128 v[182:185], v241 offset:17408
	ds_read_b128 v[186:189], v241 offset:18432
	ds_read_b128 v[190:193], v241 offset:19456
	ds_read_b128 v[194:197], v241 offset:20480
	ds_read_b128 v[198:201], v241 offset:21504
	ds_read_b128 v[202:205], v241 offset:22528
	ds_read_b128 v[206:209], v241 offset:23552
	global_load_lds_dwordx4 v[154:155], off
	s_add_i32 m0, s93, 0x2000
	v_lshl_add_u64 v[162:163], vcc, 0, v[128:129]
	s_add_u32 vcc_lo, vcc_lo, s10
	s_addc_u32 vcc_hi, vcc_hi, s11
	s_add_i32 s37, s37, s46
	global_load_lds_dwordx4 v[162:163], off
	v_lshl_add_u64 v[210:211], vcc, 0, v[156:157]
	s_mov_b32 m0, s37
	v_lshl_add_u64 v[212:213], vcc, 0, v[128:129]
	global_load_lds_dwordx4 v[210:211], off
	s_add_i32 m0, s37, 0x2000
	v_lshl_add_u64 v[214:215], s[22:23], 0, v[156:157]
	global_load_lds_dwordx4 v[212:213], off
	s_mov_b32 m0, s47
	v_lshl_add_u64 v[216:217], s[22:23], 0, v[128:129]
	global_load_lds_dwordx4 v[214:215], off
	s_mov_b32 m0, s52
	s_nop 0
	global_load_lds_dwordx4 v[216:217], off
	s_waitcnt vmcnt(8)
	s_waitcnt lgkmcnt(0)
	s_barrier
	s_waitcnt lgkmcnt(0)
	v_mfma_f32_16x16x32_bf16 v[60:63], v[134:137], v[178:181], 0
	v_mfma_f32_16x16x32_bf16 v[56:59], v[142:145], v[178:181], 0
	v_mfma_f32_16x16x32_bf16 v[44:47], v[134:137], v[186:189], 0
	v_mfma_f32_16x16x32_bf16 v[40:43], v[142:145], v[186:189], 0
	v_mfma_f32_16x16x32_bf16 v[28:31], v[134:137], v[194:197], 0
	v_mfma_f32_16x16x32_bf16 v[24:27], v[142:145], v[194:197], 0
	v_mfma_f32_16x16x32_bf16 v[12:15], v[134:137], v[202:205], 0
	v_mfma_f32_16x16x32_bf16 v[8:11], v[142:145], v[202:205], 0
	v_mfma_f32_16x16x32_bf16 v[60:63], v[138:141], v[182:185], v[60:63]
	v_mfma_f32_16x16x32_bf16 v[56:59], v[146:149], v[182:185], v[56:59]
	v_mfma_f32_16x16x32_bf16 v[44:47], v[138:141], v[190:193], v[44:47]
	v_mfma_f32_16x16x32_bf16 v[40:43], v[146:149], v[190:193], v[40:43]
	v_mfma_f32_16x16x32_bf16 v[28:31], v[138:141], v[198:201], v[28:31]
	v_mfma_f32_16x16x32_bf16 v[24:27], v[146:149], v[198:201], v[24:27]
	v_mfma_f32_16x16x32_bf16 v[12:15], v[138:141], v[206:209], v[12:15]
	v_mfma_f32_16x16x32_bf16 v[8:11], v[146:149], v[206:209], v[8:11]
	v_mfma_f32_16x16x32_bf16 v[52:55], v[150:153], v[178:181], 0
	v_mfma_f32_16x16x32_bf16 v[48:51], v[170:173], v[178:181], 0
	v_mfma_f32_16x16x32_bf16 v[36:39], v[150:153], v[186:189], 0
	v_mfma_f32_16x16x32_bf16 v[32:35], v[170:173], v[186:189], 0
	v_mfma_f32_16x16x32_bf16 v[20:23], v[150:153], v[194:197], 0
	v_mfma_f32_16x16x32_bf16 v[16:19], v[170:173], v[194:197], 0
	v_mfma_f32_16x16x32_bf16 v[4:7], v[150:153], v[202:205], 0
	v_mfma_f32_16x16x32_bf16 v[0:3], v[170:173], v[202:205], 0
	v_mfma_f32_16x16x32_bf16 v[52:55], v[166:169], v[182:185], v[52:55]
	v_mfma_f32_16x16x32_bf16 v[48:51], v[174:177], v[182:185], v[48:51]
	v_mfma_f32_16x16x32_bf16 v[36:39], v[166:169], v[190:193], v[36:39]
	v_mfma_f32_16x16x32_bf16 v[32:35], v[174:177], v[190:193], v[32:35]
	v_mfma_f32_16x16x32_bf16 v[20:23], v[166:169], v[198:201], v[20:23]
	v_mfma_f32_16x16x32_bf16 v[16:19], v[174:177], v[198:201], v[16:19]
	v_mfma_f32_16x16x32_bf16 v[4:7], v[166:169], v[206:209], v[4:7]
	v_mfma_f32_16x16x32_bf16 v[0:3], v[174:177], v[206:209], v[0:3]
	s_barrier
; #define PG8_STAGE(bufoff, gbase, voff) do { _Pragma("unroll") for (int _i = 0; _i < 2; ++_i) \
;         __builtin_amdgcn_global_load_lds((const unsigned*)((const char*)(gbase) + (voff)[_i]), (PG8_LAS unsigned*)(lds + (bufoff) + ldsw + _i * 8192), 16, 0, 0); } while (0)
; #define PG8_LDA(dst, b, h) do { _Pragma("unroll") for (int m = 0; m < 4; ++m) _Pragma("unroll") for (int k = 0; k < 2; ++k) dst[m][k] = *(const PG8_LAS bf16x8*)(lds + PG8_SA(b, h) + aoff + m * 2048 + k * 1024); } while (0)
; #define PG8_LDB(dst, b, h) do { _Pragma("unroll") for (int n = 0; n < 2; ++n) _Pragma("unroll") for (int k = 0; k < 2; ++k) dst[n][k] = *(const PG8_LAS bf16x8*)(lds + PG8_SB(b, h) + boff + n * 2048 + k * 1024); } while (0)
; #define PG8_MMA(ai, bj, At, Bt) do { __builtin_amdgcn_s_setprio(1); _Pragma("unroll") for (int m = 0; m < 4; ++m) _Pragma("unroll") for (int n = 0; n < 2; ++n) _Pragma("unroll") for (int k = 0; k < 2; ++k) \
;         acc[ai][bj][m][n] = __builtin_amdgcn_mfma_f32_16x16x32_bf16(Bt[n][k], At[m][k], acc[ai][bj][m][n], 0, 0, 0); __builtin_amdgcn_s_setprio(0); } while (0)
; #define PG8_WAIT_V(n) asm volatile("s_waitcnt vmcnt(" #n ")" ::: "memory")
; #define PG8_WAIT_L(n) asm volatile("s_waitcnt lgkmcnt(" #n ")" ::: "memory")
; #define PG8_BAR __builtin_amdgcn_s_barrier()
; #define PG8_SCHED __builtin_amdgcn_sched_barrier(0)
; template <class Epi, class Sched, bool ALIGN_EPI = false, bool SP2 = false>
; __device__ __forceinline__ void gemm_phase(PG8_LAS unsigned char* lds, const Gemm g, const Sched& S, const Epi& E, int tid_in) {
;     ...
;         for (int t = 0; t < nt; t += 2) {
;     ...
;             PG8_LDB(B0, 1, 0); PG8_LDB(B1, 1, 1); PG8_SCHED; PG8_LDA(At, 1, 0); PG8_STAGE(PG8_SA(0, 1), a2 + hstep, voffA);
;             PG8_WAIT_V(8); PG8_WAIT_L(0); PG8_BAR; PG8_MMA(0, 0, At, B0); PG8_MMA(0, 1, At, B1); PG8_BAR; PG8_SCHED;
;             PG8_LDA(At, 1, 1); PG8_STAGE(PG8_SB(1, 0), b3, voffB); PG8_STAGE(PG8_SB(1, 1), b3 + hstep, voffB); PG8_STAGE(PG8_SA(1, 0), a3, voffA);
;             PG8_WAIT_V(8); PG8_WAIT_L(0); PG8_BAR; PG8_MMA(1, 0, At, B0); PG8_MMA(1, 1, At, B1); PG8_BAR; PG8_SCHED;
	s_add_i32 s37, 0, 0x18000
	s_add_i32 s93, 0, 0x1c000
	v_add_u32_e32 v146, s37, v237
	v_add_u32_e32 v174, s93, v237
	ds_read_b128 v[134:137], v146
	ds_read_b128 v[138:141], v146 offset:1024
	ds_read_b128 v[142:145], v146 offset:2048
	ds_read_b128 v[146:149], v146 offset:3072
	ds_read_b128 v[150:153], v174
	ds_read_b128 v[166:169], v174 offset:1024
	ds_read_b128 v[170:173], v174 offset:2048
	ds_read_b128 v[174:177], v174 offset:3072
	s_add_u32 s22, s22, s10
	s_addc_u32 s23, s23, s11
	s_mov_b32 m0, s53
	v_lshl_add_u64 v[218:219], s[22:23], 0, v[156:157]
	ds_read_b128 v[178:181], v241 offset:32768
	ds_read_b128 v[182:185], v241 offset:33792
	ds_read_b128 v[186:189], v241 offset:34816
	ds_read_b128 v[190:193], v241 offset:35840
	ds_read_b128 v[194:197], v241 offset:36864
	ds_read_b128 v[198:201], v241 offset:37888
	ds_read_b128 v[202:205], v241 offset:38912
	ds_read_b128 v[206:209], v241 offset:39936
	global_load_lds_dwordx4 v[218:219], off
	v_lshl_add_u64 v[218:219], s[22:23], 0, v[128:129]
	s_mov_b32 m0, s56
	s_nop 0
	global_load_lds_dwordx4 v[218:219], off
	s_waitcnt vmcnt(8)
	s_waitcnt lgkmcnt(0)
	s_barrier
	s_waitcnt lgkmcnt(0)
	v_mfma_f32_16x16x32_bf16 v[124:127], v[134:137], v[178:181], v[124:127]
	v_mfma_f32_16x16x32_bf16 v[120:123], v[142:145], v[178:181], v[120:123]
	v_mfma_f32_16x16x32_bf16 v[108:111], v[134:137], v[186:189], v[108:111]
	v_mfma_f32_16x16x32_bf16 v[104:107], v[142:145], v[186:189], v[104:107]
	v_mfma_f32_16x16x32_bf16 v[92:95], v[134:137], v[194:197], v[92:95]
	v_mfma_f32_16x16x32_bf16 v[88:91], v[142:145], v[194:197], v[88:91]
	v_mfma_f32_16x16x32_bf16 v[76:79], v[134:137], v[202:205], v[76:79]
	v_mfma_f32_16x16x32_bf16 v[72:75], v[142:145], v[202:205], v[72:75]
	v_mfma_f32_16x16x32_bf16 v[124:127], v[138:141], v[182:185], v[124:127]
	v_mfma_f32_16x16x32_bf16 v[120:123], v[146:149], v[182:185], v[120:123]
	v_mfma_f32_16x16x32_bf16 v[108:111], v[138:141], v[190:193], v[108:111]
	v_mfma_f32_16x16x32_bf16 v[104:107], v[146:149], v[190:193], v[104:107]
	v_mfma_f32_16x16x32_bf16 v[92:95], v[138:141], v[198:201], v[92:95]
	v_mfma_f32_16x16x32_bf16 v[88:91], v[146:149], v[198:201], v[88:91]
	v_mfma_f32_16x16x32_bf16 v[76:79], v[138:141], v[206:209], v[76:79]
	v_mfma_f32_16x16x32_bf16 v[72:75], v[146:149], v[206:209], v[72:75]
	v_mfma_f32_16x16x32_bf16 v[116:119], v[150:153], v[178:181], v[116:119]
	v_mfma_f32_16x16x32_bf16 v[112:115], v[170:173], v[178:181], v[112:115]
	v_mfma_f32_16x16x32_bf16 v[100:103], v[150:153], v[186:189], v[100:103]
	v_mfma_f32_16x16x32_bf16 v[96:99], v[170:173], v[186:189], v[96:99]
	v_mfma_f32_16x16x32_bf16 v[84:87], v[150:153], v[194:197], v[84:87]
	v_mfma_f32_16x16x32_bf16 v[80:83], v[170:173], v[194:197], v[80:83]
	v_mfma_f32_16x16x32_bf16 v[68:71], v[150:153], v[202:205], v[68:71]
	v_mfma_f32_16x16x32_bf16 v[64:67], v[170:173], v[202:205], v[64:67]
	v_mfma_f32_16x16x32_bf16 v[116:119], v[166:169], v[182:185], v[116:119]
	v_mfma_f32_16x16x32_bf16 v[112:115], v[174:177], v[182:185], v[112:115]
	v_mfma_f32_16x16x32_bf16 v[100:103], v[166:169], v[190:193], v[100:103]
	v_mfma_f32_16x16x32_bf16 v[96:99], v[174:177], v[190:193], v[96:99]
	v_mfma_f32_16x16x32_bf16 v[84:87], v[166:169], v[198:201], v[84:87]
	v_mfma_f32_16x16x32_bf16 v[80:83], v[174:177], v[198:201], v[80:83]
	v_mfma_f32_16x16x32_bf16 v[68:71], v[166:169], v[206:209], v[68:71]
	v_mfma_f32_16x16x32_bf16 v[64:67], v[174:177], v[206:209], v[64:67]
	s_barrier
	s_add_i32 s22, s37, s46
	v_lshl_add_u64 v[154:155], v[154:155], 0, s[64:65]
	s_mov_b32 m0, s22
	ds_read_b128 v[178:181], v241 offset:49152
	ds_read_b128 v[182:185], v241 offset:50176
	ds_read_b128 v[186:189], v241 offset:51200
	ds_read_b128 v[190:193], v241 offset:52224
	ds_read_b128 v[194:197], v241 offset:53248
	ds_read_b128 v[198:201], v241 offset:54272
	ds_read_b128 v[202:205], v241 offset:55296
	ds_read_b128 v[206:209], v241 offset:56320
	global_load_lds_dwordx4 v[154:155], off
	v_lshl_add_u64 v[154:155], v[162:163], 0, s[64:65]
	s_add_i32 m0, s22, 0x2000
	s_add_i32 s22, s93, s46
	global_load_lds_dwordx4 v[154:155], off
	v_lshl_add_u64 v[154:155], v[210:211], 0, s[64:65]
	s_mov_b32 m0, s22
	s_nop 0
	global_load_lds_dwordx4 v[154:155], off
	v_lshl_add_u64 v[154:155], v[212:213], 0, s[64:65]
	s_add_i32 m0, s22, 0x2000
	s_nop 0
	global_load_lds_dwordx4 v[154:155], off
	v_lshl_add_u64 v[154:155], v[214:215], 0, s[64:65]
	s_mov_b32 m0, s66
	s_nop 0
	global_load_lds_dwordx4 v[154:155], off
	v_lshl_add_u64 v[154:155], v[216:217], 0, s[64:65]
	s_mov_b32 m0, s67
	s_nop 0
	global_load_lds_dwordx4 v[154:155], off
	s_waitcnt vmcnt(8)
	s_waitcnt lgkmcnt(0)
	s_barrier
	s_waitcnt lgkmcnt(0)
	v_mfma_f32_16x16x32_bf16 v[60:63], v[134:137], v[178:181], v[60:63]
	v_mfma_f32_16x16x32_bf16 v[56:59], v[142:145], v[178:181], v[56:59]
	v_mfma_f32_16x16x32_bf16 v[44:47], v[134:137], v[186:189], v[44:47]
	v_mfma_f32_16x16x32_bf16 v[40:43], v[142:145], v[186:189], v[40:43]
	v_mfma_f32_16x16x32_bf16 v[28:31], v[134:137], v[194:197], v[28:31]
	v_mfma_f32_16x16x32_bf16 v[24:27], v[142:145], v[194:197], v[24:27]
	v_mfma_f32_16x16x32_bf16 v[12:15], v[134:137], v[202:205], v[12:15]
	v_mfma_f32_16x16x32_bf16 v[8:11], v[142:145], v[202:205], v[8:11]
	v_mfma_f32_16x16x32_bf16 v[60:63], v[138:141], v[182:185], v[60:63]
	v_mfma_f32_16x16x32_bf16 v[56:59], v[146:149], v[182:185], v[56:59]
	v_mfma_f32_16x16x32_bf16 v[44:47], v[138:141], v[190:193], v[44:47]
	v_mfma_f32_16x16x32_bf16 v[40:43], v[146:149], v[190:193], v[40:43]
	v_mfma_f32_16x16x32_bf16 v[28:31], v[138:141], v[198:201], v[28:31]
	v_mfma_f32_16x16x32_bf16 v[24:27], v[146:149], v[198:201], v[24:27]
	v_mfma_f32_16x16x32_bf16 v[12:15], v[138:141], v[206:209], v[12:15]
	v_mfma_f32_16x16x32_bf16 v[8:11], v[146:149], v[206:209], v[8:11]
	v_mfma_f32_16x16x32_bf16 v[52:55], v[150:153], v[178:181], v[52:55]
	v_mfma_f32_16x16x32_bf16 v[48:51], v[170:173], v[178:181], v[48:51]
	v_mfma_f32_16x16x32_bf16 v[36:39], v[150:153], v[186:189], v[36:39]
	v_mfma_f32_16x16x32_bf16 v[32:35], v[170:173], v[186:189], v[32:35]
	v_mfma_f32_16x16x32_bf16 v[20:23], v[150:153], v[194:197], v[20:23]
	v_mfma_f32_16x16x32_bf16 v[16:19], v[170:173], v[194:197], v[16:19]
	v_mfma_f32_16x16x32_bf16 v[4:7], v[150:153], v[202:205], v[4:7]
	v_mfma_f32_16x16x32_bf16 v[0:3], v[170:173], v[202:205], v[0:3]
	v_mfma_f32_16x16x32_bf16 v[52:55], v[166:169], v[182:185], v[52:55]
	v_mfma_f32_16x16x32_bf16 v[48:51], v[174:177], v[182:185], v[48:51]
	v_mfma_f32_16x16x32_bf16 v[36:39], v[166:169], v[190:193], v[36:39]
	v_mfma_f32_16x16x32_bf16 v[32:35], v[174:177], v[190:193], v[32:35]
	v_mfma_f32_16x16x32_bf16 v[20:23], v[166:169], v[198:201], v[20:23]
	v_mfma_f32_16x16x32_bf16 v[16:19], v[174:177], v[198:201], v[16:19]
	v_mfma_f32_16x16x32_bf16 v[4:7], v[166:169], v[206:209], v[4:7]
	v_mfma_f32_16x16x32_bf16 v[0:3], v[174:177], v[206:209], v[0:3]
	s_barrier
	s_add_u32 s0, s0, 0x100
	s_addc_u32 s1, s1, 0
	s_add_u32 s55, s55, 0x100
	s_addc_u32 s92, s92, 0
	s_cmp_ge_i32 s36, s63
	s_mov_b32 s22, s36
	s_cbranch_scc0 .LBB0_1024
	s_branch .Lpeel_exit_g4

; #define PG8_BAR __builtin_amdgcn_s_barrier()
; template <class Epi, class Sched, bool ALIGN_EPI = false, bool SP2 = false>
; __device__ __forceinline__ void gemm_phase(PG8_LAS unsigned char* lds, const Gemm g, const Sched& S, const Epi& E, int tid_in) {
;     ...
;         if constexpr (ALIGN_EPI) { if (wr == 0) PG8_BAR; }
;         if constexpr (!Epi::AFTER_DRAIN) { E(acc, cur, wr, wc, fr, fq); S.done(cur); }
;         if (!has_next) break;
.Lpeel_exit_g4:
.LBB0_1025:
	s_and_b64 vcc, exec, s[38:39]
	s_cbranch_vccz .LBB0_1027
	s_barrier

; __global__ void __launch_bounds__(NTHR, 2) mega_fwd(Args args) {
	.amdhsa_kernel _Z8mega_fwd4Args
		.amdhsa_group_segment_fixed_size 0
		.amdhsa_private_segment_fixed_size 0
		.amdhsa_kernarg_size 392
		.amdhsa_user_sgpr_count 2
		.amdhsa_user_sgpr_dispatch_ptr 0
		.amdhsa_user_sgpr_queue_ptr 0
		.amdhsa_user_sgpr_kernarg_segment_ptr 1
		.amdhsa_user_sgpr_dispatch_id 0
		.amdhsa_user_sgpr_kernarg_preload_length 0
		.amdhsa_user_sgpr_kernarg_preload_offset 0
		.amdhsa_user_sgpr_private_segment_size 0
		.amdhsa_uses_dynamic_stack 0
		.amdhsa_enable_private_segment 0
		.amdhsa_system_sgpr_workgroup_id_x 1
		.amdhsa_system_sgpr_workgroup_id_y 0
		.amdhsa_system_sgpr_workgroup_id_z 0
		.amdhsa_system_sgpr_workgroup_info 0
		.amdhsa_system_vgpr_workitem_id 2
		.amdhsa_next_free_vgpr 256
		.amdhsa_next_free_sgpr 102
		.amdhsa_accum_offset 256
		.amdhsa_reserve_vcc 1
		.amdhsa_float_round_mode_32 0
		.amdhsa_float_round_mode_16_64 0
		.amdhsa_float_denorm_mode_32 3
		.amdhsa_float_denorm_mode_16_64 3
		.amdhsa_dx10_clamp 1
		.amdhsa_ieee_mode 1
		.amdhsa_fp16_overflow 0
		.amdhsa_tg_split 0
		.amdhsa_exception_fp_ieee_invalid_op 0
		.amdhsa_exception_fp_denorm_src 0
		.amdhsa_exception_fp_ieee_div_zero 0
		.amdhsa_exception_fp_ieee_overflow 0
		.amdhsa_exception_fp_ieee_underflow 0
		.amdhsa_exception_fp_ieee_inexact 0
		.amdhsa_exception_int_div_zero 0
	.end_amdhsa_kernel

; __global__ void __launch_bounds__(NTHR, 2) mega_fwd(Args args) {
.Lfunc_end0:
	.size	_Z8mega_fwd4Args, .Lfunc_end0-_Z8mega_fwd4Args
	.set _Z8mega_fwd4Args.num_vgpr, 256
	.set _Z8mega_fwd4Args.num_agpr, 0
	.set _Z8mega_fwd4Args.numbered_sgpr, 102
	.set _Z8mega_fwd4Args.num_named_barrier, 0
	.set _Z8mega_fwd4Args.private_seg_size, 0
	.set _Z8mega_fwd4Args.uses_vcc, 1
	.set _Z8mega_fwd4Args.uses_flat_scratch, 0
	.set _Z8mega_fwd4Args.has_dyn_sized_stack, 0
	.set _Z8mega_fwd4Args.has_recursion, 0
	.set _Z8mega_fwd4Args.has_indirect_call, 0

; __global__ void __launch_bounds__(NTHR, 2) mega_fwd(Args args) {
amdhsa.kernels:
  - .agpr_count:     0
    .args:
      - .offset:         0
        .size:           136
        .value_kind:     by_value
      - .offset:         136
        .size:           4
        .value_kind:     hidden_block_count_x
      - .offset:         140
        .size:           4
        .value_kind:     hidden_block_count_y
      - .offset:         144
        .size:           4
        .value_kind:     hidden_block_count_z
      - .offset:         148
        .size:           2
        .value_kind:     hidden_group_size_x
      - .offset:         150
        .size:           2
        .value_kind:     hidden_group_size_y
      - .offset:         152
        .size:           2
        .value_kind:     hidden_group_size_z
      - .offset:         154
        .size:           2
        .value_kind:     hidden_remainder_x
      - .offset:         156
        .size:           2
        .value_kind:     hidden_remainder_y
      - .offset:         158
        .size:           2
        .value_kind:     hidden_remainder_z
      - .offset:         176
        .size:           8
        .value_kind:     hidden_global_offset_x
      - .offset:         184
        .size:           8
        .value_kind:     hidden_global_offset_y
      - .offset:         192
        .size:           8
        .value_kind:     hidden_global_offset_z
      - .offset:         200
        .size:           2
        .value_kind:     hidden_grid_dims
      - .offset:         224
        .size:           8
        .value_kind:     hidden_multigrid_sync_arg
      - .offset:         256
        .size:           4
        .value_kind:     hidden_dynamic_lds_size
    .group_segment_fixed_size: 0
    .kernarg_segment_align: 8
    .kernarg_segment_size: 392
    .language:       OpenCL C
    .language_version:
      - 2
      - 0
    .max_flat_workgroup_size: 512
    .name:           _Z8mega_fwd4Args
    .private_segment_fixed_size: 0
    .sgpr_count:     108
    .sgpr_spill_count: 130
    .symbol:         _Z8mega_fwd4Args.kd
    .uniform_work_group_size: 1
    .uses_dynamic_stack: false
    .vgpr_count:     256
    .vgpr_spill_count: 0
    .wavefront_size: 64
